# gMLP u-loads/stores as dwordx4 via permlane32_swap; attention O stores widened to dwordx4; attnC K/V prefetch decoupled from QK waits
# speedup vs baseline: 1.0470x; 1.0132x over previous
.LBB0_471:
	v_div_scale_f32 v33, s[80:81], v32, v32, 1.0
	v_rcp_f32_e32 v34, v33
	s_or_b32 s84, s84, s46
	s_lshl_b64 s[18:19], s[84:85], 11
	s_add_u32 s17, s48, s18
	v_fma_f32 v35, -v33, v34, 1.0
	v_fmac_f32_e32 v34, v35, v34
	v_div_scale_f32 v35, vcc, 1.0, v32, 1.0
	v_mul_f32_e32 v36, v35, v34
	v_fma_f32 v37, -v33, v36, v35
	v_fmac_f32_e32 v36, v37, v34
	s_addc_u32 s19, s49, s19
	v_fma_f32 v33, -v33, v36, v35
	s_add_u32 s18, s17, s82
	v_div_fmas_f32 v33, v33, v34, v36
	s_addc_u32 s19, s19, s83
	v_div_fixup_f32 v32, v33, v32, 1.0
	v_lshl_add_u64 v[34:35], s[18:19], 0, v[144:145]
	v_mov_b32_e32 v153, v145
	v_pk_mul_f32 v[16:17], v[32:33], v[16:17] op_sel_hi:[0,1]
	v_pk_mul_f32 v[18:19], v[32:33], v[18:19] op_sel_hi:[0,1]
	v_pk_mul_f32 v[20:21], v[32:33], v[20:21] op_sel_hi:[0,1]
	v_pk_mul_f32 v[22:23], v[32:33], v[22:23] op_sel_hi:[0,1]
	v_pk_mul_f32 v[24:25], v[32:33], v[24:25] op_sel_hi:[0,1]
	v_pk_mul_f32 v[26:27], v[32:33], v[26:27] op_sel_hi:[0,1]
	v_pk_mul_f32 v[28:29], v[32:33], v[28:29] op_sel_hi:[0,1]
	v_pk_mul_f32 v[30:31], v[32:33], v[30:31] op_sel_hi:[0,1]
	v_pk_mul_f32 v[0:1], v[32:33], v[0:1] op_sel_hi:[0,1]
	v_pk_mul_f32 v[2:3], v[32:33], v[2:3] op_sel_hi:[0,1]
	v_pk_mul_f32 v[4:5], v[32:33], v[4:5] op_sel_hi:[0,1]
	v_pk_mul_f32 v[6:7], v[32:33], v[6:7] op_sel_hi:[0,1]
	v_pk_mul_f32 v[8:9], v[32:33], v[8:9] op_sel_hi:[0,1]
	v_pk_mul_f32 v[10:11], v[32:33], v[10:11] op_sel_hi:[0,1]
	v_pk_mul_f32 v[12:13], v[32:33], v[12:13] op_sel_hi:[0,1]
	v_pk_mul_f32 v[14:15], v[32:33], v[14:15] op_sel_hi:[0,1]
	v_lshl_add_u64 v[34:35], v[34:35], 0, v[152:153]
	v_lshl_add_u64 v[34:35], v[34:35], 0, v[152:153]
	v_cvt_pk_bf16_f32 v16, v16, v17
	v_cvt_pk_bf16_f32 v17, v18, v19
	v_cvt_pk_bf16_f32 v18, v20, v21
	v_cvt_pk_bf16_f32 v19, v22, v23
	v_cvt_pk_bf16_f32 v20, v24, v25
	v_cvt_pk_bf16_f32 v21, v26, v27
	v_cvt_pk_bf16_f32 v22, v28, v29
	v_cvt_pk_bf16_f32 v23, v30, v31
	v_cvt_pk_bf16_f32 v0, v0, v1
	v_cvt_pk_bf16_f32 v1, v2, v3
	v_cvt_pk_bf16_f32 v2, v4, v5
	v_cvt_pk_bf16_f32 v3, v6, v7
	v_cvt_pk_bf16_f32 v4, v8, v9
	v_cvt_pk_bf16_f32 v5, v10, v11
	v_cvt_pk_bf16_f32 v6, v12, v13
	v_cvt_pk_bf16_f32 v7, v14, v15
	s_andn2_b64 vcc, exec, s[78:79]
	s_add_i32 s95, s95, s96
	s_nop 1
	v_permlane32_swap_b32 v16, v18
	v_permlane32_swap_b32 v17, v19
	v_permlane32_swap_b32 v20, v22
	v_permlane32_swap_b32 v21, v23
	v_permlane32_swap_b32 v0, v2
	v_permlane32_swap_b32 v1, v3
	v_permlane32_swap_b32 v4, v6
	v_permlane32_swap_b32 v5, v7
	global_store_dwordx4 v[34:35], v[16:19], off
	global_store_dwordx4 v[34:35], v[20:23], off offset:32
	global_store_dwordx4 v[34:35], v[0:3], off offset:64
	global_store_dwordx4 v[34:35], v[4:7], off offset:96
	s_nop 1
	s_cbranch_vccz .LBB0_490

.LBB0_485:
	s_lshl_b64 s[18:19], s[80:81], 11
	v_div_scale_f32 v33, s[80:81], v32, v32, 1.0
	v_rcp_f32_e32 v34, v33
	s_add_u32 s18, s48, s18
	s_addc_u32 s19, s49, s19
	s_add_u32 s18, s18, s82
	v_fma_f32 v35, -v33, v34, 1.0
	v_fmac_f32_e32 v34, v35, v34
	v_div_scale_f32 v35, vcc, 1.0, v32, 1.0
	v_mul_f32_e32 v36, v35, v34
	v_fma_f32 v37, -v33, v36, v35
	v_fmac_f32_e32 v36, v37, v34
	v_fma_f32 v33, -v33, v36, v35
	v_div_fmas_f32 v33, v33, v34, v36
	s_addc_u32 s19, s19, s83
	v_div_fixup_f32 v32, v33, v32, 1.0
	v_lshl_add_u64 v[34:35], s[18:19], 0, v[144:145]
	v_mov_b32_e32 v153, v145
	v_pk_mul_f32 v[16:17], v[32:33], v[16:17] op_sel_hi:[0,1]
	v_pk_mul_f32 v[18:19], v[32:33], v[18:19] op_sel_hi:[0,1]
	v_pk_mul_f32 v[20:21], v[32:33], v[20:21] op_sel_hi:[0,1]
	v_pk_mul_f32 v[22:23], v[32:33], v[22:23] op_sel_hi:[0,1]
	v_pk_mul_f32 v[24:25], v[32:33], v[24:25] op_sel_hi:[0,1]
	v_pk_mul_f32 v[26:27], v[32:33], v[26:27] op_sel_hi:[0,1]
	v_pk_mul_f32 v[28:29], v[32:33], v[28:29] op_sel_hi:[0,1]
	v_pk_mul_f32 v[30:31], v[32:33], v[30:31] op_sel_hi:[0,1]
	v_pk_mul_f32 v[0:1], v[32:33], v[0:1] op_sel_hi:[0,1]
	v_pk_mul_f32 v[2:3], v[32:33], v[2:3] op_sel_hi:[0,1]
	v_pk_mul_f32 v[4:5], v[32:33], v[4:5] op_sel_hi:[0,1]
	v_pk_mul_f32 v[6:7], v[32:33], v[6:7] op_sel_hi:[0,1]
	v_pk_mul_f32 v[8:9], v[32:33], v[8:9] op_sel_hi:[0,1]
	v_pk_mul_f32 v[10:11], v[32:33], v[10:11] op_sel_hi:[0,1]
	v_pk_mul_f32 v[12:13], v[32:33], v[12:13] op_sel_hi:[0,1]
	v_pk_mul_f32 v[14:15], v[32:33], v[14:15] op_sel_hi:[0,1]
	v_lshl_add_u64 v[34:35], v[34:35], 0, v[152:153]
	v_lshl_add_u64 v[34:35], v[34:35], 0, v[152:153]
	v_cvt_pk_bf16_f32 v16, v16, v17
	v_cvt_pk_bf16_f32 v17, v18, v19
	v_cvt_pk_bf16_f32 v18, v20, v21
	v_cvt_pk_bf16_f32 v19, v22, v23
	v_cvt_pk_bf16_f32 v20, v24, v25
	v_cvt_pk_bf16_f32 v21, v26, v27
	v_cvt_pk_bf16_f32 v22, v28, v29
	v_cvt_pk_bf16_f32 v23, v30, v31
	v_cvt_pk_bf16_f32 v0, v0, v1
	v_cvt_pk_bf16_f32 v1, v2, v3
	v_cvt_pk_bf16_f32 v2, v4, v5
	v_cvt_pk_bf16_f32 v3, v6, v7
	v_cvt_pk_bf16_f32 v4, v8, v9
	v_cvt_pk_bf16_f32 v5, v10, v11
	v_cvt_pk_bf16_f32 v6, v12, v13
	v_cvt_pk_bf16_f32 v7, v14, v15
	s_or_b32 s46, s17, s94
	s_and_b64 vcc, exec, s[86:87]
	s_nop 1
	v_permlane32_swap_b32 v16, v18
	v_permlane32_swap_b32 v17, v19
	v_permlane32_swap_b32 v20, v22
	v_permlane32_swap_b32 v21, v23
	v_permlane32_swap_b32 v0, v2
	v_permlane32_swap_b32 v1, v3
	v_permlane32_swap_b32 v4, v6
	v_permlane32_swap_b32 v5, v7
	global_store_dwordx4 v[34:35], v[16:19], off
	global_store_dwordx4 v[34:35], v[20:23], off offset:32
	global_store_dwordx4 v[34:35], v[0:3], off offset:64
	global_store_dwordx4 v[34:35], v[4:7], off offset:96
	s_nop 1
	s_cbranch_vccz .LBB0_488
	ds_read_b128 v[0:3], v178
	ds_read_b128 v[4:7], v178 offset:32
	s_waitcnt lgkmcnt(1)
	v_mfma_f32_32x32x16_bf16 v[64:79], v[0:3], v[124:127], 0
	ds_read_b128 v[0:3], v178 offset:64
	ds_read_b128 v[48:51], v178 offset:13856
	ds_read_b128 v[128:131], v178 offset:18464
	s_waitcnt lgkmcnt(3)
	v_mfma_f32_32x32x16_bf16 v[64:79], v[4:7], v[120:123], v[64:79]
	s_waitcnt lgkmcnt(2)
	v_mfma_f32_32x32x16_bf16 v[64:79], v[0:3], v[112:115], v[64:79]
	ds_read_b128 v[0:3], v178 offset:96
	s_waitcnt lgkmcnt(0)
	v_mfma_f32_32x32x16_bf16 v[64:79], v[0:3], v[116:119], v[64:79]
	ds_read_b128 v[0:3], v178 offset:4608
	s_waitcnt lgkmcnt(0)
	v_mfma_f32_32x32x16_bf16 v[32:47], v[0:3], v[124:127], 0
	ds_read_b128 v[0:3], v178 offset:4640
	s_nop 7
	v_mul_f32_e32 v64, 0x3e38aa3b, v64
	v_mul_f32_e32 v65, 0x3e38aa3b, v65
	v_mul_f32_e32 v66, 0x3e38aa3b, v66
	v_mul_f32_e32 v67, 0x3e38aa3b, v67
	v_mul_f32_e32 v68, 0x3e38aa3b, v68
	v_mul_f32_e32 v69, 0x3e38aa3b, v69
	s_waitcnt lgkmcnt(0)
	v_mfma_f32_32x32x16_bf16 v[32:47], v[0:3], v[120:123], v[32:47]
	ds_read_b128 v[0:3], v178 offset:4672
	v_mul_f32_e32 v70, 0x3e38aa3b, v70
	v_mul_f32_e32 v71, 0x3e38aa3b, v71
	v_mul_f32_e32 v72, 0x3e38aa3b, v72
	v_mul_f32_e32 v73, 0x3e38aa3b, v73
	v_mul_f32_e32 v74, 0x3e38aa3b, v74
	v_mul_f32_e32 v75, 0x3e38aa3b, v75
	s_waitcnt lgkmcnt(0)
	v_mfma_f32_32x32x16_bf16 v[32:47], v[0:3], v[112:115], v[32:47]
	ds_read_b128 v[0:3], v178 offset:4704
	v_mul_f32_e32 v76, 0x3e38aa3b, v76
	v_mul_f32_e32 v77, 0x3e38aa3b, v77
	v_mul_f32_e32 v78, 0x3e38aa3b, v78
	v_mul_f32_e32 v79, 0x3e38aa3b, v79
	s_waitcnt lgkmcnt(0)
	v_mfma_f32_32x32x16_bf16 v[32:47], v[0:3], v[116:119], v[32:47]
	ds_read_b128 v[0:3], v178 offset:9216
	s_waitcnt lgkmcnt(0)
	v_mfma_f32_32x32x16_bf16 v[16:31], v[0:3], v[124:127], 0
	ds_read_b128 v[0:3], v178 offset:9248
	s_nop 7
	v_mul_f32_e32 v133, 0x3e38aa3b, v33
	s_waitcnt lgkmcnt(0)
	v_mfma_f32_32x32x16_bf16 v[16:31], v[0:3], v[120:123], v[16:31]
	ds_read_b128 v[0:3], v178 offset:9280
	s_waitcnt lgkmcnt(0)
	v_mfma_f32_32x32x16_bf16 v[16:31], v[0:3], v[112:115], v[16:31]
	ds_read_b128 v[0:3], v178 offset:9312
	s_waitcnt lgkmcnt(0)
	v_mfma_f32_32x32x16_bf16 v[16:31], v[0:3], v[116:119], v[16:31]
	ds_read_b128 v[0:3], v178 offset:13824
	s_waitcnt lgkmcnt(0)
	v_mfma_f32_32x32x16_bf16 v[0:15], v[0:3], v[124:127], 0
	v_mfma_f32_32x32x16_bf16 v[0:15], v[48:51], v[120:123], v[0:15]
	ds_read_b128 v[48:51], v178 offset:13888
	s_waitcnt lgkmcnt(0)
	v_mfma_f32_32x32x16_bf16 v[0:15], v[48:51], v[112:115], v[0:15]
	ds_read_b128 v[48:51], v178 offset:13920
	s_waitcnt lgkmcnt(0)
	v_mfma_f32_32x32x16_bf16 v[0:15], v[48:51], v[116:119], v[0:15]
	ds_read_b128 v[48:51], v178 offset:18432
	s_waitcnt lgkmcnt(0)
	v_mfma_f32_32x32x16_bf16 v[48:63], v[48:51], v[124:127], 0
	v_mfma_f32_32x32x16_bf16 v[48:63], v[128:131], v[120:123], v[48:63]
	ds_read_b128 v[128:131], v178 offset:18496
	s_waitcnt lgkmcnt(0)
	v_mfma_f32_32x32x16_bf16 v[48:63], v[128:131], v[112:115], v[48:63]
	ds_read_b128 v[128:131], v178 offset:18528
	s_waitcnt lgkmcnt(0)
	v_mfma_f32_32x32x16_bf16 v[48:63], v[128:131], v[116:119], v[48:63]
	v_add_u32_e32 v128, s17, v164
	v_or_b32_e32 v130, s46, v158
	v_sub_u32_e32 v131, v130, v128
	v_cmp_gt_i32_e32 vcc, s92, v131
	v_sub_u32_e32 v132, v128, v130
	v_add_u32_e32 v129, 0x9b, v128
	v_cndmask_b32_e32 v64, v177, v64, vcc
	v_cmp_lt_i32_e32 vcc, s93, v132
	s_nop 3
	v_mul_f32_e32 v48, 0x3e38aa3b, v48
	v_mul_f32_e32 v49, 0x3e38aa3b, v49
	v_cndmask_b32_e32 v65, v177, v65, vcc
	v_cmp_gt_i32_e32 vcc, s4, v131
	v_max3_f32 v132, v64, s1, v65
	v_mul_f32_e32 v50, 0x3e38aa3b, v50
	v_cndmask_b32_e32 v66, v177, v66, vcc
	v_cmp_gt_i32_e32 vcc, s5, v131
	v_mul_f32_e32 v51, 0x3e38aa3b, v51
	v_mul_f32_e32 v52, 0x3e38aa3b, v52
	v_cndmask_b32_e32 v67, v177, v67, vcc
	v_cmp_gt_i32_e32 vcc, s6, v131
	v_max3_f32 v132, v132, v66, v67
	v_mul_f32_e32 v53, 0x3e38aa3b, v53
	v_cndmask_b32_e32 v68, v177, v68, vcc
	v_cmp_gt_i32_e32 vcc, s7, v131
	s_nop 1
	v_cndmask_b32_e32 v69, v177, v69, vcc
	v_cmp_gt_i32_e32 vcc, s8, v131
	v_max3_f32 v132, v132, v68, v69
	s_nop 0
	v_cndmask_b32_e32 v70, v177, v70, vcc
	v_cmp_gt_i32_e32 vcc, s9, v131
	s_nop 1
	v_cndmask_b32_e32 v71, v177, v71, vcc
	v_cmp_gt_i32_e32 vcc, s33, v131
	v_max3_f32 v132, v132, v70, v71
	s_nop 0
	v_cndmask_b32_e32 v72, v177, v72, vcc
	v_cmp_gt_i32_e32 vcc, s10, v131
	s_nop 1
	v_cndmask_b32_e32 v73, v177, v73, vcc
	v_cmp_gt_i32_e32 vcc, s11, v131
	v_max3_f32 v132, v132, v72, v73
	s_nop 0
	v_cndmask_b32_e32 v74, v177, v74, vcc
	v_cmp_gt_i32_e32 vcc, s12, v131
	s_nop 1
	v_cndmask_b32_e32 v75, v177, v75, vcc
	v_cmp_gt_i32_e32 vcc, s13, v131
	v_max3_f32 v132, v132, v74, v75
	s_nop 0
	v_cndmask_b32_e32 v76, v177, v76, vcc
	v_cmp_gt_i32_e32 vcc, s14, v131
	s_nop 1
	v_cndmask_b32_e32 v77, v177, v77, vcc
	v_cmp_gt_i32_e32 vcc, s15, v131
	v_max3_f32 v132, v132, v76, v77
	s_nop 0
	v_cndmask_b32_e32 v78, v177, v78, vcc
	v_cmp_gt_i32_e32 vcc, s97, v131
	s_nop 1
	v_cndmask_b32_e32 v79, v177, v79, vcc
	v_max3_f32 v131, v132, v78, v79
	v_mul_f32_e32 v132, 0x3e38aa3b, v32
	v_max3_f32 v131, v131, v132, v133
	v_mul_f32_e32 v132, 0x3e38aa3b, v34
	v_mul_f32_e32 v133, 0x3e38aa3b, v35
	v_max3_f32 v131, v131, v132, v133
	v_mul_f32_e32 v132, 0x3e38aa3b, v36
	v_mul_f32_e32 v133, 0x3e38aa3b, v37
	v_max3_f32 v131, v131, v132, v133
	v_mul_f32_e32 v132, 0x3e38aa3b, v38
	v_mul_f32_e32 v133, 0x3e38aa3b, v39
	v_max3_f32 v131, v131, v132, v133
	v_mul_f32_e32 v132, 0x3e38aa3b, v40
	v_mul_f32_e32 v133, 0x3e38aa3b, v41
	v_max3_f32 v131, v131, v132, v133
	v_mul_f32_e32 v132, 0x3e38aa3b, v42
	v_mul_f32_e32 v133, 0x3e38aa3b, v43
	v_max3_f32 v131, v131, v132, v133
	v_mul_f32_e32 v132, 0x3e38aa3b, v44
	v_mul_f32_e32 v133, 0x3e38aa3b, v45
	v_max3_f32 v131, v131, v132, v133
	v_mul_f32_e32 v132, 0x3e38aa3b, v46
	v_mul_f32_e32 v133, 0x3e38aa3b, v47
	v_max3_f32 v131, v131, v132, v133
	v_mul_f32_e32 v132, 0x3e38aa3b, v16
	v_mul_f32_e32 v133, 0x3e38aa3b, v17
	v_max3_f32 v131, v131, v132, v133
	v_mul_f32_e32 v132, 0x3e38aa3b, v18
	v_mul_f32_e32 v133, 0x3e38aa3b, v19
	v_max3_f32 v131, v131, v132, v133
	v_mul_f32_e32 v132, 0x3e38aa3b, v20
	v_mul_f32_e32 v133, 0x3e38aa3b, v21
	v_max3_f32 v131, v131, v132, v133
	v_mul_f32_e32 v132, 0x3e38aa3b, v22
	v_mul_f32_e32 v133, 0x3e38aa3b, v23
	v_max3_f32 v131, v131, v132, v133
	v_mul_f32_e32 v132, 0x3e38aa3b, v24
	v_mul_f32_e32 v133, 0x3e38aa3b, v25
	v_max3_f32 v131, v131, v132, v133
	v_mul_f32_e32 v132, 0x3e38aa3b, v26
	v_mul_f32_e32 v133, 0x3e38aa3b, v27
	v_max3_f32 v131, v131, v132, v133
	v_mul_f32_e32 v132, 0x3e38aa3b, v28
	v_mul_f32_e32 v133, 0x3e38aa3b, v29
	v_max3_f32 v131, v131, v132, v133
	v_mul_f32_e32 v132, 0x3e38aa3b, v30
	v_mul_f32_e32 v133, 0x3e38aa3b, v31
	v_max3_f32 v131, v131, v132, v133
	v_mul_f32_e32 v132, 0x3e38aa3b, v0
	v_mul_f32_e32 v133, 0x3e38aa3b, v1
	v_max3_f32 v131, v131, v132, v133
	v_mul_f32_e32 v132, 0x3e38aa3b, v2
	v_mul_f32_e32 v133, 0x3e38aa3b, v3
	v_max3_f32 v131, v131, v132, v133
	v_mul_f32_e32 v132, 0x3e38aa3b, v4
	v_mul_f32_e32 v133, 0x3e38aa3b, v5
	v_max3_f32 v131, v131, v132, v133
	v_mul_f32_e32 v132, 0x3e38aa3b, v6
	v_mul_f32_e32 v133, 0x3e38aa3b, v7
	v_max3_f32 v131, v131, v132, v133
	v_mul_f32_e32 v132, 0x3e38aa3b, v8
	v_mul_f32_e32 v133, 0x3e38aa3b, v9
	v_max3_f32 v131, v131, v132, v133
	v_mul_f32_e32 v132, 0x3e38aa3b, v10
	v_mul_f32_e32 v133, 0x3e38aa3b, v11
	v_max3_f32 v131, v131, v132, v133
	v_mul_f32_e32 v132, 0x3e38aa3b, v12
	v_mul_f32_e32 v133, 0x3e38aa3b, v13
	v_max3_f32 v131, v131, v132, v133
	v_mul_f32_e32 v132, 0x3e38aa3b, v14
	v_mul_f32_e32 v133, 0x3e38aa3b, v15
	v_max3_f32 v131, v131, v132, v133
	v_add_u32_e32 v132, 0x80, v128
	v_cmp_ge_u32_e32 vcc, v130, v132
	v_add_u32_e32 v132, 0x81, v128
	s_nop 0
	v_cndmask_b32_e32 v48, v177, v48, vcc
	v_cmp_ge_u32_e32 vcc, v130, v132
	v_add_u32_e32 v132, 0x82, v128
	s_nop 0
	v_cndmask_b32_e32 v49, v177, v49, vcc
	v_cmp_ge_u32_e32 vcc, v130, v132
	v_add_u32_e32 v132, 0x83, v128
	v_max3_f32 v131, v131, v48, v49
	v_cndmask_b32_e32 v50, v177, v50, vcc
	v_cmp_ge_u32_e32 vcc, v130, v132
	s_nop 1
	v_cndmask_b32_e32 v201, v177, v51, vcc
	v_max3_f32 v51, v131, v50, v201
	v_add_u32_e32 v131, 0x88, v128
	v_cmp_ge_u32_e32 vcc, v130, v131
	s_nop 1
	v_cndmask_b32_e32 v202, v177, v52, vcc
	v_add_u32_e32 v52, 0x89, v128
	v_cmp_ge_u32_e32 vcc, v130, v52
	v_add_u32_e32 v52, 0x8a, v128
	s_nop 0
	v_cndmask_b32_e32 v203, v177, v53, vcc
	v_mul_f32_e32 v53, 0x3e38aa3b, v54
	v_cmp_ge_u32_e32 vcc, v130, v52
	v_add_u32_e32 v52, 0x8b, v128
	v_max3_f32 v51, v51, v202, v203
	v_cndmask_b32_e32 v204, v177, v53, vcc
	v_mul_f32_e32 v53, 0x3e38aa3b, v55
	v_cmp_ge_u32_e32 vcc, v130, v52
	v_add_u32_e32 v52, 0x90, v128
	s_nop 0
	v_cndmask_b32_e32 v205, v177, v53, vcc
	v_mul_f32_e32 v53, 0x3e38aa3b, v56
	v_cmp_ge_u32_e32 vcc, v130, v52
	v_add_u32_e32 v52, 0x91, v128
	v_max3_f32 v51, v51, v204, v205
	v_cndmask_b32_e32 v206, v177, v53, vcc
	v_mul_f32_e32 v53, 0x3e38aa3b, v57
	v_cmp_ge_u32_e32 vcc, v130, v52
	v_add_u32_e32 v52, 0x92, v128
	s_nop 0
	v_cndmask_b32_e32 v207, v177, v53, vcc
	v_mul_f32_e32 v53, 0x3e38aa3b, v58
	v_cmp_ge_u32_e32 vcc, v130, v52
	v_add_u32_e32 v52, 0x93, v128
	v_max3_f32 v51, v51, v206, v207
	v_cndmask_b32_e32 v208, v177, v53, vcc
	v_mul_f32_e32 v53, 0x3e38aa3b, v59
	v_cmp_ge_u32_e32 vcc, v130, v52
	v_add_u32_e32 v52, 0x98, v128
	s_nop 0
	v_cndmask_b32_e32 v209, v177, v53, vcc
	v_mul_f32_e32 v53, 0x3e38aa3b, v60
	v_cmp_ge_u32_e32 vcc, v130, v52
	v_add_u32_e32 v52, 0x99, v128
	v_max3_f32 v51, v51, v208, v209
	v_cndmask_b32_e32 v210, v177, v53, vcc
	v_mul_f32_e32 v53, 0x3e38aa3b, v61
	v_cmp_ge_u32_e32 vcc, v130, v52
	v_add_u32_e32 v52, 0x9a, v128
	s_nop 0
	v_cndmask_b32_e32 v211, v177, v53, vcc
	v_mul_f32_e32 v53, 0x3e38aa3b, v62
	v_cmp_ge_u32_e32 vcc, v130, v52
	v_mul_f32_e32 v52, 0x3e38aa3b, v63
	v_max3_f32 v51, v51, v210, v211
	v_cndmask_b32_e32 v212, v177, v53, vcc
	v_cmp_ge_u32_e32 vcc, v130, v129
	v_and_b32_e32 v53, 64, v180
	v_add_u32_e32 v53, 64, v53
	v_cndmask_b32_e32 v213, v177, v52, vcc
	v_xor_b32_e32 v52, 32, v180
	v_cmp_lt_i32_e32 vcc, v52, v53
	v_max3_f32 v51, v51, v212, v213
	s_nop 0
	v_cndmask_b32_e32 v52, v180, v52, vcc
	v_lshlrev_b32_e32 v214, 2, v52
	ds_bpermute_b32 v52, v214, v51
	s_waitcnt lgkmcnt(0)
	v_max3_f32 v215, v51, v52, v179
	v_sub_f32_e32 v51, v64, v215
	v_exp_f32_e32 v187, v51
	v_sub_f32_e32 v52, v65, v215
	v_exp_f32_e32 v190, v52
	v_sub_f32_e32 v52, v66, v215
	v_exp_f32_e32 v195, v52
	v_sub_f32_e32 v52, v67, v215
	v_exp_f32_e32 v196, v52
	v_sub_f32_e32 v52, v68, v215
	v_add_f32_e32 v51, 0, v187
	v_exp_f32_e32 v197, v52
	v_sub_f32_e32 v52, v69, v215
	v_add_f32_e32 v51, v190, v51
	v_exp_f32_e32 v198, v52
	v_sub_f32_e32 v52, v70, v215
	v_add_f32_e32 v51, v195, v51
	v_exp_f32_e32 v199, v52
	v_sub_f32_e32 v52, v71, v215
	v_add_f32_e32 v51, v196, v51
	v_exp_f32_e32 v200, v52
	v_sub_f32_e32 v52, v72, v215
	v_add_f32_e32 v51, v197, v51
	v_exp_f32_e32 v142, v52
	v_sub_f32_e32 v52, v73, v215
	v_add_f32_e32 v51, v198, v51
	v_exp_f32_e32 v182, v52
	v_sub_f32_e32 v52, v74, v215
	v_add_f32_e32 v51, v199, v51
	v_exp_f32_e32 v186, v52
	v_sub_f32_e32 v52, v75, v215
	v_add_f32_e32 v51, v200, v51
	v_exp_f32_e32 v189, v52
	v_sub_f32_e32 v52, v76, v215
	v_add_f32_e32 v51, v142, v51
	v_exp_f32_e32 v191, v52
	v_sub_f32_e32 v52, v77, v215
	v_add_f32_e32 v51, v182, v51
	v_exp_f32_e32 v192, v52
	v_sub_f32_e32 v52, v78, v215
	v_add_f32_e32 v51, v186, v51
	v_exp_f32_e32 v193, v52
	v_sub_f32_e32 v52, v79, v215
	v_add_f32_e32 v51, v189, v51
	v_exp_f32_e32 v194, v52
	v_fma_f32 v32, v32, s0, -v215
	v_add_f32_e32 v51, v191, v51
	v_exp_f32_e32 v76, v32
	v_fma_f32 v33, v33, s0, -v215
	v_add_f32_e32 v51, v192, v51
	v_exp_f32_e32 v79, v33
	v_fma_f32 v33, v34, s0, -v215
	v_add_f32_e32 v51, v193, v51
	v_exp_f32_e32 v132, v33
	v_fma_f32 v33, v35, s0, -v215
	v_add_f32_e32 v51, v194, v51
	v_exp_f32_e32 v135, v33
	v_fma_f32 v33, v36, s0, -v215
	v_add_f32_e32 v32, v76, v51
	v_exp_f32_e32 v138, v33
	v_fma_f32 v33, v37, s0, -v215
	v_add_f32_e32 v32, v79, v32
	v_exp_f32_e32 v140, v33
	v_fma_f32 v33, v38, s0, -v215
	v_add_f32_e32 v32, v132, v32
	v_exp_f32_e32 v153, v33
	v_fma_f32 v33, v39, s0, -v215
	v_add_f32_e32 v32, v135, v32
	v_exp_f32_e32 v184, v33
	v_fma_f32 v33, v40, s0, -v215
	v_add_f32_e32 v32, v138, v32
	v_exp_f32_e32 v128, v33
	v_fma_f32 v33, v41, s0, -v215
	v_add_f32_e32 v32, v140, v32
	v_exp_f32_e32 v131, v33
	v_fma_f32 v33, v42, s0, -v215
	v_add_f32_e32 v32, v153, v32
	v_exp_f32_e32 v136, v33
	v_fma_f32 v33, v43, s0, -v215
	v_add_f32_e32 v32, v184, v32
	v_exp_f32_e32 v139, v33
	v_fma_f32 v33, v44, s0, -v215
	v_add_f32_e32 v32, v128, v32
	v_exp_f32_e32 v141, v33
	v_fma_f32 v33, v45, s0, -v215
	v_add_f32_e32 v32, v131, v32
	v_exp_f32_e32 v143, v33
	v_fma_f32 v33, v46, s0, -v215
	v_add_f32_e32 v32, v136, v32
	v_exp_f32_e32 v185, v33
	v_fma_f32 v33, v47, s0, -v215
	v_add_f32_e32 v32, v139, v32
	v_exp_f32_e32 v188, v33
	v_fma_f32 v16, v16, s0, -v215
	v_add_f32_e32 v32, v141, v32
	v_exp_f32_e32 v64, v16
	v_fma_f32 v17, v17, s0, -v215
	v_add_f32_e32 v32, v143, v32
	v_exp_f32_e32 v66, v17
	v_fma_f32 v17, v18, s0, -v215
	v_add_f32_e32 v32, v185, v32
	v_exp_f32_e32 v70, v17
	v_fma_f32 v17, v19, s0, -v215
	v_add_f32_e32 v32, v188, v32
	v_exp_f32_e32 v72, v17
	v_fma_f32 v17, v20, s0, -v215
	v_add_f32_e32 v16, v64, v32
	v_exp_f32_e32 v74, v17
	v_fma_f32 v17, v21, s0, -v215
	v_add_f32_e32 v16, v66, v16
	v_exp_f32_e32 v77, v17
	v_fma_f32 v17, v22, s0, -v215
	v_add_f32_e32 v16, v70, v16
	v_exp_f32_e32 v130, v17
	v_fma_f32 v17, v23, s0, -v215
	v_add_f32_e32 v16, v72, v16
	v_exp_f32_e32 v133, v17
	v_fma_f32 v17, v24, s0, -v215
	v_add_f32_e32 v16, v74, v16
	v_exp_f32_e32 v67, v17
	v_fma_f32 v17, v25, s0, -v215
	v_add_f32_e32 v16, v77, v16
	v_exp_f32_e32 v69, v17
	v_fma_f32 v17, v26, s0, -v215
	v_add_f32_e32 v16, v130, v16
	v_exp_f32_e32 v73, v17
	v_fma_f32 v17, v27, s0, -v215
	v_add_f32_e32 v16, v133, v16
	v_exp_f32_e32 v75, v17
	v_fma_f32 v17, v28, s0, -v215
	v_add_f32_e32 v16, v67, v16
	v_exp_f32_e32 v78, v17
	v_fma_f32 v17, v29, s0, -v215
	v_add_f32_e32 v16, v69, v16
	v_exp_f32_e32 v129, v17
	v_fma_f32 v17, v30, s0, -v215
	v_add_f32_e32 v16, v73, v16
	v_exp_f32_e32 v134, v17
	v_fma_f32 v17, v31, s0, -v215
	v_add_f32_e32 v16, v75, v16
	v_exp_f32_e32 v137, v17
	v_fma_f32 v0, v0, s0, -v215
	v_add_f32_e32 v16, v78, v16
	v_exp_f32_e32 v51, v0
	v_fma_f32 v1, v1, s0, -v215
	v_add_f32_e32 v16, v129, v16
	v_exp_f32_e32 v52, v1
	v_fma_f32 v1, v2, s0, -v215
	v_add_f32_e32 v16, v134, v16
	v_exp_f32_e32 v57, v1
	v_fma_f32 v1, v3, s0, -v215
	v_add_f32_e32 v16, v137, v16
	v_exp_f32_e32 v61, v1
	v_fma_f32 v1, v4, s0, -v215
	v_add_f32_e32 v0, v51, v16
	v_exp_f32_e32 v63, v1
	v_fma_f32 v1, v5, s0, -v215
	v_add_f32_e32 v0, v52, v0
	v_exp_f32_e32 v65, v1
	v_fma_f32 v1, v6, s0, -v215
	v_add_f32_e32 v0, v57, v0
	v_exp_f32_e32 v68, v1
	v_fma_f32 v1, v7, s0, -v215
	v_add_f32_e32 v0, v61, v0
	v_exp_f32_e32 v71, v1
	v_fma_f32 v1, v8, s0, -v215
	v_add_f32_e32 v0, v63, v0
	v_exp_f32_e32 v53, v1
	v_fma_f32 v1, v9, s0, -v215
	v_add_f32_e32 v0, v65, v0
	v_exp_f32_e32 v54, v1
	v_fma_f32 v1, v10, s0, -v215
	v_add_f32_e32 v0, v68, v0
	v_exp_f32_e32 v55, v1
	v_fma_f32 v1, v11, s0, -v215
	v_add_f32_e32 v0, v71, v0
	v_exp_f32_e32 v56, v1
	v_fma_f32 v1, v12, s0, -v215
	v_add_f32_e32 v0, v53, v0
	v_exp_f32_e32 v58, v1
	v_fma_f32 v1, v13, s0, -v215
	v_add_f32_e32 v0, v54, v0
	v_exp_f32_e32 v59, v1
	v_fma_f32 v1, v14, s0, -v215
	v_add_f32_e32 v0, v55, v0
	v_exp_f32_e32 v60, v1
	v_fma_f32 v1, v15, s0, -v215
	v_add_f32_e32 v0, v56, v0
	v_exp_f32_e32 v62, v1
	v_sub_f32_e32 v1, v48, v215
	v_add_f32_e32 v0, v58, v0
	v_exp_f32_e32 v43, v1
	v_sub_f32_e32 v1, v49, v215
	v_add_f32_e32 v0, v59, v0
	v_exp_f32_e32 v44, v1
	v_sub_f32_e32 v1, v50, v215
	v_add_f32_e32 v0, v60, v0
	v_exp_f32_e32 v45, v1
	v_sub_f32_e32 v1, v201, v215
	v_add_f32_e32 v0, v62, v0
	v_exp_f32_e32 v46, v1
	v_sub_f32_e32 v1, v202, v215
	v_add_f32_e32 v0, v43, v0
	v_exp_f32_e32 v47, v1
	v_sub_f32_e32 v1, v203, v215
	v_add_f32_e32 v0, v44, v0
	v_exp_f32_e32 v48, v1
	v_sub_f32_e32 v1, v204, v215
	v_add_f32_e32 v0, v45, v0
	v_exp_f32_e32 v49, v1
	v_sub_f32_e32 v1, v205, v215
	v_add_f32_e32 v0, v46, v0
	v_exp_f32_e32 v50, v1
	v_sub_f32_e32 v1, v206, v215
	v_add_f32_e32 v0, v47, v0
	v_exp_f32_e32 v35, v1
	v_sub_f32_e32 v1, v207, v215
	v_add_f32_e32 v0, v48, v0
	v_exp_f32_e32 v36, v1
	v_sub_f32_e32 v1, v208, v215
	v_add_f32_e32 v0, v49, v0
	v_exp_f32_e32 v37, v1
	v_sub_f32_e32 v1, v209, v215
	v_add_f32_e32 v0, v50, v0
	v_exp_f32_e32 v38, v1
	v_sub_f32_e32 v1, v210, v215
	v_add_f32_e32 v0, v35, v0
	v_exp_f32_e32 v39, v1
	v_sub_f32_e32 v1, v211, v215
	v_add_f32_e32 v0, v36, v0
	v_exp_f32_e32 v40, v1
	v_sub_f32_e32 v1, v212, v215
	v_add_f32_e32 v0, v37, v0
	v_exp_f32_e32 v41, v1
	v_sub_f32_e32 v1, v213, v215
	v_add_f32_e32 v0, v38, v0
	v_exp_f32_e32 v42, v1
	v_add_f32_e32 v0, v39, v0
	v_add_f32_e32 v0, v40, v0
	v_add_f32_e32 v0, v41, v0
	v_add_f32_e32 v32, v42, v0
	v_sub_f32_e32 v0, v179, v215
	v_exp_f32_e32 v34, v0
	v_cvt_pk_bf16_f32 v0, v187, v190
	v_add_u32_e32 v190, v165, v161
	v_add_u32_e32 v187, v165, v162
	ds_read_b64_tr_b16 v[4:5], v190 offset:36864
	ds_read_b64_tr_b16 v[6:7], v190 offset:37888
	ds_read_b64_tr_b16 v[8:9], v187 offset:36864
	ds_read_b64_tr_b16 v[10:11], v187 offset:37888
	v_cvt_pk_bf16_f32 v1, v195, v196
	v_cvt_pk_bf16_f32 v2, v197, v198
	v_cvt_pk_bf16_f32 v3, v199, v200
	v_cvt_pk_bf16_f32 v198, v191, v192
	v_cvt_pk_bf16_f32 v199, v193, v194
	s_waitcnt lgkmcnt(2)
	v_mfma_f32_32x32x16_bf16 v[16:31], v[4:7], v[0:3], 0
	ds_read_b64_tr_b16 v[192:193], v190 offset:38912
	ds_read_b64_tr_b16 v[194:195], v190 offset:39936
	ds_read_b64_tr_b16 v[200:201], v187 offset:38912
	ds_read_b64_tr_b16 v[202:203], v187 offset:39936
	v_cvt_pk_bf16_f32 v196, v142, v182
	v_cvt_pk_bf16_f32 v197, v186, v189
	v_cvt_pk_bf16_f32 v139, v136, v139
	v_cvt_pk_bf16_f32 v73, v73, v75
	v_cvt_pk_bf16_f32 v75, v134, v137
	v_cvt_pk_bf16_f32 v45, v45, v46
	s_waitcnt lgkmcnt(4)
	v_mfma_f32_32x32x16_bf16 v[0:15], v[8:11], v[0:3], 0
	v_cvt_pk_bf16_f32 v46, v47, v48
	v_cvt_pk_bf16_f32 v47, v49, v50
	v_cvt_pk_bf16_f32 v44, v43, v44
	ds_bpermute_b32 v33, v214, v32
	v_cvt_pk_bf16_f32 v37, v37, v38
	v_cvt_pk_bf16_f32 v38, v39, v40
	v_cvt_pk_bf16_f32 v39, v41, v42
	s_waitcnt lgkmcnt(3)
	v_mfma_f32_32x32x16_bf16 v[16:31], v[192:195], v[196:199], v[16:31]
	v_cvt_pk_bf16_f32 v192, v76, v79
	v_cvt_pk_bf16_f32 v193, v132, v135
	v_cvt_pk_bf16_f32 v194, v138, v140
	v_cvt_pk_bf16_f32 v195, v153, v184
	v_cvt_pk_bf16_f32 v138, v128, v131
	v_cvt_pk_bf16_f32 v140, v141, v143
	v_cvt_pk_bf16_f32 v141, v185, v188
	s_waitcnt lgkmcnt(1)
	v_mfma_f32_32x32x16_bf16 v[0:15], v[200:203], v[196:199], v[0:15]
	ds_read_b64_tr_b16 v[196:197], v190 offset:40960
	ds_read_b64_tr_b16 v[198:199], v190 offset:41984
	ds_read_b64_tr_b16 v[200:201], v187 offset:40960
	ds_read_b64_tr_b16 v[202:203], v187 offset:41984
	v_cvt_pk_bf16_f32 v36, v35, v36
	s_waitcnt lgkmcnt(4)
	v_add_f32_e32 v32, v32, v33
	v_add_f32_e32 v32, v34, v32
	s_waitcnt lgkmcnt(2)
	v_mfma_f32_32x32x16_bf16 v[16:31], v[196:199], v[192:195], v[16:31]
	s_waitcnt lgkmcnt(0)
	v_mfma_f32_32x32x16_bf16 v[0:15], v[200:203], v[192:195], v[0:15]
	ds_read_b64_tr_b16 v[192:193], v190 offset:43008
	ds_read_b64_tr_b16 v[194:195], v190 offset:44032
	ds_read_b64_tr_b16 v[196:197], v187 offset:43008
	ds_read_b64_tr_b16 v[198:199], v187 offset:44032
	s_waitcnt lgkmcnt(2)
	v_mfma_f32_32x32x16_bf16 v[16:31], v[192:195], v[138:141], v[16:31]
	s_waitcnt lgkmcnt(0)
	v_mfma_f32_32x32x16_bf16 v[0:15], v[196:199], v[138:141], v[0:15]
	v_cvt_pk_bf16_f32 v141, v130, v133
	ds_read_b64_tr_b16 v[130:131], v190 offset:45056
	ds_read_b64_tr_b16 v[132:133], v190 offset:46080
	ds_read_b64_tr_b16 v[192:193], v187 offset:45056
	ds_read_b64_tr_b16 v[194:195], v187 offset:46080
	v_cvt_pk_bf16_f32 v138, v64, v66
	v_cvt_pk_bf16_f32 v139, v70, v72
	v_cvt_pk_bf16_f32 v140, v74, v77
	v_cvt_pk_bf16_f32 v74, v78, v129
	v_cvt_pk_bf16_f32 v72, v67, v69
	s_waitcnt lgkmcnt(2)
	v_mfma_f32_32x32x16_bf16 v[16:31], v[130:133], v[138:141], v[16:31]
	ds_read_b64_tr_b16 v[76:77], v190 offset:47104
	ds_read_b64_tr_b16 v[78:79], v190 offset:48128
	ds_read_b64_tr_b16 v[128:129], v187 offset:47104
	ds_read_b64_tr_b16 v[130:131], v187 offset:48128
	s_waitcnt lgkmcnt(4)
	v_mfma_f32_32x32x16_bf16 v[0:15], v[192:195], v[138:141], v[0:15]
	s_waitcnt lgkmcnt(2)
	v_mfma_f32_32x32x16_bf16 v[16:31], v[76:79], v[72:75], v[16:31]
	s_waitcnt lgkmcnt(0)
	v_mfma_f32_32x32x16_bf16 v[0:15], v[128:131], v[72:75], v[0:15]
	v_cvt_pk_bf16_f32 v74, v63, v65
	v_cvt_pk_bf16_f32 v75, v68, v71
	ds_read_b64_tr_b16 v[64:65], v190 offset:49152
	ds_read_b64_tr_b16 v[66:67], v190 offset:50176
	ds_read_b64_tr_b16 v[68:69], v187 offset:49152
	ds_read_b64_tr_b16 v[70:71], v187 offset:50176
	v_cvt_pk_bf16_f32 v72, v51, v52
	v_cvt_pk_bf16_f32 v73, v57, v61
	v_cvt_pk_bf16_f32 v52, v53, v54
	v_cvt_pk_bf16_f32 v53, v55, v56
	s_waitcnt lgkmcnt(2)
	v_mfma_f32_32x32x16_bf16 v[16:31], v[64:67], v[72:75], v[16:31]
	v_cvt_pk_bf16_f32 v54, v58, v59
	v_cvt_pk_bf16_f32 v55, v60, v62
	ds_read_b64_tr_b16 v[56:57], v190 offset:51200
	ds_read_b64_tr_b16 v[58:59], v190 offset:52224
	ds_read_b64_tr_b16 v[60:61], v187 offset:51200
	ds_read_b64_tr_b16 v[62:63], v187 offset:52224
	s_waitcnt lgkmcnt(4)
	v_mfma_f32_32x32x16_bf16 v[0:15], v[68:71], v[72:75], v[0:15]
	s_waitcnt lgkmcnt(2)
	v_mfma_f32_32x32x16_bf16 v[16:31], v[56:59], v[52:55], v[16:31]
	s_waitcnt lgkmcnt(0)
	v_mfma_f32_32x32x16_bf16 v[0:15], v[60:63], v[52:55], v[0:15]
	ds_read_b64_tr_b16 v[48:49], v190 offset:53248
	ds_read_b64_tr_b16 v[50:51], v190 offset:54272
	ds_read_b64_tr_b16 v[52:53], v187 offset:53248
	ds_read_b64_tr_b16 v[54:55], v187 offset:54272
	s_waitcnt lgkmcnt(2)
	v_mfma_f32_32x32x16_bf16 v[16:31], v[48:51], v[44:47], v[16:31]
	s_waitcnt lgkmcnt(0)
	v_mfma_f32_32x32x16_bf16 v[0:15], v[52:55], v[44:47], v[0:15]
	ds_read_b64_tr_b16 v[40:41], v190 offset:55296
	ds_read_b64_tr_b16 v[42:43], v190 offset:56320
	ds_read_b64_tr_b16 v[44:45], v187 offset:55296
	ds_read_b64_tr_b16 v[46:47], v187 offset:56320
	s_waitcnt lgkmcnt(2)
	v_mfma_f32_32x32x16_bf16 v[16:31], v[40:43], v[36:39], v[16:31]
	s_waitcnt lgkmcnt(0)
	v_mfma_f32_32x32x16_bf16 v[0:15], v[44:47], v[36:39], v[0:15]
	s_cbranch_execnz .LBB0_471
	s_branch .LBB0_489

.LBB0_1110:
	s_add_i32 s44, s78, s33
	s_ashr_i32 s70, s44, 11
	s_bfe_u32 s90, s44, 0x30006
	s_and_b32 s44, s44, 63
	s_lshl_b32 s89, s70, 1
	s_lshr_b32 s92, s44, s89
	s_bfm_b32 s45, s89, 0
	s_lshl_b32 s91, s92, 7
	s_and_b32 s46, s45, s44
	s_or_b32 s54, s91, s80
	s_and_b32 s47, s84, 0x6000
	s_lshl_b64 s[44:45], s[54:55], s89
	s_or_b32 s46, s46, s47
	s_add_u32 s56, s44, s46
	s_addc_u32 s57, s45, 0
	s_mul_i32 s44, s57, 0x1400
	s_mul_hi_u32 s45, s56, 0x1400
	s_add_i32 s45, s45, s44
	s_mul_i32 s44, s56, 0x1400
	s_add_u32 s44, s76, s44
	s_addc_u32 s45, s77, s45
	s_lshl_b32 s46, s90, 7
	s_add_u32 s44, s44, s46
	s_addc_u32 s45, s45, 0
	s_lshl_b64 s[46:47], 0xa00, s89
	v_mad_u64_u32 v[0:1], s[58:59], s46, v162, 0
	v_mov_b32_e32 v2, v1
	v_mad_u64_u32 v[2:3], s[46:47], s47, v162, v[2:3]
	v_mov_b32_e32 v1, v2
	v_lshl_add_u64 v[0:1], v[0:1], 1, s[44:45]
	v_lshl_add_u64 v[0:1], v[0:1], 0, v[160:161]
	global_load_dwordx4 v[156:159], v[0:1], off
	global_load_dwordx4 v[152:155], v[0:1], off offset:32
	global_load_dwordx4 v[148:151], v[0:1], off offset:64
	global_load_dwordx4 v[144:147], v[0:1], off offset:96
	s_barrier
	s_waitcnt vmcnt(4)
	ds_write_b128 v179, v[80:83]
	s_waitcnt vmcnt(4)
	ds_write_b128 v180, v[84:87] offset:36864
	ds_write_b128 v179, v[92:95] offset:4608
	ds_write_b128 v182, v[88:91] offset:36864
	ds_write_b128 v179, v[100:103] offset:9216
	ds_write_b128 v184, v[96:99] offset:36864
	ds_write_b128 v179, v[104:107] offset:13824
	ds_write_b128 v185, v[108:111] offset:36864
	s_waitcnt vmcnt(4)
	ds_write_b128 v179, v[112:115] offset:18432
	s_waitcnt vmcnt(4)
	ds_write_b128 v186, v[128:131] offset:36864
	ds_write_b128 v179, v[120:123] offset:23040
	ds_write_b128 v187, v[132:135] offset:36864
	ds_write_b128 v179, v[124:127] offset:27648
	ds_write_b128 v188, v[136:139] offset:36864
	ds_write_b128 v179, v[140:143] offset:32256
	ds_write_b128 v189, v[116:119] offset:36864
	s_waitcnt lgkmcnt(0)
	s_barrier
	s_waitcnt vmcnt(0)
	s_add_i32 s88, s88, s66
	s_cmpk_gt_i32 s88, 0xbff
	s_cselect_b64 s[58:59], -1, 0
	s_and_b64 vcc, exec, s[58:59]
	s_cbranch_vccnz .LBB0_1118
	s_add_i32 s44, s82, s33
	s_bfe_u32 s45, s44, 0x20009
	s_and_b32 s95, s44, 0x1c0
	s_and_b32 s46, s44, 63
	s_ashr_i32 s44, s44, 10
	s_and_b32 s71, s44, -2
	s_lshr_b32 vcc_lo, s46, s71
	s_bfm_b32 s44, s71, 0
	s_lshl_b32 s94, vcc_lo, 7
	s_and_b32 s93, s44, s46
	s_addk_i32 s94, 0xff80
	s_mul_i32 s44, s45, 0x2800000
	s_mov_b32 s45, s55
	s_cmp_lg_u32 vcc_lo, 0
	v_lshl_add_u64 v[0:1], v[164:165], 0, s[44:45]
	s_cselect_b64 s[46:47], -1, 0
	s_cmp_eq_u32 vcc_lo, 0
	s_cbranch_scc1 .LBB0_1124
	v_or_b32_e32 v2, s94, v167
	v_lshlrev_b32_e32 v2, s71, v2
	v_add_u32_e32 v2, s93, v2
	v_mad_i64_i32 v[2:3], s[44:45], v2, s79, v[0:1]
	s_lshl_b32 s44, s95, 1
	s_mov_b32 s45, s55
	v_lshl_add_u64 v[2:3], v[2:3], 0, s[44:45]
	global_load_dwordx4 v[80:83], v[2:3], off offset:1024
	global_load_dwordx4 v[84:87], v[2:3], off offset:2048
	v_cndmask_b32_e64 v2, 0, 1, s[46:47]
	v_cmp_ne_u32_e64 s[44:45], 1, v2
	s_andn2_b64 vcc, exec, s[46:47]
	s_cbranch_vccnz .LBB0_1125

.LBB0_1118:
	s_ashr_i32 s71, s70, 31
	s_lshl_b32 s44, s90, 6
	s_lshl_b64 s[46:47], s[70:71], 25
	s_add_u32 s45, s50, s46
	s_addc_u32 s93, s51, s47
	s_lshl_b64 s[46:47], s[56:57], 10
	s_add_u32 s45, s45, s46
	s_addc_u32 s46, s93, s47
	s_lshl_b32 s44, s44, 1
	s_add_u32 s44, s45, s44
	s_addc_u32 s45, s46, 0
	s_cmp_lg_u32 s92, 0
	v_add_u32_e32 v193, v176, v177
	s_cbranch_scc0 .LBB0_1123
	ds_read_b128 v[0:3], v190
	ds_read_b128 v[4:7], v190 offset:32
	s_movk_i32 s46, 0xff7e
	s_waitcnt lgkmcnt(1)
	v_mfma_f32_32x32x16_bf16 v[64:79], v[0:3], v[156:159], 0
	ds_read_b128 v[0:3], v190 offset:64
	ds_read_b128 v[48:51], v190 offset:13856
	ds_read_b128 v[194:197], v190 offset:18464
	s_waitcnt lgkmcnt(3)
	v_mfma_f32_32x32x16_bf16 v[64:79], v[4:7], v[152:155], v[64:79]
	s_waitcnt lgkmcnt(2)
	v_mfma_f32_32x32x16_bf16 v[64:79], v[0:3], v[148:151], v[64:79]
	ds_read_b128 v[0:3], v190 offset:96
	s_waitcnt lgkmcnt(0)
	v_mfma_f32_32x32x16_bf16 v[64:79], v[0:3], v[144:147], v[64:79]
	ds_read_b128 v[0:3], v190 offset:4608
	s_waitcnt lgkmcnt(0)
	v_mfma_f32_32x32x16_bf16 v[32:47], v[0:3], v[156:159], 0
	ds_read_b128 v[0:3], v190 offset:4640
	s_nop 7
	v_mul_f32_e32 v64, 0x3e38aa3b, v64
	v_mul_f32_e32 v65, 0x3e38aa3b, v65
	v_mul_f32_e32 v66, 0x3e38aa3b, v66
	v_mul_f32_e32 v67, 0x3e38aa3b, v67
	v_mul_f32_e32 v68, 0x3e38aa3b, v68
	v_mul_f32_e32 v69, 0x3e38aa3b, v69
	s_waitcnt lgkmcnt(0)
	v_mfma_f32_32x32x16_bf16 v[32:47], v[0:3], v[152:155], v[32:47]
	ds_read_b128 v[0:3], v190 offset:4672
	v_mul_f32_e32 v70, 0x3e38aa3b, v70
	v_mul_f32_e32 v71, 0x3e38aa3b, v71
	v_mul_f32_e32 v72, 0x3e38aa3b, v72
	v_mul_f32_e32 v73, 0x3e38aa3b, v73
	v_mul_f32_e32 v74, 0x3e38aa3b, v74
	v_mul_f32_e32 v75, 0x3e38aa3b, v75
	s_waitcnt lgkmcnt(0)
	v_mfma_f32_32x32x16_bf16 v[32:47], v[0:3], v[148:151], v[32:47]
	ds_read_b128 v[0:3], v190 offset:4704
	v_mul_f32_e32 v76, 0x3e38aa3b, v76
	v_mul_f32_e32 v77, 0x3e38aa3b, v77
	v_mul_f32_e32 v78, 0x3e38aa3b, v78
	v_mul_f32_e32 v79, 0x3e38aa3b, v79
	s_waitcnt lgkmcnt(0)
	v_mfma_f32_32x32x16_bf16 v[32:47], v[0:3], v[144:147], v[32:47]
	ds_read_b128 v[0:3], v190 offset:9216
	s_waitcnt lgkmcnt(0)
	v_mfma_f32_32x32x16_bf16 v[16:31], v[0:3], v[156:159], 0
	ds_read_b128 v[0:3], v190 offset:9248
	s_nop 7
	v_mul_f32_e32 v198, 0x3e38aa3b, v33
	s_waitcnt lgkmcnt(0)
	v_mfma_f32_32x32x16_bf16 v[16:31], v[0:3], v[152:155], v[16:31]
	ds_read_b128 v[0:3], v190 offset:9280
	s_waitcnt lgkmcnt(0)
	v_mfma_f32_32x32x16_bf16 v[16:31], v[0:3], v[148:151], v[16:31]
	ds_read_b128 v[0:3], v190 offset:9312
	s_waitcnt lgkmcnt(0)
	v_mfma_f32_32x32x16_bf16 v[16:31], v[0:3], v[144:147], v[16:31]
	ds_read_b128 v[0:3], v190 offset:13824
	s_waitcnt lgkmcnt(0)
	v_mfma_f32_32x32x16_bf16 v[0:15], v[0:3], v[156:159], 0
	v_mfma_f32_32x32x16_bf16 v[0:15], v[48:51], v[152:155], v[0:15]
	ds_read_b128 v[48:51], v190 offset:13888
	s_waitcnt lgkmcnt(0)
	v_mfma_f32_32x32x16_bf16 v[0:15], v[48:51], v[148:151], v[0:15]
	ds_read_b128 v[48:51], v190 offset:13920
	s_waitcnt lgkmcnt(0)
	v_mfma_f32_32x32x16_bf16 v[0:15], v[48:51], v[144:147], v[0:15]
	ds_read_b128 v[48:51], v190 offset:18432
	s_waitcnt lgkmcnt(0)
	v_mfma_f32_32x32x16_bf16 v[48:63], v[48:51], v[156:159], 0
	v_mfma_f32_32x32x16_bf16 v[48:63], v[194:197], v[152:155], v[48:63]
	ds_read_b128 v[194:197], v190 offset:18496
	s_waitcnt lgkmcnt(0)
	v_mfma_f32_32x32x16_bf16 v[48:63], v[194:197], v[148:151], v[48:63]
	ds_read_b128 v[194:197], v190 offset:18528
	s_waitcnt lgkmcnt(0)
	v_mfma_f32_32x32x16_bf16 v[48:63], v[194:197], v[144:147], v[48:63]
	v_or_b32_e32 v194, s54, v162
	v_add_u32_e32 v195, s91, v175
	v_sub_u32_e32 v196, v194, v195
	v_cmp_gt_i32_e32 vcc, s81, v196
	v_sub_u32_e32 v197, v195, v194
	s_nop 6
	v_mul_f32_e32 v48, 0x3e38aa3b, v48
	v_cndmask_b32_e32 v64, v191, v64, vcc
	v_cmp_lt_i32_e32 vcc, s46, v197
	s_movk_i32 s46, 0x83
	v_mul_f32_e32 v49, 0x3e38aa3b, v49
	v_cndmask_b32_e32 v65, v191, v65, vcc
	v_cmp_gt_i32_e32 vcc, s46, v196
	s_movk_i32 s46, 0x84
	v_max3_f32 v197, v64, s87, v65
	v_cndmask_b32_e32 v66, v191, v66, vcc
	v_cmp_gt_i32_e32 vcc, s46, v196
	s_movk_i32 s46, 0x89
	v_mul_f32_e32 v50, 0x3e38aa3b, v50
	v_cndmask_b32_e32 v67, v191, v67, vcc
	v_cmp_gt_i32_e32 vcc, s46, v196
	s_movk_i32 s46, 0x8a
	v_max3_f32 v197, v197, v66, v67
	v_cndmask_b32_e32 v68, v191, v68, vcc
	v_cmp_gt_i32_e32 vcc, s46, v196
	s_movk_i32 s46, 0x8b
	v_mul_f32_e32 v51, 0x3e38aa3b, v51
	v_cndmask_b32_e32 v69, v191, v69, vcc
	v_cmp_gt_i32_e32 vcc, s46, v196
	s_movk_i32 s46, 0x8c
	v_max3_f32 v197, v197, v68, v69
	v_cndmask_b32_e32 v70, v191, v70, vcc
	v_cmp_gt_i32_e32 vcc, s46, v196
	s_movk_i32 s46, 0x91
	v_mul_f32_e32 v52, 0x3e38aa3b, v52
	v_cndmask_b32_e32 v71, v191, v71, vcc
	v_cmp_gt_i32_e32 vcc, s46, v196
	s_movk_i32 s46, 0x92
	v_max3_f32 v197, v197, v70, v71
	v_cndmask_b32_e32 v72, v191, v72, vcc
	v_cmp_gt_i32_e32 vcc, s46, v196
	s_movk_i32 s46, 0x93
	s_nop 0
	v_cndmask_b32_e32 v73, v191, v73, vcc
	v_cmp_gt_i32_e32 vcc, s46, v196
	s_movk_i32 s46, 0x94
	v_max3_f32 v197, v197, v72, v73
	v_cndmask_b32_e32 v74, v191, v74, vcc
	v_cmp_gt_i32_e32 vcc, s46, v196
	s_movk_i32 s46, 0x99
	s_nop 0
	v_cndmask_b32_e32 v75, v191, v75, vcc
	v_cmp_gt_i32_e32 vcc, s46, v196
	s_movk_i32 s46, 0x9a
	v_max3_f32 v197, v197, v74, v75
	v_cndmask_b32_e32 v76, v191, v76, vcc
	v_cmp_gt_i32_e32 vcc, s46, v196
	s_movk_i32 s46, 0x9b
	s_nop 0
	v_cndmask_b32_e32 v77, v191, v77, vcc
	v_cmp_gt_i32_e32 vcc, s46, v196
	s_movk_i32 s46, 0x9c
	v_max3_f32 v197, v197, v76, v77
	v_cndmask_b32_e32 v78, v191, v78, vcc
	v_cmp_gt_i32_e32 vcc, s46, v196
	s_nop 1
	v_cndmask_b32_e32 v79, v191, v79, vcc
	v_max3_f32 v196, v197, v78, v79
	v_mul_f32_e32 v197, 0x3e38aa3b, v32
	v_max3_f32 v196, v196, v197, v198
	v_mul_f32_e32 v197, 0x3e38aa3b, v34
	v_mul_f32_e32 v198, 0x3e38aa3b, v35
	v_max3_f32 v196, v196, v197, v198
	v_mul_f32_e32 v197, 0x3e38aa3b, v36
	v_mul_f32_e32 v198, 0x3e38aa3b, v37
	v_max3_f32 v196, v196, v197, v198
	v_mul_f32_e32 v197, 0x3e38aa3b, v38
	v_mul_f32_e32 v198, 0x3e38aa3b, v39
	v_max3_f32 v196, v196, v197, v198
	v_mul_f32_e32 v197, 0x3e38aa3b, v40
	v_mul_f32_e32 v198, 0x3e38aa3b, v41
	v_max3_f32 v196, v196, v197, v198
	v_mul_f32_e32 v197, 0x3e38aa3b, v42
	v_mul_f32_e32 v198, 0x3e38aa3b, v43
	v_max3_f32 v196, v196, v197, v198
	v_mul_f32_e32 v197, 0x3e38aa3b, v44
	v_mul_f32_e32 v198, 0x3e38aa3b, v45
	v_max3_f32 v196, v196, v197, v198
	v_mul_f32_e32 v197, 0x3e38aa3b, v46
	v_mul_f32_e32 v198, 0x3e38aa3b, v47
	v_max3_f32 v196, v196, v197, v198
	v_mul_f32_e32 v197, 0x3e38aa3b, v16
	v_mul_f32_e32 v198, 0x3e38aa3b, v17
	v_max3_f32 v196, v196, v197, v198
	v_mul_f32_e32 v197, 0x3e38aa3b, v18
	v_mul_f32_e32 v198, 0x3e38aa3b, v19
	v_max3_f32 v196, v196, v197, v198
	v_mul_f32_e32 v197, 0x3e38aa3b, v20
	v_mul_f32_e32 v198, 0x3e38aa3b, v21
	v_max3_f32 v196, v196, v197, v198
	v_mul_f32_e32 v197, 0x3e38aa3b, v22
	v_mul_f32_e32 v198, 0x3e38aa3b, v23
	v_max3_f32 v196, v196, v197, v198
	v_mul_f32_e32 v197, 0x3e38aa3b, v24
	v_mul_f32_e32 v198, 0x3e38aa3b, v25
	v_max3_f32 v196, v196, v197, v198
	v_mul_f32_e32 v197, 0x3e38aa3b, v26
	v_mul_f32_e32 v198, 0x3e38aa3b, v27
	v_max3_f32 v196, v196, v197, v198
	v_mul_f32_e32 v197, 0x3e38aa3b, v28
	v_mul_f32_e32 v198, 0x3e38aa3b, v29
	v_max3_f32 v196, v196, v197, v198
	v_mul_f32_e32 v197, 0x3e38aa3b, v30
	v_mul_f32_e32 v198, 0x3e38aa3b, v31
	v_max3_f32 v196, v196, v197, v198
	v_mul_f32_e32 v197, 0x3e38aa3b, v0
	v_mul_f32_e32 v198, 0x3e38aa3b, v1
	v_max3_f32 v196, v196, v197, v198
	v_mul_f32_e32 v197, 0x3e38aa3b, v2
	v_mul_f32_e32 v198, 0x3e38aa3b, v3
	v_max3_f32 v196, v196, v197, v198
	v_mul_f32_e32 v197, 0x3e38aa3b, v4
	v_mul_f32_e32 v198, 0x3e38aa3b, v5
	v_max3_f32 v196, v196, v197, v198
	v_mul_f32_e32 v197, 0x3e38aa3b, v6
	v_mul_f32_e32 v198, 0x3e38aa3b, v7
	v_max3_f32 v196, v196, v197, v198
	v_mul_f32_e32 v197, 0x3e38aa3b, v8
	v_mul_f32_e32 v198, 0x3e38aa3b, v9
	v_max3_f32 v196, v196, v197, v198
	v_mul_f32_e32 v197, 0x3e38aa3b, v10
	v_mul_f32_e32 v198, 0x3e38aa3b, v11
	v_max3_f32 v196, v196, v197, v198
	v_mul_f32_e32 v197, 0x3e38aa3b, v12
	v_mul_f32_e32 v198, 0x3e38aa3b, v13
	v_max3_f32 v196, v196, v197, v198
	v_mul_f32_e32 v197, 0x3e38aa3b, v14
	v_mul_f32_e32 v198, 0x3e38aa3b, v15
	v_max3_f32 v196, v196, v197, v198
	v_add_u32_e32 v197, 0x80, v195
	v_cmp_ge_i32_e32 vcc, v194, v197
	s_nop 1
	v_cndmask_b32_e32 v229, v191, v48, vcc
	v_add_u32_e32 v48, 0x81, v195
	v_cmp_ge_i32_e32 vcc, v194, v48
	s_nop 1
	v_cndmask_b32_e32 v49, v191, v49, vcc
	v_max3_f32 v48, v196, v229, v49
	v_add_u32_e32 v196, 0x82, v195
	v_cmp_ge_i32_e32 vcc, v194, v196
	v_add_u32_e32 v196, 0x83, v195
	s_nop 0
	v_cndmask_b32_e32 v50, v191, v50, vcc
	v_cmp_ge_i32_e32 vcc, v194, v196
	s_nop 1
	v_cndmask_b32_e32 v230, v191, v51, vcc
	v_add_u32_e32 v51, 0x88, v195
	v_cmp_ge_i32_e32 vcc, v194, v51
	v_add_u32_e32 v51, 0x89, v195
	v_max3_f32 v48, v48, v50, v230
	v_cndmask_b32_e32 v231, v191, v52, vcc
	v_mul_f32_e32 v52, 0x3e38aa3b, v53
	v_cmp_ge_i32_e32 vcc, v194, v51
	v_add_u32_e32 v51, 0x8a, v195
	s_nop 0
	v_cndmask_b32_e32 v232, v191, v52, vcc
	v_mul_f32_e32 v52, 0x3e38aa3b, v54
	v_cmp_ge_i32_e32 vcc, v194, v51
	v_add_u32_e32 v51, 0x8b, v195
	v_max3_f32 v48, v48, v231, v232
	v_cndmask_b32_e32 v233, v191, v52, vcc
	v_mul_f32_e32 v52, 0x3e38aa3b, v55
	v_cmp_ge_i32_e32 vcc, v194, v51
	v_add_u32_e32 v51, 0x90, v195
	s_nop 0
	v_cndmask_b32_e32 v234, v191, v52, vcc
	v_mul_f32_e32 v52, 0x3e38aa3b, v56
	v_cmp_ge_i32_e32 vcc, v194, v51
	v_add_u32_e32 v51, 0x91, v195
	v_max3_f32 v48, v48, v233, v234
	v_cndmask_b32_e32 v235, v191, v52, vcc
	v_mul_f32_e32 v52, 0x3e38aa3b, v57
	v_cmp_ge_i32_e32 vcc, v194, v51
	v_add_u32_e32 v51, 0x92, v195
	s_nop 0
	v_cndmask_b32_e32 v236, v191, v52, vcc
	v_mul_f32_e32 v52, 0x3e38aa3b, v58
	v_cmp_ge_i32_e32 vcc, v194, v51
	v_add_u32_e32 v51, 0x93, v195
	v_max3_f32 v48, v48, v235, v236
	v_cndmask_b32_e32 v237, v191, v52, vcc
	v_mul_f32_e32 v52, 0x3e38aa3b, v59
	v_cmp_ge_i32_e32 vcc, v194, v51
	v_add_u32_e32 v51, 0x98, v195
	s_nop 0
	v_cndmask_b32_e32 v238, v191, v52, vcc
	v_mul_f32_e32 v52, 0x3e38aa3b, v60
	v_cmp_ge_i32_e32 vcc, v194, v51
	v_add_u32_e32 v51, 0x99, v195
	v_max3_f32 v48, v48, v237, v238
	v_cndmask_b32_e32 v239, v191, v52, vcc
	v_mul_f32_e32 v52, 0x3e38aa3b, v61
	v_cmp_ge_i32_e32 vcc, v194, v51
	v_add_u32_e32 v51, 0x9a, v195
	s_nop 0
	v_cndmask_b32_e32 v240, v191, v52, vcc
	v_mul_f32_e32 v52, 0x3e38aa3b, v62
	v_cmp_ge_i32_e32 vcc, v194, v51
	v_add_u32_e32 v51, 0x9b, v195
	v_max3_f32 v48, v48, v239, v240
	v_cndmask_b32_e32 v241, v191, v52, vcc
	v_mul_f32_e32 v52, 0x3e38aa3b, v63
	v_cmp_ge_i32_e32 vcc, v194, v51
	v_xor_b32_e32 v51, 32, v192
	s_nop 0
	v_cndmask_b32_e32 v242, v191, v52, vcc
	v_and_b32_e32 v52, 64, v192
	v_add_u32_e32 v52, 64, v52
	v_cmp_lt_i32_e32 vcc, v51, v52
	v_max3_f32 v48, v48, v241, v242
	s_nop 0
	v_cndmask_b32_e32 v51, v192, v51, vcc
	v_lshlrev_b32_e32 v243, 2, v51
	ds_bpermute_b32 v51, v243, v48
	s_waitcnt lgkmcnt(0)
	v_max_f32_e32 v51, v51, v51
	v_max_f32_e32 v48, v48, v51
	v_sub_f32_e32 v51, v64, v48
	v_exp_f32_e32 v209, v51
	v_sub_f32_e32 v52, v65, v48
	v_exp_f32_e32 v222, v52
	v_sub_f32_e32 v52, v66, v48
	v_exp_f32_e32 v223, v52
	v_sub_f32_e32 v52, v67, v48
	v_exp_f32_e32 v224, v52
	v_sub_f32_e32 v52, v68, v48
	v_add_f32_e32 v51, 0, v209
	v_exp_f32_e32 v225, v52
	v_sub_f32_e32 v52, v69, v48
	v_add_f32_e32 v51, v222, v51
	v_exp_f32_e32 v226, v52
	v_sub_f32_e32 v52, v70, v48
	v_add_f32_e32 v51, v223, v51
	v_exp_f32_e32 v227, v52
	v_sub_f32_e32 v52, v71, v48
	v_add_f32_e32 v51, v224, v51
	v_exp_f32_e32 v228, v52
	v_sub_f32_e32 v52, v72, v48
	v_add_f32_e32 v51, v225, v51
	v_exp_f32_e32 v210, v52
	v_sub_f32_e32 v52, v73, v48
	v_add_f32_e32 v51, v226, v51
	v_exp_f32_e32 v213, v52
	v_sub_f32_e32 v52, v74, v48
	v_add_f32_e32 v51, v227, v51
	v_exp_f32_e32 v215, v52
	v_sub_f32_e32 v52, v75, v48
	v_add_f32_e32 v51, v228, v51
	v_exp_f32_e32 v217, v52
	v_sub_f32_e32 v52, v76, v48
	v_add_f32_e32 v51, v210, v51
	v_exp_f32_e32 v218, v52
	v_sub_f32_e32 v52, v77, v48
	v_add_f32_e32 v51, v213, v51
	v_exp_f32_e32 v219, v52
	v_sub_f32_e32 v52, v78, v48
	v_add_f32_e32 v51, v215, v51
	v_exp_f32_e32 v220, v52
	v_sub_f32_e32 v52, v79, v48
	v_add_f32_e32 v51, v217, v51
	v_exp_f32_e32 v221, v52
	v_fma_f32 v32, v32, s86, -v48
	v_add_f32_e32 v51, v218, v51
	v_exp_f32_e32 v76, v32
	v_fma_f32 v33, v33, s86, -v48
	v_add_f32_e32 v51, v219, v51
	v_exp_f32_e32 v194, v33
	v_fma_f32 v33, v34, s86, -v48
	v_add_f32_e32 v51, v220, v51
	v_exp_f32_e32 v197, v33
	v_fma_f32 v33, v35, s86, -v48
	v_add_f32_e32 v51, v221, v51
	v_exp_f32_e32 v201, v33
	v_fma_f32 v33, v36, s86, -v48
	v_add_f32_e32 v32, v76, v51
	v_exp_f32_e32 v205, v33
	v_fma_f32 v33, v37, s86, -v48
	v_add_f32_e32 v32, v194, v32
	v_exp_f32_e32 v206, v33
	v_fma_f32 v33, v38, s86, -v48
	v_add_f32_e32 v32, v197, v32
	v_exp_f32_e32 v208, v33
	v_fma_f32 v33, v39, s86, -v48
	v_add_f32_e32 v32, v201, v32
	v_exp_f32_e32 v212, v33
	v_fma_f32 v33, v40, s86, -v48
	v_add_f32_e32 v32, v205, v32
	v_exp_f32_e32 v195, v33
	v_fma_f32 v33, v41, s86, -v48
	v_add_f32_e32 v32, v206, v32
	v_exp_f32_e32 v200, v33
	v_fma_f32 v33, v42, s86, -v48
	v_add_f32_e32 v32, v208, v32
	v_exp_f32_e32 v202, v33
	v_fma_f32 v33, v43, s86, -v48
	v_add_f32_e32 v32, v212, v32
	v_exp_f32_e32 v204, v33
	v_fma_f32 v33, v44, s86, -v48
	v_add_f32_e32 v32, v195, v32
	v_exp_f32_e32 v207, v33
	v_fma_f32 v33, v45, s86, -v48
	v_add_f32_e32 v32, v200, v32
	v_exp_f32_e32 v211, v33
	v_fma_f32 v33, v46, s86, -v48
	v_add_f32_e32 v32, v202, v32
	v_exp_f32_e32 v214, v33
	v_fma_f32 v33, v47, s86, -v48
	v_add_f32_e32 v32, v204, v32
	v_exp_f32_e32 v216, v33
	v_fma_f32 v16, v16, s86, -v48
	v_add_f32_e32 v32, v207, v32
	v_exp_f32_e32 v64, v16
	v_fma_f32 v17, v17, s86, -v48
	v_add_f32_e32 v32, v211, v32
	v_exp_f32_e32 v67, v17
	v_fma_f32 v17, v18, s86, -v48
	v_add_f32_e32 v32, v214, v32
	v_exp_f32_e32 v69, v17
	v_fma_f32 v17, v19, s86, -v48
	v_add_f32_e32 v32, v216, v32
	v_exp_f32_e32 v72, v17
	v_fma_f32 v17, v20, s86, -v48
	v_add_f32_e32 v16, v64, v32
	v_exp_f32_e32 v75, v17
	v_fma_f32 v17, v21, s86, -v48
	v_add_f32_e32 v16, v67, v16
	v_exp_f32_e32 v77, v17
	v_fma_f32 v17, v22, s86, -v48
	v_add_f32_e32 v16, v69, v16
	v_exp_f32_e32 v79, v17
	v_fma_f32 v17, v23, s86, -v48
	v_add_f32_e32 v16, v72, v16
	v_exp_f32_e32 v198, v17
	v_fma_f32 v17, v24, s86, -v48
	v_add_f32_e32 v16, v75, v16
	v_exp_f32_e32 v68, v17
	v_fma_f32 v17, v25, s86, -v48
	v_add_f32_e32 v16, v77, v16
	v_exp_f32_e32 v71, v17
	v_fma_f32 v17, v26, s86, -v48
	v_add_f32_e32 v16, v79, v16
	v_exp_f32_e32 v73, v17
	v_fma_f32 v17, v27, s86, -v48
	v_add_f32_e32 v16, v198, v16
	v_exp_f32_e32 v74, v17
	v_fma_f32 v17, v28, s86, -v48
	v_add_f32_e32 v16, v68, v16
	v_exp_f32_e32 v78, v17
	v_fma_f32 v17, v29, s86, -v48
	v_add_f32_e32 v16, v71, v16
	v_exp_f32_e32 v196, v17
	v_fma_f32 v17, v30, s86, -v48
	v_add_f32_e32 v16, v73, v16
	v_exp_f32_e32 v199, v17
	v_fma_f32 v17, v31, s86, -v48
	v_add_f32_e32 v16, v74, v16
	v_exp_f32_e32 v203, v17
	v_fma_f32 v0, v0, s86, -v48
	v_add_f32_e32 v16, v78, v16
	v_exp_f32_e32 v51, v0
	v_fma_f32 v1, v1, s86, -v48
	v_add_f32_e32 v16, v196, v16
	v_exp_f32_e32 v52, v1
	v_fma_f32 v1, v2, s86, -v48
	v_add_f32_e32 v16, v199, v16
	v_exp_f32_e32 v54, v1
	v_fma_f32 v1, v3, s86, -v48
	v_add_f32_e32 v16, v203, v16
	v_exp_f32_e32 v57, v1
	v_fma_f32 v1, v4, s86, -v48
	v_add_f32_e32 v0, v51, v16
	v_exp_f32_e32 v63, v1
	v_fma_f32 v1, v5, s86, -v48
	v_add_f32_e32 v0, v52, v0
	v_exp_f32_e32 v65, v1
	v_fma_f32 v1, v6, s86, -v48
	v_add_f32_e32 v0, v54, v0
	v_exp_f32_e32 v66, v1
	v_fma_f32 v1, v7, s86, -v48
	v_add_f32_e32 v0, v57, v0
	v_exp_f32_e32 v70, v1
	v_fma_f32 v1, v8, s86, -v48
	v_add_f32_e32 v0, v63, v0
	v_exp_f32_e32 v53, v1
	v_fma_f32 v1, v9, s86, -v48
	v_add_f32_e32 v0, v65, v0
	v_exp_f32_e32 v55, v1
	v_fma_f32 v1, v10, s86, -v48
	v_add_f32_e32 v0, v66, v0
	v_exp_f32_e32 v56, v1
	v_fma_f32 v1, v11, s86, -v48
	v_add_f32_e32 v0, v70, v0
	v_exp_f32_e32 v58, v1
	v_fma_f32 v1, v12, s86, -v48
	v_add_f32_e32 v0, v53, v0
	v_exp_f32_e32 v59, v1
	v_fma_f32 v1, v13, s86, -v48
	v_add_f32_e32 v0, v55, v0
	v_exp_f32_e32 v60, v1
	v_fma_f32 v1, v14, s86, -v48
	v_add_f32_e32 v0, v56, v0
	v_exp_f32_e32 v61, v1
	v_fma_f32 v1, v15, s86, -v48
	v_add_f32_e32 v0, v58, v0
	v_exp_f32_e32 v62, v1
	v_sub_f32_e32 v1, v229, v48
	v_add_f32_e32 v0, v59, v0
	v_exp_f32_e32 v42, v1
	v_sub_f32_e32 v1, v49, v48
	v_add_f32_e32 v0, v60, v0
	v_exp_f32_e32 v43, v1
	v_sub_f32_e32 v1, v50, v48
	v_add_f32_e32 v0, v61, v0
	v_exp_f32_e32 v44, v1
	v_sub_f32_e32 v1, v230, v48
	v_add_f32_e32 v0, v62, v0
	v_exp_f32_e32 v45, v1
	v_sub_f32_e32 v1, v231, v48
	v_add_f32_e32 v0, v42, v0
	v_exp_f32_e32 v46, v1
	v_sub_f32_e32 v1, v232, v48
	v_add_f32_e32 v0, v43, v0
	v_exp_f32_e32 v47, v1
	v_sub_f32_e32 v1, v233, v48
	v_add_f32_e32 v0, v44, v0
	v_exp_f32_e32 v49, v1
	v_sub_f32_e32 v1, v234, v48
	v_add_f32_e32 v0, v45, v0
	v_exp_f32_e32 v50, v1
	v_sub_f32_e32 v1, v235, v48
	v_add_f32_e32 v0, v46, v0
	v_exp_f32_e32 v34, v1
	v_sub_f32_e32 v1, v236, v48
	v_add_f32_e32 v0, v47, v0
	v_exp_f32_e32 v35, v1
	v_sub_f32_e32 v1, v237, v48
	v_add_f32_e32 v0, v49, v0
	v_exp_f32_e32 v36, v1
	v_sub_f32_e32 v1, v238, v48
	v_add_f32_e32 v0, v50, v0
	v_exp_f32_e32 v37, v1
	v_sub_f32_e32 v1, v239, v48
	v_add_f32_e32 v0, v34, v0
	v_exp_f32_e32 v38, v1
	v_sub_f32_e32 v1, v240, v48
	v_add_f32_e32 v0, v35, v0
	v_exp_f32_e32 v39, v1
	v_sub_f32_e32 v1, v241, v48
	v_add_f32_e32 v0, v36, v0
	v_exp_f32_e32 v40, v1
	v_sub_f32_e32 v1, v242, v48
	v_add_f32_e32 v0, v37, v0
	v_exp_f32_e32 v41, v1
	v_add_f32_e32 v0, v38, v0
	v_add_f32_e32 v0, v39, v0
	v_add_f32_e32 v0, v40, v0
	v_add_f32_e32 v32, v41, v0
	v_cvt_pk_bf16_f32 v0, v209, v222
	v_add_u32_e32 v209, v176, v178
	ds_read_b64_tr_b16 v[4:5], v193 offset:36864
	ds_read_b64_tr_b16 v[6:7], v193 offset:37888
	ds_read_b64_tr_b16 v[8:9], v209 offset:36864
	ds_read_b64_tr_b16 v[10:11], v209 offset:37888
	v_cvt_pk_bf16_f32 v1, v223, v224
	v_cvt_pk_bf16_f32 v2, v225, v226
	v_cvt_pk_bf16_f32 v3, v227, v228
	v_cvt_pk_bf16_f32 v224, v218, v219
	v_cvt_pk_bf16_f32 v225, v220, v221
	s_waitcnt lgkmcnt(2)
	v_mfma_f32_32x32x16_bf16 v[16:31], v[4:7], v[0:3], 0
	ds_read_b64_tr_b16 v[218:219], v193 offset:38912
	ds_read_b64_tr_b16 v[220:221], v193 offset:39936
	ds_read_b64_tr_b16 v[226:227], v209 offset:38912
	ds_read_b64_tr_b16 v[228:229], v209 offset:39936
	v_cvt_pk_bf16_f32 v222, v210, v213
	v_cvt_pk_bf16_f32 v223, v215, v217
	v_cvt_pk_bf16_f32 v73, v73, v74
	v_cvt_pk_bf16_f32 v74, v78, v196
	v_cvt_pk_bf16_f32 v42, v42, v43
	v_cvt_pk_bf16_f32 v43, v44, v45
	s_waitcnt lgkmcnt(4)
	v_mfma_f32_32x32x16_bf16 v[0:15], v[8:11], v[0:3], 0
	v_cvt_pk_bf16_f32 v45, v49, v50
	v_cvt_pk_bf16_f32 v44, v46, v47
	ds_bpermute_b32 v33, v243, v32
	v_cvt_pk_bf16_f32 v34, v34, v35
	v_cvt_pk_bf16_f32 v35, v36, v37
	v_cvt_pk_bf16_f32 v36, v38, v39
	v_cvt_pk_bf16_f32 v37, v40, v41
	s_waitcnt lgkmcnt(3)
	v_mfma_f32_32x32x16_bf16 v[16:31], v[218:221], v[222:225], v[16:31]
	v_cvt_pk_bf16_f32 v218, v76, v194
	v_cvt_pk_bf16_f32 v219, v197, v201
	v_cvt_pk_bf16_f32 v220, v205, v206
	v_cvt_pk_bf16_f32 v221, v208, v212
	s_waitcnt lgkmcnt(0)
	v_add_f32_e32 v32, v32, v33
	v_div_scale_f32 v33, s[46:47], v32, v32, 1.0
	v_mfma_f32_32x32x16_bf16 v[0:15], v[226:229], v[222:225], v[0:15]
	ds_read_b64_tr_b16 v[222:223], v193 offset:40960
	ds_read_b64_tr_b16 v[224:225], v193 offset:41984
	ds_read_b64_tr_b16 v[226:227], v209 offset:40960
	ds_read_b64_tr_b16 v[228:229], v209 offset:41984
	s_add_i32 s46, s89, 9
	s_waitcnt lgkmcnt(2)
	v_mfma_f32_32x32x16_bf16 v[16:31], v[222:225], v[218:221], v[16:31]
	s_waitcnt lgkmcnt(0)
	v_mfma_f32_32x32x16_bf16 v[0:15], v[226:229], v[218:221], v[0:15]
	v_cvt_pk_bf16_f32 v219, v202, v204
	v_cvt_pk_bf16_f32 v220, v207, v211
	ds_read_b64_tr_b16 v[204:205], v193 offset:43008
	ds_read_b64_tr_b16 v[206:207], v193 offset:44032
	ds_read_b64_tr_b16 v[210:211], v209 offset:43008
	ds_read_b64_tr_b16 v[212:213], v209 offset:44032
	v_cvt_pk_bf16_f32 v218, v195, v200
	v_cvt_pk_bf16_f32 v221, v214, v216
	s_waitcnt lgkmcnt(2)
	s_nop 0
	v_mfma_f32_32x32x16_bf16 v[16:31], v[204:207], v[218:221], v[16:31]
	v_cvt_pk_bf16_f32 v204, v64, v67
	v_cvt_pk_bf16_f32 v205, v69, v72
	v_cvt_pk_bf16_f32 v206, v75, v77
	v_cvt_pk_bf16_f32 v207, v79, v198
	v_cvt_pk_bf16_f32 v72, v68, v71
	v_cvt_pk_bf16_f32 v75, v199, v203
	s_waitcnt lgkmcnt(0)
	v_mfma_f32_32x32x16_bf16 v[0:15], v[210:213], v[218:221], v[0:15]
	ds_read_b64_tr_b16 v[210:211], v193 offset:45056
	ds_read_b64_tr_b16 v[212:213], v193 offset:46080
	ds_read_b64_tr_b16 v[214:215], v209 offset:45056
	ds_read_b64_tr_b16 v[216:217], v209 offset:46080
	ds_read_b64_tr_b16 v[76:77], v193 offset:47104
	ds_read_b64_tr_b16 v[78:79], v193 offset:48128
	ds_read_b64_tr_b16 v[194:195], v209 offset:47104
	ds_read_b64_tr_b16 v[196:197], v209 offset:48128
	s_waitcnt lgkmcnt(6)
	v_mfma_f32_32x32x16_bf16 v[16:31], v[210:213], v[204:207], v[16:31]
	s_waitcnt lgkmcnt(4)
	v_mfma_f32_32x32x16_bf16 v[0:15], v[214:217], v[204:207], v[0:15]
	s_waitcnt lgkmcnt(2)
	v_mfma_f32_32x32x16_bf16 v[16:31], v[76:79], v[72:75], v[16:31]
	s_waitcnt lgkmcnt(0)
	v_mfma_f32_32x32x16_bf16 v[0:15], v[194:197], v[72:75], v[0:15]
	v_cvt_pk_bf16_f32 v74, v63, v65
	v_cvt_pk_bf16_f32 v75, v66, v70
	ds_read_b64_tr_b16 v[64:65], v193 offset:49152
	ds_read_b64_tr_b16 v[66:67], v193 offset:50176
	ds_read_b64_tr_b16 v[68:69], v209 offset:49152
	ds_read_b64_tr_b16 v[70:71], v209 offset:50176
	v_cvt_pk_bf16_f32 v72, v51, v52
	v_cvt_pk_bf16_f32 v73, v54, v57
	v_cvt_pk_bf16_f32 v52, v53, v55
	v_cvt_pk_bf16_f32 v53, v56, v58
	s_waitcnt lgkmcnt(2)
	v_mfma_f32_32x32x16_bf16 v[16:31], v[64:67], v[72:75], v[16:31]
	v_cvt_pk_bf16_f32 v54, v59, v60
	v_cvt_pk_bf16_f32 v55, v61, v62
	ds_read_b64_tr_b16 v[56:57], v193 offset:51200
	ds_read_b64_tr_b16 v[58:59], v193 offset:52224
	ds_read_b64_tr_b16 v[60:61], v209 offset:51200
	ds_read_b64_tr_b16 v[62:63], v209 offset:52224
	s_waitcnt lgkmcnt(4)
	v_mfma_f32_32x32x16_bf16 v[0:15], v[68:71], v[72:75], v[0:15]
	s_waitcnt lgkmcnt(2)
	v_mfma_f32_32x32x16_bf16 v[16:31], v[56:59], v[52:55], v[16:31]
	s_waitcnt lgkmcnt(0)
	v_mfma_f32_32x32x16_bf16 v[0:15], v[60:63], v[52:55], v[0:15]
	ds_read_b64_tr_b16 v[50:51], v193 offset:53248
	ds_read_b64_tr_b16 v[52:53], v193 offset:54272
	ds_read_b64_tr_b16 v[54:55], v209 offset:53248
	ds_read_b64_tr_b16 v[56:57], v209 offset:54272
	s_waitcnt lgkmcnt(2)
	v_mfma_f32_32x32x16_bf16 v[16:31], v[50:53], v[42:45], v[16:31]
	s_waitcnt lgkmcnt(0)
	v_mfma_f32_32x32x16_bf16 v[0:15], v[54:57], v[42:45], v[0:15]
	ds_read_b64_tr_b16 v[38:39], v193 offset:55296
	ds_read_b64_tr_b16 v[40:41], v193 offset:56320
	ds_read_b64_tr_b16 v[42:43], v209 offset:55296
	ds_read_b64_tr_b16 v[44:45], v209 offset:56320
	s_waitcnt lgkmcnt(2)
	v_mfma_f32_32x32x16_bf16 v[16:31], v[38:41], v[34:37], v[16:31]
	v_lshlrev_b32_e32 v38, 1, v166
	v_mov_b32_e32 v39, v161
	s_waitcnt lgkmcnt(0)
	v_mfma_f32_32x32x16_bf16 v[0:15], v[42:45], v[34:37], v[0:15]
	v_rcp_f32_e32 v34, v33
	s_nop 0
	v_fma_f32 v35, -v33, v34, 1.0
	v_fmac_f32_e32 v34, v35, v34
	v_div_scale_f32 v35, vcc, 1.0, v32, 1.0
	v_mul_f32_e32 v36, v35, v34
	v_fma_f32 v37, -v33, v36, v35
	v_fmac_f32_e32 v36, v37, v34
	v_fma_f32 v33, -v33, v36, v35
	v_div_fmas_f32 v33, v33, v34, v36
	v_div_fixup_f32 v34, v33, v32, 1.0
	v_lshlrev_b64 v[36:37], s46, v[162:163]
	v_lshl_add_u64 v[36:37], v[36:37], 1, s[44:45]
	v_pk_mul_f32 v[16:17], v[16:17], v[34:35] op_sel_hi:[1,0]
	v_pk_mul_f32 v[18:19], v[18:19], v[34:35] op_sel_hi:[1,0]
	v_pk_mul_f32 v[20:21], v[20:21], v[34:35] op_sel_hi:[1,0]
	v_pk_mul_f32 v[22:23], v[22:23], v[34:35] op_sel_hi:[1,0]
	v_pk_mul_f32 v[24:25], v[24:25], v[34:35] op_sel_hi:[1,0]
	v_pk_mul_f32 v[26:27], v[26:27], v[34:35] op_sel_hi:[1,0]
	v_pk_mul_f32 v[28:29], v[28:29], v[34:35] op_sel_hi:[1,0]
	v_pk_mul_f32 v[30:31], v[30:31], v[34:35] op_sel_hi:[1,0]
	v_pk_mul_f32 v[0:1], v[0:1], v[34:35] op_sel_hi:[1,0]
	v_pk_mul_f32 v[2:3], v[2:3], v[34:35] op_sel_hi:[1,0]
	v_pk_mul_f32 v[4:5], v[4:5], v[34:35] op_sel_hi:[1,0]
	v_pk_mul_f32 v[6:7], v[6:7], v[34:35] op_sel_hi:[1,0]
	v_pk_mul_f32 v[8:9], v[8:9], v[34:35] op_sel_hi:[1,0]
	v_pk_mul_f32 v[10:11], v[10:11], v[34:35] op_sel_hi:[1,0]
	v_pk_mul_f32 v[12:13], v[12:13], v[34:35] op_sel_hi:[1,0]
	v_pk_mul_f32 v[14:15], v[14:15], v[34:35] op_sel_hi:[1,0]
	v_lshl_add_u64 v[36:37], v[36:37], 0, v[38:39]
	v_lshl_add_u64 v[36:37], v[36:37], 0, v[38:39]
	v_cvt_pk_bf16_f32 v16, v16, v17
	v_cvt_pk_bf16_f32 v17, v18, v19
	v_cvt_pk_bf16_f32 v18, v20, v21
	v_cvt_pk_bf16_f32 v19, v22, v23
	v_cvt_pk_bf16_f32 v20, v24, v25
	v_cvt_pk_bf16_f32 v21, v26, v27
	v_cvt_pk_bf16_f32 v22, v28, v29
	v_cvt_pk_bf16_f32 v23, v30, v31
	v_cvt_pk_bf16_f32 v0, v0, v1
	v_cvt_pk_bf16_f32 v1, v2, v3
	v_cvt_pk_bf16_f32 v2, v4, v5
	v_cvt_pk_bf16_f32 v3, v6, v7
	v_cvt_pk_bf16_f32 v4, v8, v9
	v_cvt_pk_bf16_f32 v5, v10, v11
	v_cvt_pk_bf16_f32 v6, v12, v13
	v_cvt_pk_bf16_f32 v7, v14, v15
	s_nop 1
	v_permlane32_swap_b32 v16, v18
	v_permlane32_swap_b32 v17, v19
	v_permlane32_swap_b32 v20, v22
	v_permlane32_swap_b32 v21, v23
	v_permlane32_swap_b32 v0, v2
	v_permlane32_swap_b32 v1, v3
	v_permlane32_swap_b32 v4, v6
	v_permlane32_swap_b32 v5, v7
	global_store_dwordx4 v[36:37], v[16:19], off
	global_store_dwordx4 v[36:37], v[20:23], off offset:32
	global_store_dwordx4 v[36:37], v[0:3], off offset:64
	global_store_dwordx4 v[36:37], v[4:7], off offset:96
	s_nop 1
	s_and_b64 s[46:47], s[0:1], exec
	s_cbranch_execnz .LBB0_1121
.LBB0_1120:
	ds_read_b128 v[0:3], v190 offset:4608
	ds_read_b128 v[4:7], v190 offset:4640
	v_readlane_b32 s92, v247, 34
	v_readlane_b32 s93, v247, 35
	v_add_u32_e32 v209, v176, v178
	s_waitcnt lgkmcnt(1)
	v_mfma_f32_32x32x16_bf16 v[48:63], v[0:3], v[156:159], 0
	ds_read_b128 v[0:3], v190 offset:4672
	ds_read_b128 v[64:67], v190 offset:18464
	s_add_i32 s54, s89, 9
	s_waitcnt lgkmcnt(2)
	v_mfma_f32_32x32x16_bf16 v[48:63], v[4:7], v[152:155], v[48:63]
	s_waitcnt lgkmcnt(1)
	v_mfma_f32_32x32x16_bf16 v[48:63], v[0:3], v[148:151], v[48:63]
	ds_read_b128 v[0:3], v190 offset:4704
	s_waitcnt lgkmcnt(0)
	v_mfma_f32_32x32x16_bf16 v[48:63], v[0:3], v[144:147], v[48:63]
	ds_read_b128 v[0:3], v190 offset:9216
	s_waitcnt lgkmcnt(0)
	v_mfma_f32_32x32x16_bf16 v[32:47], v[0:3], v[156:159], 0
	ds_read_b128 v[0:3], v190 offset:9248
	s_nop 7
	v_mul_f32_e32 v48, 0x3e38aa3b, v48
	v_cndmask_b32_e64 v78, v191, v48, s[92:93]
	v_readlane_b32 s92, v247, 36
	v_mul_f32_e32 v48, 0x3e38aa3b, v49
	v_readlane_b32 s93, v247, 37
	v_mul_f32_e32 v49, 0x3e38aa3b, v50
	s_waitcnt lgkmcnt(0)
	v_mfma_f32_32x32x16_bf16 v[32:47], v[0:3], v[152:155], v[32:47]
	ds_read_b128 v[0:3], v190 offset:9280
	v_cndmask_b32_e64 v77, v191, v48, s[92:93]
	v_readlane_b32 s92, v247, 38
	v_readlane_b32 s93, v247, 39
	v_max3_f32 v48, v78, s87, v77
	s_nop 0
	v_cndmask_b32_e64 v76, v191, v49, s[92:93]
	s_waitcnt lgkmcnt(0)
	v_mfma_f32_32x32x16_bf16 v[32:47], v[0:3], v[148:151], v[32:47]
	ds_read_b128 v[0:3], v190 offset:9312
	v_readlane_b32 s92, v247, 40
	v_mul_f32_e32 v49, 0x3e38aa3b, v51
	v_readlane_b32 s93, v247, 41
	s_nop 1
	v_cndmask_b32_e64 v75, v191, v49, s[92:93]
	s_waitcnt lgkmcnt(0)
	v_mfma_f32_32x32x16_bf16 v[32:47], v[0:3], v[144:147], v[32:47]
	ds_read_b128 v[0:3], v190 offset:13824
	v_readlane_b32 s92, v247, 42
	v_mul_f32_e32 v49, 0x3e38aa3b, v52
	v_readlane_b32 s93, v247, 43
	v_max3_f32 v48, v48, v76, v75
	s_nop 6
	v_mul_f32_e32 v32, 0x3e38aa3b, v32
	s_waitcnt lgkmcnt(0)
	v_mfma_f32_32x32x16_bf16 v[16:31], v[0:3], v[156:159], 0
	ds_read_b128 v[0:3], v190 offset:13856
	v_cndmask_b32_e64 v74, v191, v49, s[92:93]
	v_readlane_b32 s92, v247, 44
	v_mul_f32_e32 v49, 0x3e38aa3b, v53
	v_readlane_b32 s93, v247, 45
	s_waitcnt lgkmcnt(0)
	v_mfma_f32_32x32x16_bf16 v[16:31], v[0:3], v[152:155], v[16:31]
	ds_read_b128 v[0:3], v190 offset:13888
	v_cndmask_b32_e64 v73, v191, v49, s[92:93]
	v_readlane_b32 s92, v247, 46
	v_mul_f32_e32 v49, 0x3e38aa3b, v54
	v_readlane_b32 s93, v247, 47
	v_max3_f32 v48, v48, v74, v73
	s_waitcnt lgkmcnt(0)
	v_mfma_f32_32x32x16_bf16 v[16:31], v[0:3], v[148:151], v[16:31]
	ds_read_b128 v[0:3], v190 offset:13920
	v_cndmask_b32_e64 v72, v191, v49, s[92:93]
	v_readlane_b32 s92, v247, 48
	v_mul_f32_e32 v49, 0x3e38aa3b, v55
	v_readlane_b32 s93, v247, 49
	s_waitcnt lgkmcnt(0)
	v_mfma_f32_32x32x16_bf16 v[16:31], v[0:3], v[144:147], v[16:31]
	ds_read_b128 v[0:3], v190 offset:18432
	v_cndmask_b32_e64 v71, v191, v49, s[92:93]
	v_readlane_b32 s92, v247, 50
	v_mul_f32_e32 v49, 0x3e38aa3b, v56
	v_readlane_b32 s93, v247, 51
	v_max3_f32 v48, v48, v72, v71
	s_nop 5
	v_mul_f32_e32 v16, 0x3e38aa3b, v16
	s_waitcnt lgkmcnt(0)
	v_mfma_f32_32x32x16_bf16 v[0:15], v[0:3], v[156:159], 0
	v_cndmask_b32_e64 v70, v191, v49, s[92:93]
	v_readlane_b32 s92, v247, 52
	v_mul_f32_e32 v49, 0x3e38aa3b, v57
	v_readlane_b32 s93, v247, 53
	s_nop 1
	v_cndmask_b32_e64 v69, v191, v49, s[92:93]
	v_mfma_f32_32x32x16_bf16 v[0:15], v[64:67], v[152:155], v[0:15]
	ds_read_b128 v[64:67], v190 offset:18496
	v_readlane_b32 s92, v247, 54
	v_mul_f32_e32 v49, 0x3e38aa3b, v58
	v_readlane_b32 s93, v247, 55
	v_max3_f32 v48, v48, v70, v69
	s_nop 0
	v_cndmask_b32_e64 v68, v191, v49, s[92:93]
	s_waitcnt lgkmcnt(0)
	v_mfma_f32_32x32x16_bf16 v[0:15], v[64:67], v[148:151], v[0:15]
	ds_read_b128 v[64:67], v190 offset:18528
	v_readlane_b32 s92, v247, 56
	v_mul_f32_e32 v49, 0x3e38aa3b, v59
	v_readlane_b32 s93, v247, 57
	s_waitcnt lgkmcnt(0)
	v_mfma_f32_32x32x16_bf16 v[0:15], v[64:67], v[144:147], v[0:15]
	v_cndmask_b32_e64 v67, v191, v49, s[92:93]
	v_readlane_b32 s92, v247, 58
	v_mul_f32_e32 v49, 0x3e38aa3b, v60
	v_readlane_b32 s93, v247, 59
	v_max3_f32 v48, v48, v68, v67
	s_nop 6
	v_mul_f32_e32 v0, 0x3e38aa3b, v0
	v_cndmask_b32_e64 v66, v191, v49, s[92:93]
	v_readlane_b32 s92, v247, 60
	v_mul_f32_e32 v49, 0x3e38aa3b, v61
	v_readlane_b32 s93, v247, 61
	s_nop 1
	v_cndmask_b32_e64 v65, v191, v49, s[92:93]
	v_readlane_b32 s92, v247, 62
	v_mul_f32_e32 v49, 0x3e38aa3b, v62
	v_readlane_b32 s93, v247, 63
	v_max3_f32 v48, v48, v66, v65
	s_nop 0
	v_cndmask_b32_e64 v64, v191, v49, s[92:93]
	v_readlane_b32 s92, v246, 0
	v_mul_f32_e32 v49, 0x3e38aa3b, v63
	v_readlane_b32 s93, v246, 1
	s_nop 1
	v_cndmask_b32_e64 v62, v191, v49, s[92:93]
	v_readlane_b32 s92, v246, 2
	v_readlane_b32 s93, v246, 3
	v_max3_f32 v48, v48, v64, v62
	s_nop 0
	v_cndmask_b32_e64 v61, v191, v32, s[92:93]
	v_readlane_b32 s92, v246, 4
	v_mul_f32_e32 v32, 0x3e38aa3b, v33
	v_readlane_b32 s93, v246, 5
	v_mul_f32_e32 v33, 0x3e38aa3b, v34
	s_nop 0
	v_cndmask_b32_e64 v60, v191, v32, s[92:93]
	v_readlane_b32 s92, v246, 6
	v_readlane_b32 s93, v246, 7
	v_max3_f32 v32, v48, v61, v60
	s_nop 0
	v_cndmask_b32_e64 v59, v191, v33, s[92:93]
	v_readlane_b32 s92, v246, 8
	v_mul_f32_e32 v33, 0x3e38aa3b, v35
	v_readlane_b32 s93, v246, 9
	s_nop 1
	v_cndmask_b32_e64 v58, v191, v33, s[92:93]
	v_readlane_b32 s92, v246, 10
	v_mul_f32_e32 v33, 0x3e38aa3b, v36
	v_readlane_b32 s93, v246, 11
	v_max3_f32 v32, v32, v59, v58
	s_nop 0
	v_cndmask_b32_e64 v57, v191, v33, s[92:93]
	v_readlane_b32 s92, v246, 12
	v_mul_f32_e32 v33, 0x3e38aa3b, v37
	v_readlane_b32 s93, v246, 13
	s_nop 1
	v_cndmask_b32_e64 v56, v191, v33, s[92:93]
	v_readlane_b32 s92, v246, 14
	v_mul_f32_e32 v33, 0x3e38aa3b, v38
	v_readlane_b32 s93, v246, 15
	v_max3_f32 v32, v32, v57, v56
	s_nop 0
	v_cndmask_b32_e64 v55, v191, v33, s[92:93]
	v_readlane_b32 s92, v246, 16
	v_mul_f32_e32 v33, 0x3e38aa3b, v39
	v_readlane_b32 s93, v246, 17
	s_nop 1
	v_cndmask_b32_e64 v54, v191, v33, s[92:93]
	v_readlane_b32 s92, v246, 18
	v_mul_f32_e32 v33, 0x3e38aa3b, v40
	v_readlane_b32 s93, v246, 19
	v_max3_f32 v32, v32, v55, v54
	s_nop 0
	v_cndmask_b32_e64 v53, v191, v33, s[92:93]
	v_readlane_b32 s92, v246, 20
	v_mul_f32_e32 v33, 0x3e38aa3b, v41
	v_readlane_b32 s93, v246, 21
	s_nop 1
	v_cndmask_b32_e64 v52, v191, v33, s[92:93]
	v_readlane_b32 s92, v246, 22
	v_mul_f32_e32 v33, 0x3e38aa3b, v42
	v_readlane_b32 s93, v246, 23
	v_max3_f32 v32, v32, v53, v52
	s_nop 0
	v_cndmask_b32_e64 v51, v191, v33, s[92:93]
	v_readlane_b32 s92, v246, 24
	v_mul_f32_e32 v33, 0x3e38aa3b, v43
	v_readlane_b32 s93, v246, 25
	s_nop 1
	v_cndmask_b32_e64 v50, v191, v33, s[92:93]
	v_readlane_b32 s92, v246, 26
	v_mul_f32_e32 v33, 0x3e38aa3b, v44
	v_readlane_b32 s93, v246, 27
	v_max3_f32 v32, v32, v51, v50
	s_nop 0
	v_cndmask_b32_e64 v49, v191, v33, s[92:93]
	v_readlane_b32 s92, v246, 28
	v_mul_f32_e32 v33, 0x3e38aa3b, v45
	v_readlane_b32 s93, v246, 29
	s_nop 1
	v_cndmask_b32_e64 v44, v191, v33, s[92:93]
	v_readlane_b32 s92, v246, 30
	v_mul_f32_e32 v33, 0x3e38aa3b, v46
	v_readlane_b32 s93, v246, 31
	v_max3_f32 v32, v32, v49, v44
	s_nop 0
	v_cndmask_b32_e64 v43, v191, v33, s[92:93]
	v_readlane_b32 s92, v246, 32
	v_mul_f32_e32 v33, 0x3e38aa3b, v47
	v_readlane_b32 s93, v246, 33
	s_nop 1
	v_cndmask_b32_e64 v42, v191, v33, s[92:93]
	v_readlane_b32 s92, v246, 34
	v_readlane_b32 s93, v246, 35
	v_max3_f32 v32, v32, v43, v42
	s_nop 0
	v_cndmask_b32_e64 v41, v191, v16, s[92:93]
	v_readlane_b32 s92, v246, 36
	v_mul_f32_e32 v16, 0x3e38aa3b, v17
	v_readlane_b32 s93, v246, 37
	v_mul_f32_e32 v17, 0x3e38aa3b, v18
	s_nop 0
	v_cndmask_b32_e64 v40, v191, v16, s[92:93]
	v_readlane_b32 s92, v246, 38
	v_readlane_b32 s93, v246, 39
	v_max3_f32 v16, v32, v41, v40
	s_nop 0
	v_cndmask_b32_e64 v39, v191, v17, s[92:93]
	v_readlane_b32 s92, v246, 40
	v_mul_f32_e32 v17, 0x3e38aa3b, v19
	v_readlane_b32 s93, v246, 41
	s_nop 1
	v_cndmask_b32_e64 v38, v191, v17, s[92:93]
	v_readlane_b32 s92, v246, 42
	v_mul_f32_e32 v17, 0x3e38aa3b, v20
	v_readlane_b32 s93, v246, 43
	v_max3_f32 v16, v16, v39, v38
	s_nop 0
	v_cndmask_b32_e64 v37, v191, v17, s[92:93]
	v_readlane_b32 s92, v246, 44
	v_mul_f32_e32 v17, 0x3e38aa3b, v21
	v_readlane_b32 s93, v246, 45
	s_nop 1
	v_cndmask_b32_e64 v36, v191, v17, s[92:93]
	v_readlane_b32 s92, v246, 46
	v_mul_f32_e32 v17, 0x3e38aa3b, v22
	v_readlane_b32 s93, v246, 47
	v_max3_f32 v16, v16, v37, v36
	s_nop 0
	v_cndmask_b32_e64 v35, v191, v17, s[92:93]
	v_readlane_b32 s92, v246, 48
	v_mul_f32_e32 v17, 0x3e38aa3b, v23
	v_readlane_b32 s93, v246, 49
	v_cndmask_b32_e64 v23, v191, v0, s[10:11]
	v_mul_f32_e32 v0, 0x3e38aa3b, v1
	v_cndmask_b32_e64 v34, v191, v17, s[92:93]
	v_readlane_b32 s92, v246, 50
	v_mul_f32_e32 v17, 0x3e38aa3b, v24
	v_readlane_b32 s93, v246, 51
	v_max3_f32 v16, v16, v35, v34
	v_mul_f32_e32 v1, 0x3e38aa3b, v2
	v_cndmask_b32_e64 v33, v191, v17, s[92:93]
	v_readlane_b32 s92, v246, 52
	v_mul_f32_e32 v17, 0x3e38aa3b, v25
	v_readlane_b32 s93, v246, 53
	v_cndmask_b32_e64 v21, v191, v1, s[14:15]
	v_mul_f32_e32 v1, 0x3e38aa3b, v3
	v_cndmask_b32_e64 v32, v191, v17, s[92:93]
	v_readlane_b32 s92, v246, 54
	v_mul_f32_e32 v17, 0x3e38aa3b, v26
	v_readlane_b32 s93, v246, 55
	v_max3_f32 v16, v16, v33, v32
	v_cndmask_b32_e64 v18, v191, v1, s[16:17]
	v_cndmask_b32_e64 v24, v191, v17, s[92:93]
	v_readlane_b32 s92, v246, 56
	v_mul_f32_e32 v17, 0x3e38aa3b, v27
	v_readlane_b32 s93, v246, 57
	v_mul_f32_e32 v1, 0x3e38aa3b, v4
	v_cndmask_b32_e64 v20, v191, v0, s[12:13]
	v_cndmask_b32_e64 v27, v191, v17, s[92:93]
	v_mul_f32_e32 v17, 0x3e38aa3b, v28
	v_cndmask_b32_e64 v28, v191, v17, s[96:97]
	v_mul_f32_e32 v17, 0x3e38aa3b, v29
	v_cndmask_b32_e64 v25, v191, v17, s[4:5]
	v_mul_f32_e32 v17, 0x3e38aa3b, v30
	v_max3_f32 v16, v16, v24, v27
	v_cndmask_b32_e64 v26, v191, v17, s[6:7]
	v_mul_f32_e32 v17, 0x3e38aa3b, v31
	v_max3_f32 v16, v16, v28, v25
	v_cndmask_b32_e64 v22, v191, v17, s[8:9]
	v_max3_f32 v16, v16, v26, v22
	v_cndmask_b32_e64 v19, v191, v1, s[18:19]
	v_mul_f32_e32 v1, 0x3e38aa3b, v5
	v_max3_f32 v0, v16, v23, v20
	v_cndmask_b32_e64 v16, v191, v1, s[20:21]
	v_mul_f32_e32 v1, 0x3e38aa3b, v6
	v_cndmask_b32_e64 v17, v191, v1, s[22:23]
	v_mul_f32_e32 v1, 0x3e38aa3b, v7
	v_cndmask_b32_e64 v7, v191, v1, s[24:25]
	v_mul_f32_e32 v1, 0x3e38aa3b, v8
	v_cndmask_b32_e64 v8, v191, v1, s[26:27]
	v_mul_f32_e32 v1, 0x3e38aa3b, v9
	v_max3_f32 v0, v0, v21, v18
	v_cndmask_b32_e64 v5, v191, v1, s[28:29]
	v_mul_f32_e32 v1, 0x3e38aa3b, v10
	v_max3_f32 v0, v0, v19, v16
	v_cndmask_b32_e64 v6, v191, v1, s[30:31]
	v_mul_f32_e32 v1, 0x3e38aa3b, v11
	v_max3_f32 v0, v0, v17, v7
	v_cndmask_b32_e64 v3, v191, v1, s[34:35]
	v_mul_f32_e32 v1, 0x3e38aa3b, v12
	v_max3_f32 v0, v0, v8, v5
	v_cndmask_b32_e64 v4, v191, v1, s[36:37]
	v_mul_f32_e32 v1, 0x3e38aa3b, v13
	v_max3_f32 v0, v0, v6, v3
	v_cndmask_b32_e64 v1, v191, v1, s[38:39]
	v_and_b32_e32 v11, 64, v192
	v_max3_f32 v9, v0, v4, v1
	v_mul_f32_e32 v0, 0x3e38aa3b, v14
	v_xor_b32_e32 v10, 32, v192
	v_add_u32_e32 v11, 64, v11
	v_cndmask_b32_e64 v2, v191, v0, s[40:41]
	v_mul_f32_e32 v0, 0x3e38aa3b, v15
	v_cmp_lt_i32_e32 vcc, v10, v11
	v_cndmask_b32_e64 v0, v191, v0, s[42:43]
	v_max3_f32 v9, v9, v2, v0
	v_cndmask_b32_e32 v10, v192, v10, vcc
	v_lshlrev_b32_e32 v10, 2, v10
	ds_bpermute_b32 v11, v10, v9
	s_waitcnt lgkmcnt(0)
	v_max_f32_e32 v11, v11, v11
	v_max_f32_e32 v48, v9, v11
	v_sub_f32_e32 v9, 0xff800000, v48
	v_exp_f32_e32 v9, v9
	v_sub_f32_e32 v12, v78, v48
	v_exp_f32_e32 v45, v12
	v_sub_f32_e32 v12, v77, v48
	v_add_f32_e32 v11, 0, v9
	v_add_f32_e32 v11, v9, v11
	v_add_f32_e32 v11, v9, v11
	v_add_f32_e32 v11, v9, v11
	v_add_f32_e32 v11, v9, v11
	v_add_f32_e32 v11, v9, v11
	v_add_f32_e32 v11, v9, v11
	v_add_f32_e32 v11, v9, v11
	v_add_f32_e32 v11, v9, v11
	v_add_f32_e32 v11, v9, v11
	v_add_f32_e32 v11, v9, v11
	v_add_f32_e32 v11, v9, v11
	v_add_f32_e32 v11, v9, v11
	v_add_f32_e32 v11, v9, v11
	v_exp_f32_e32 v46, v12
	v_sub_f32_e32 v12, v76, v48
	v_add_f32_e32 v11, v9, v11
	v_exp_f32_e32 v47, v12
	v_sub_f32_e32 v12, v75, v48
	v_add_f32_e32 v11, v9, v11
	v_exp_f32_e32 v63, v12
	v_sub_f32_e32 v12, v74, v48
	v_add_f32_e32 v11, v45, v11
	v_exp_f32_e32 v74, v12
	v_sub_f32_e32 v12, v73, v48
	v_add_f32_e32 v11, v46, v11
	v_exp_f32_e32 v73, v12
	v_sub_f32_e32 v12, v72, v48
	v_add_f32_e32 v11, v47, v11
	v_exp_f32_e32 v72, v12
	v_sub_f32_e32 v12, v71, v48
	v_add_f32_e32 v11, v63, v11
	v_exp_f32_e32 v71, v12
	v_sub_f32_e32 v12, v70, v48
	v_add_f32_e32 v11, v74, v11
	v_exp_f32_e32 v70, v12
	v_sub_f32_e32 v12, v69, v48
	v_add_f32_e32 v11, v73, v11
	v_exp_f32_e32 v69, v12
	v_sub_f32_e32 v12, v68, v48
	v_add_f32_e32 v11, v72, v11
	v_exp_f32_e32 v68, v12
	v_sub_f32_e32 v12, v67, v48
	v_add_f32_e32 v11, v71, v11
	v_exp_f32_e32 v67, v12
	v_sub_f32_e32 v12, v66, v48
	v_add_f32_e32 v11, v70, v11
	v_exp_f32_e32 v66, v12
	v_sub_f32_e32 v12, v65, v48
	v_add_f32_e32 v11, v69, v11
	v_exp_f32_e32 v65, v12
	v_sub_f32_e32 v12, v64, v48
	v_add_f32_e32 v11, v68, v11
	v_exp_f32_e32 v64, v12
	v_sub_f32_e32 v12, v62, v48
	v_add_f32_e32 v11, v67, v11
	v_exp_f32_e32 v62, v12
	v_sub_f32_e32 v12, v61, v48
	v_add_f32_e32 v11, v66, v11
	v_exp_f32_e32 v61, v12
	v_sub_f32_e32 v12, v60, v48
	v_add_f32_e32 v11, v65, v11
	v_exp_f32_e32 v60, v12
	v_sub_f32_e32 v12, v59, v48
	v_add_f32_e32 v11, v64, v11
	v_exp_f32_e32 v59, v12
	v_sub_f32_e32 v12, v58, v48
	v_add_f32_e32 v11, v62, v11
	v_exp_f32_e32 v58, v12
	v_sub_f32_e32 v12, v57, v48
	v_add_f32_e32 v11, v61, v11
	v_exp_f32_e32 v57, v12
	v_sub_f32_e32 v12, v56, v48
	v_add_f32_e32 v11, v60, v11
	v_exp_f32_e32 v56, v12
	v_sub_f32_e32 v12, v55, v48
	v_add_f32_e32 v11, v59, v11
	v_exp_f32_e32 v55, v12
	v_sub_f32_e32 v12, v54, v48
	v_add_f32_e32 v11, v58, v11
	v_exp_f32_e32 v54, v12
	v_sub_f32_e32 v12, v53, v48
	v_add_f32_e32 v11, v57, v11
	v_exp_f32_e32 v53, v12
	v_sub_f32_e32 v12, v52, v48
	v_add_f32_e32 v11, v56, v11
	v_exp_f32_e32 v52, v12
	v_sub_f32_e32 v12, v51, v48
	v_add_f32_e32 v11, v55, v11
	v_exp_f32_e32 v51, v12
	v_sub_f32_e32 v12, v50, v48
	v_add_f32_e32 v11, v54, v11
	v_exp_f32_e32 v50, v12
	v_sub_f32_e32 v12, v49, v48
	v_add_f32_e32 v11, v53, v11
	v_exp_f32_e32 v77, v12
	v_sub_f32_e32 v12, v44, v48
	v_add_f32_e32 v11, v52, v11
	v_exp_f32_e32 v148, v12
	v_sub_f32_e32 v12, v43, v48
	v_add_f32_e32 v11, v51, v11
	v_exp_f32_e32 v150, v12
	v_sub_f32_e32 v12, v42, v48
	v_add_f32_e32 v11, v50, v11
	v_exp_f32_e32 v154, v12
	v_sub_f32_e32 v12, v41, v48
	v_add_f32_e32 v11, v77, v11
	v_exp_f32_e32 v41, v12
	v_sub_f32_e32 v12, v40, v48
	v_add_f32_e32 v11, v148, v11
	v_exp_f32_e32 v40, v12
	v_sub_f32_e32 v12, v39, v48
	v_add_f32_e32 v11, v150, v11
	v_exp_f32_e32 v39, v12
	v_sub_f32_e32 v12, v38, v48
	v_add_f32_e32 v11, v154, v11
	v_exp_f32_e32 v78, v12
	v_sub_f32_e32 v12, v37, v48
	v_add_f32_e32 v11, v41, v11
	v_exp_f32_e32 v149, v12
	v_sub_f32_e32 v12, v36, v48
	v_add_f32_e32 v11, v40, v11
	v_exp_f32_e32 v151, v12
	v_sub_f32_e32 v12, v35, v48
	v_add_f32_e32 v11, v39, v11
	v_exp_f32_e32 v153, v12
	v_sub_f32_e32 v12, v34, v48
	v_add_f32_e32 v11, v78, v11
	v_exp_f32_e32 v157, v12
	v_sub_f32_e32 v12, v33, v48
	v_add_f32_e32 v11, v149, v11
	v_exp_f32_e32 v152, v12
	v_sub_f32_e32 v12, v32, v48
	v_add_f32_e32 v11, v151, v11
	v_exp_f32_e32 v155, v12
	v_sub_f32_e32 v12, v24, v48
	v_add_f32_e32 v11, v153, v11
	v_exp_f32_e32 v156, v12
	v_sub_f32_e32 v12, v27, v48
	v_add_f32_e32 v11, v157, v11
	v_exp_f32_e32 v158, v12
	v_sub_f32_e32 v12, v28, v48
	v_add_f32_e32 v11, v152, v11
	v_exp_f32_e32 v159, v12
	v_sub_f32_e32 v12, v25, v48
	v_add_f32_e32 v11, v155, v11
	v_exp_f32_e32 v194, v12
	v_sub_f32_e32 v12, v26, v48
	v_add_f32_e32 v11, v156, v11
	v_exp_f32_e32 v195, v12
	v_sub_f32_e32 v12, v22, v48
	v_add_f32_e32 v11, v158, v11
	v_exp_f32_e32 v208, v12
	v_sub_f32_e32 v12, v23, v48
	v_add_f32_e32 v11, v159, v11
	v_exp_f32_e32 v35, v12
	v_sub_f32_e32 v12, v20, v48
	v_add_f32_e32 v11, v194, v11
	v_exp_f32_e32 v37, v12
	v_sub_f32_e32 v12, v21, v48
	v_add_f32_e32 v11, v195, v11
	v_exp_f32_e32 v42, v12
	v_sub_f32_e32 v12, v18, v48
	v_add_f32_e32 v11, v208, v11
	v_exp_f32_e32 v44, v12
	v_sub_f32_e32 v12, v19, v48
	v_add_f32_e32 v11, v35, v11
	v_exp_f32_e32 v75, v12
	v_sub_f32_e32 v12, v16, v48
	v_add_f32_e32 v11, v37, v11
	v_exp_f32_e32 v79, v12
	v_sub_f32_e32 v12, v17, v48
	v_add_f32_e32 v11, v42, v11
	v_exp_f32_e32 v145, v12
	v_sub_f32_e32 v7, v7, v48
	v_add_f32_e32 v11, v44, v11
	v_exp_f32_e32 v147, v7
	v_sub_f32_e32 v8, v8, v48
	v_add_f32_e32 v11, v75, v11
	v_exp_f32_e32 v34, v8
	v_sub_f32_e32 v5, v5, v48
	v_add_f32_e32 v11, v79, v11
	v_exp_f32_e32 v36, v5
	v_sub_f32_e32 v6, v6, v48
	v_add_f32_e32 v11, v145, v11
	v_exp_f32_e32 v38, v6
	v_sub_f32_e32 v3, v3, v48
	v_add_f32_e32 v7, v147, v11
	v_exp_f32_e32 v43, v3
	v_sub_f32_e32 v4, v4, v48
	v_add_f32_e32 v7, v34, v7
	v_exp_f32_e32 v49, v4
	v_sub_f32_e32 v1, v1, v48
	v_add_f32_e32 v5, v36, v7
	v_exp_f32_e32 v76, v1
	v_sub_f32_e32 v2, v2, v48
	v_add_f32_e32 v5, v38, v5
	v_exp_f32_e32 v144, v2
	v_sub_f32_e32 v0, v0, v48
	v_add_f32_e32 v3, v43, v5
	v_exp_f32_e32 v146, v0
	v_add_f32_e32 v3, v49, v3
	v_add_f32_e32 v1, v76, v3
	v_add_f32_e32 v1, v144, v1
	v_add_f32_e32 v32, v146, v1
	ds_read_b64_tr_b16 v[0:1], v193 offset:36864
	ds_read_b64_tr_b16 v[2:3], v193 offset:37888
	ds_read_b64_tr_b16 v[4:5], v209 offset:36864
	ds_read_b64_tr_b16 v[6:7], v209 offset:37888
	v_cvt_pk_bf16_f32 v196, v9, v9
	v_mov_b32_e32 v197, v196
	v_mov_b32_e32 v198, v196
	v_mov_b32_e32 v199, v196
	ds_bpermute_b32 v33, v10, v32
	ds_read_b64_tr_b16 v[200:201], v193 offset:38912
	ds_read_b64_tr_b16 v[202:203], v193 offset:39936
	ds_read_b64_tr_b16 v[204:205], v209 offset:38912
	ds_read_b64_tr_b16 v[206:207], v209 offset:39936
	s_waitcnt lgkmcnt(7)
	v_mfma_f32_32x32x16_bf16 v[16:31], v[0:3], v[196:199], 0
	v_cvt_pk_bf16_f32 v70, v70, v69
	v_cvt_pk_bf16_f32 v60, v61, v60
	v_cvt_pk_bf16_f32 v61, v59, v58
	v_cvt_pk_bf16_f32 v52, v53, v52
	v_cvt_pk_bf16_f32 v53, v51, v50
	v_cvt_pk_bf16_f32 v50, v41, v40
	v_cvt_pk_bf16_f32 v51, v39, v78
	s_waitcnt lgkmcnt(5)
	v_mfma_f32_32x32x16_bf16 v[0:15], v[4:7], v[196:199], 0
	s_waitcnt lgkmcnt(4)
	v_add_f32_e32 v32, v32, v33
	v_cvt_pk_bf16_f32 v34, v34, v36
	v_cvt_pk_bf16_f32 v36, v49, v76
	v_div_scale_f32 v33, s[92:93], v32, v32, 1.0
	s_waitcnt lgkmcnt(2)
	v_mfma_f32_32x32x16_bf16 v[16:31], v[200:203], v[196:199], v[16:31]
	s_waitcnt lgkmcnt(0)
	v_mfma_f32_32x32x16_bf16 v[0:15], v[204:207], v[196:199], v[0:15]
	ds_read_b64_tr_b16 v[200:201], v193 offset:40960
	ds_read_b64_tr_b16 v[202:203], v193 offset:41984
	ds_read_b64_tr_b16 v[204:205], v209 offset:40960
	ds_read_b64_tr_b16 v[206:207], v209 offset:41984
	v_cvt_pk_bf16_f32 v196, v45, v46
	v_cvt_pk_bf16_f32 v197, v47, v63
	v_cvt_pk_bf16_f32 v198, v74, v73
	v_cvt_pk_bf16_f32 v199, v72, v71
	v_cvt_pk_bf16_f32 v71, v68, v67
	v_cvt_pk_bf16_f32 v72, v66, v65
	s_waitcnt lgkmcnt(2)
	v_mfma_f32_32x32x16_bf16 v[16:31], v[200:203], v[196:199], v[16:31]
	v_cvt_pk_bf16_f32 v73, v64, v62
	ds_read_b64_tr_b16 v[62:63], v193 offset:43008
	ds_read_b64_tr_b16 v[64:65], v193 offset:44032
	ds_read_b64_tr_b16 v[66:67], v209 offset:43008
	ds_read_b64_tr_b16 v[68:69], v209 offset:44032
	s_waitcnt lgkmcnt(4)
	v_mfma_f32_32x32x16_bf16 v[0:15], v[204:207], v[196:199], v[0:15]
	s_waitcnt lgkmcnt(2)
	v_mfma_f32_32x32x16_bf16 v[16:31], v[62:65], v[70:73], v[16:31]
	v_cvt_pk_bf16_f32 v62, v57, v56
	v_cvt_pk_bf16_f32 v63, v55, v54
	s_waitcnt lgkmcnt(0)
	v_mfma_f32_32x32x16_bf16 v[0:15], v[66:69], v[70:73], v[0:15]
	ds_read_b64_tr_b16 v[54:55], v193 offset:45056
	ds_read_b64_tr_b16 v[56:57], v193 offset:46080
	ds_read_b64_tr_b16 v[64:65], v209 offset:45056
	ds_read_b64_tr_b16 v[66:67], v209 offset:46080
	s_waitcnt lgkmcnt(2)
	v_mfma_f32_32x32x16_bf16 v[16:31], v[54:57], v[60:63], v[16:31]
	v_cvt_pk_bf16_f32 v54, v77, v148
	v_cvt_pk_bf16_f32 v55, v150, v154
	s_waitcnt lgkmcnt(0)
	v_mfma_f32_32x32x16_bf16 v[0:15], v[64:67], v[60:63], v[0:15]
	ds_read_b64_tr_b16 v[56:57], v193 offset:47104
	ds_read_b64_tr_b16 v[58:59], v193 offset:48128
	ds_read_b64_tr_b16 v[60:61], v209 offset:47104
	ds_read_b64_tr_b16 v[62:63], v209 offset:48128
	s_waitcnt lgkmcnt(2)
	v_mfma_f32_32x32x16_bf16 v[16:31], v[56:59], v[52:55], v[16:31]
	s_waitcnt lgkmcnt(0)
	v_mfma_f32_32x32x16_bf16 v[0:15], v[60:63], v[52:55], v[0:15]
	ds_read_b64_tr_b16 v[54:55], v193 offset:49152
	ds_read_b64_tr_b16 v[56:57], v193 offset:50176
	ds_read_b64_tr_b16 v[58:59], v209 offset:49152
	ds_read_b64_tr_b16 v[60:61], v209 offset:50176
	v_cvt_pk_bf16_f32 v52, v149, v151
	v_cvt_pk_bf16_f32 v53, v153, v157
	s_waitcnt lgkmcnt(2)
	s_nop 0
	v_mfma_f32_32x32x16_bf16 v[16:31], v[54:57], v[50:53], v[16:31]
	s_waitcnt lgkmcnt(0)
	v_mfma_f32_32x32x16_bf16 v[0:15], v[58:61], v[50:53], v[0:15]
	ds_read_b64_tr_b16 v[54:55], v193 offset:51200
	ds_read_b64_tr_b16 v[56:57], v193 offset:52224
	ds_read_b64_tr_b16 v[58:59], v209 offset:51200
	ds_read_b64_tr_b16 v[60:61], v209 offset:52224
	v_cvt_pk_bf16_f32 v50, v152, v155
	v_cvt_pk_bf16_f32 v51, v156, v158
	v_cvt_pk_bf16_f32 v52, v159, v194
	v_cvt_pk_bf16_f32 v53, v195, v208
	s_waitcnt lgkmcnt(2)
	s_nop 0
	v_mfma_f32_32x32x16_bf16 v[16:31], v[54:57], v[50:53], v[16:31]
	s_waitcnt lgkmcnt(0)
	v_mfma_f32_32x32x16_bf16 v[0:15], v[58:61], v[50:53], v[0:15]
	v_cvt_pk_bf16_f32 v51, v42, v44
	ds_read_b64_tr_b16 v[44:45], v193 offset:53248
	ds_read_b64_tr_b16 v[46:47], v193 offset:54272
	ds_read_b64_tr_b16 v[54:55], v209 offset:53248
	ds_read_b64_tr_b16 v[56:57], v209 offset:54272
	v_cvt_pk_bf16_f32 v50, v35, v37
	v_cvt_pk_bf16_f32 v52, v75, v79
	v_cvt_pk_bf16_f32 v53, v145, v147
	v_cvt_pk_bf16_f32 v35, v38, v43
	v_cvt_pk_bf16_f32 v37, v144, v146
	s_waitcnt lgkmcnt(2)
	v_mfma_f32_32x32x16_bf16 v[16:31], v[44:47], v[50:53], v[16:31]
	ds_read_b64_tr_b16 v[38:39], v193 offset:55296
	ds_read_b64_tr_b16 v[40:41], v193 offset:56320
	ds_read_b64_tr_b16 v[42:43], v209 offset:55296
	ds_read_b64_tr_b16 v[44:45], v209 offset:56320
	s_waitcnt lgkmcnt(4)
	v_mfma_f32_32x32x16_bf16 v[0:15], v[54:57], v[50:53], v[0:15]
	s_waitcnt lgkmcnt(2)
	v_mfma_f32_32x32x16_bf16 v[16:31], v[38:41], v[34:37], v[16:31]
	v_lshlrev_b32_e32 v38, 1, v166
	v_mov_b32_e32 v39, v161
	s_waitcnt lgkmcnt(0)
	v_mfma_f32_32x32x16_bf16 v[0:15], v[42:45], v[34:37], v[0:15]
	v_rcp_f32_e32 v34, v33
	s_nop 0
	v_fma_f32 v35, -v33, v34, 1.0
	v_fmac_f32_e32 v34, v35, v34
	v_div_scale_f32 v35, vcc, 1.0, v32, 1.0
	v_mul_f32_e32 v36, v35, v34
	v_fma_f32 v37, -v33, v36, v35
	v_fmac_f32_e32 v36, v37, v34
	v_fma_f32 v33, -v33, v36, v35
	v_div_fmas_f32 v33, v33, v34, v36
	v_div_fixup_f32 v34, v33, v32, 1.0
	v_lshlrev_b64 v[36:37], s54, v[162:163]
	v_lshl_add_u64 v[36:37], v[36:37], 1, s[44:45]
	v_pk_mul_f32 v[16:17], v[16:17], v[34:35] op_sel_hi:[1,0]
	v_pk_mul_f32 v[18:19], v[18:19], v[34:35] op_sel_hi:[1,0]
	v_pk_mul_f32 v[20:21], v[20:21], v[34:35] op_sel_hi:[1,0]
	v_pk_mul_f32 v[22:23], v[22:23], v[34:35] op_sel_hi:[1,0]
	v_pk_mul_f32 v[24:25], v[24:25], v[34:35] op_sel_hi:[1,0]
	v_pk_mul_f32 v[26:27], v[26:27], v[34:35] op_sel_hi:[1,0]
	v_pk_mul_f32 v[28:29], v[28:29], v[34:35] op_sel_hi:[1,0]
	v_pk_mul_f32 v[30:31], v[30:31], v[34:35] op_sel_hi:[1,0]
	v_pk_mul_f32 v[0:1], v[0:1], v[34:35] op_sel_hi:[1,0]
	v_pk_mul_f32 v[2:3], v[2:3], v[34:35] op_sel_hi:[1,0]
	v_pk_mul_f32 v[4:5], v[4:5], v[34:35] op_sel_hi:[1,0]
	v_pk_mul_f32 v[6:7], v[6:7], v[34:35] op_sel_hi:[1,0]
	v_pk_mul_f32 v[8:9], v[8:9], v[34:35] op_sel_hi:[1,0]
	v_pk_mul_f32 v[10:11], v[10:11], v[34:35] op_sel_hi:[1,0]
	v_pk_mul_f32 v[12:13], v[12:13], v[34:35] op_sel_hi:[1,0]
	v_pk_mul_f32 v[14:15], v[14:15], v[34:35] op_sel_hi:[1,0]
	v_lshl_add_u64 v[36:37], v[36:37], 0, v[38:39]
	v_lshl_add_u64 v[36:37], v[36:37], 0, v[38:39]
	v_cvt_pk_bf16_f32 v16, v16, v17
	v_cvt_pk_bf16_f32 v17, v18, v19
	v_cvt_pk_bf16_f32 v18, v20, v21
	v_cvt_pk_bf16_f32 v19, v22, v23
	v_cvt_pk_bf16_f32 v20, v24, v25
	v_cvt_pk_bf16_f32 v21, v26, v27
	v_cvt_pk_bf16_f32 v22, v28, v29
	v_cvt_pk_bf16_f32 v23, v30, v31
	v_cvt_pk_bf16_f32 v0, v0, v1
	v_cvt_pk_bf16_f32 v1, v2, v3
	v_cvt_pk_bf16_f32 v2, v4, v5
	v_cvt_pk_bf16_f32 v3, v6, v7
	v_cvt_pk_bf16_f32 v4, v8, v9
	v_cvt_pk_bf16_f32 v5, v10, v11
	v_cvt_pk_bf16_f32 v6, v12, v13
	v_cvt_pk_bf16_f32 v7, v14, v15
	s_andn2_b64 s[44:45], s[46:47], exec
	s_and_b64 s[46:47], s[0:1], exec
	s_or_b64 s[46:47], s[44:45], s[46:47]
	s_nop 1
	v_permlane32_swap_b32 v16, v18
	v_permlane32_swap_b32 v17, v19
	v_permlane32_swap_b32 v20, v22
	v_permlane32_swap_b32 v21, v23
	v_permlane32_swap_b32 v0, v2
	v_permlane32_swap_b32 v1, v3
	v_permlane32_swap_b32 v4, v6
	v_permlane32_swap_b32 v5, v7
	global_store_dwordx4 v[36:37], v[16:19], off
	global_store_dwordx4 v[36:37], v[20:23], off offset:32
	global_store_dwordx4 v[36:37], v[0:3], off offset:64
	global_store_dwordx4 v[36:37], v[4:7], off offset:96
	s_nop 1

.LBB0_1129:
	s_mov_b64 exec, -1
	s_cmpk_gt_i32 s2, 0xff
	s_barrier
	s_cbranch_scc1 .LBB0_1164
	v_and_b32_e32 v0, 63, v181
	v_lshrrev_b32_e32 v4, 6, v181
	v_and_b32_e32 v1, 31, v0
	v_lshrrev_b32_e32 v2, 5, v0
	v_readfirstlane_b32 s0, v4
	v_lshlrev_b32_e32 v6, 4, v0
	v_mov_b32_e32 v7, 0x3b000000
	v_mov_b32_e32 v132, 0x3727c5ac
	v_readlane_b32 s8, v247, 9
	v_readlane_b32 s9, v247, 10
	v_readlane_b32 s10, v247, 11
	v_readlane_b32 s11, v247, 12
	v_readlane_b32 s12, v247, 15
	v_readlane_b32 s13, v247, 16
	s_nop 3
	s_add_u32 s28, s64, 0x3200000
	s_addc_u32 s29, s65, 0
	s_add_u32 s30, s64, 0xe200000
	s_addc_u32 s31, s65, 0
	s_lshl_b32 s4, s0, 15
	s_add_u32 s32, s64, 0x100000
	s_addc_u32 s33, s65, 0
	s_add_u32 s32, s32, s4
	s_addc_u32 s33, s33, 0
	s_lshl_b32 s4, s0, 9
	s_add_u32 s44, s12, s4
	s_addc_u32 s45, s13, 0
	s_lshl_b32 s4, s0, 14
	v_add_u32_e32 v128, s4, v6
	v_xor_b32_e32 v4, 64, v6
	v_add_u32_e32 v129, s4, v4
	v_xor_b32_e32 v4, 0x80, v6
	v_add_u32_e32 v130, s4, v4
	v_xor_b32_e32 v4, 0xc0, v6
	v_add_u32_e32 v131, s4, v4
	v_bfe_u32 v4, v0, 2, 2
	v_and_b32_e32 v5, 3, v0
	v_bfe_u32 v133, v0, 4, 1
	v_lshlrev_b32_e32 v133, 5, v133
	v_lshl_or_b32 v133, v5, 3, v133
	s_lshl_b32 s4, s0, 7
	v_or_b32_e32 v133, s4, v133
	v_lshlrev_b32_e32 v5, 6, v4
	v_xor_b32_e32 v135, 64, v133
	v_xor_b32_e32 v133, v133, v5
	v_xor_b32_e32 v135, v135, v5
	v_lshl_add_u32 v4, v2, 3, v4
	v_lshlrev_b32_e32 v4, 10, v4
	v_add_u32_e32 v133, v133, v4
	v_add_u32_e32 v135, v135, v4
	v_add_u32_e32 v134, 0x10000, v133
	v_add_u32_e32 v136, 0x10000, v135
	v_lshlrev_b32_e32 v137, 8, v1
	v_lshl_or_b32 v137, v2, 4, v137
	v_mul_u32_u24_e32 v138, 0x1400, v1
	v_lshl_or_b32 v138, v2, 4, v138
	v_lshlrev_b32_e32 v139, 11, v1
	v_lshl_or_b32 v139, v2, 4, v139
	v_lshlrev_b32_e32 v140, 2, v1
	s_mov_b32 s1, s2
.Lgm_loop:
	v_lshlrev_b32_e32 v4, 5, v0
	global_load_dwordx4 v[112:115], v4, s[8:9]
	global_load_dwordx4 v[116:119], v4, s[8:9] offset:16
	global_load_dwordx4 v[120:123], v4, s[10:11]
	global_load_dwordx4 v[124:127], v4, s[10:11] offset:16
	s_lshl_b32 s4, s1, 7
	s_lshl_b32 s5, s0, 4
	s_add_i32 s4, s4, s5
	s_mul_i32 s5, s4, 0x1400
	s_add_u32 s34, s28, s5
	s_addc_u32 s35, s29, 0
	s_add_u32 s34, s34, 0x1000
	s_addc_u32 s35, s35, 0
	s_add_u32 s36, s34, 0x1400
	s_addc_u32 s37, s35, 0
	global_load_dwordx4 v[8:11], v6, s[34:35]
	s_add_u32 s34, s34, 0x2800
	s_addc_u32 s35, s35, 0
	global_load_dwordx4 v[12:15], v6, s[36:37]
	s_add_u32 s36, s36, 0x2800
	s_addc_u32 s37, s37, 0
	global_load_dwordx4 v[16:19], v6, s[34:35]
	s_add_u32 s34, s34, 0x2800
	s_addc_u32 s35, s35, 0
	global_load_dwordx4 v[20:23], v6, s[36:37]
	s_add_u32 s36, s36, 0x2800
	s_addc_u32 s37, s37, 0
	global_load_dwordx4 v[24:27], v6, s[34:35]
	s_add_u32 s34, s34, 0x2800
	s_addc_u32 s35, s35, 0
	global_load_dwordx4 v[28:31], v6, s[36:37]
	s_add_u32 s36, s36, 0x2800
	s_addc_u32 s37, s37, 0
	global_load_dwordx4 v[32:35], v6, s[34:35]
	s_add_u32 s34, s34, 0x2800
	s_addc_u32 s35, s35, 0
	global_load_dwordx4 v[36:39], v6, s[36:37]
	s_add_u32 s36, s36, 0x2800
	s_addc_u32 s37, s37, 0
	global_load_dwordx4 v[40:43], v6, s[34:35]
	s_add_u32 s34, s34, 0x2800
	s_addc_u32 s35, s35, 0
	global_load_dwordx4 v[44:47], v6, s[36:37]
	s_add_u32 s36, s36, 0x2800
	s_addc_u32 s37, s37, 0
	global_load_dwordx4 v[48:51], v6, s[34:35]
	s_add_u32 s34, s34, 0x2800
	s_addc_u32 s35, s35, 0
	global_load_dwordx4 v[52:55], v6, s[36:37]
	s_add_u32 s36, s36, 0x2800
	s_addc_u32 s37, s37, 0
	global_load_dwordx4 v[56:59], v6, s[34:35]
	s_add_u32 s34, s34, 0x2800
	s_addc_u32 s35, s35, 0
	global_load_dwordx4 v[60:63], v6, s[36:37]
	s_add_u32 s36, s36, 0x2800
	s_addc_u32 s37, s37, 0
	global_load_dwordx4 v[64:67], v6, s[34:35]
	global_load_dwordx4 v[68:71], v6, s[36:37]
	s_lshl_b32 s4, s1, 7
	s_mul_i32 s4, s4, 0x1400
	s_lshl_b32 s5, s0, 7
	s_add_i32 s5, s5, 0xc00
	s_add_u32 s34, s28, s4
	s_addc_u32 s35, s29, 0
	s_add_u32 s34, s34, s5
	s_addc_u32 s35, s35, 0
	s_add_u32 s36, s34, 0x28000
	s_addc_u32 s37, s35, 0
	global_load_dwordx4 v[144:147], v138, s[34:35] offset:0
	global_load_dwordx4 v[148:151], v138, s[34:35] offset:32
	global_load_dwordx4 v[152:155], v138, s[34:35] offset:64
	global_load_dwordx4 v[156:159], v138, s[34:35] offset:96
	s_add_u32 s34, s34, 0x50000
	s_addc_u32 s35, s35, 0
	global_load_dwordx4 v[160:163], v138, s[36:37] offset:0
	global_load_dwordx4 v[164:167], v138, s[36:37] offset:32
	global_load_dwordx4 v[168:171], v138, s[36:37] offset:64
	global_load_dwordx4 v[172:175], v138, s[36:37] offset:96
	s_add_u32 s36, s36, 0x50000
	s_addc_u32 s37, s37, 0
	global_load_dwordx4 v[176:179], v138, s[34:35] offset:0
	global_load_dwordx4 v[184:187], v138, s[34:35] offset:32
	global_load_dwordx4 v[188:191], v138, s[34:35] offset:64
	global_load_dwordx4 v[192:195], v138, s[34:35] offset:96
	global_load_dwordx4 v[196:199], v138, s[36:37] offset:0
	global_load_dwordx4 v[200:203], v138, s[36:37] offset:32
	global_load_dwordx4 v[204:207], v138, s[36:37] offset:64
	global_load_dwordx4 v[240:243], v138, s[36:37] offset:96
	s_waitcnt vmcnt(28)
	v_lshlrev_b32_e32 v72, 16, v8
	v_and_b32_e32 v73, 0xffff0000, v8
	v_lshlrev_b32_e32 v74, 16, v9
	v_and_b32_e32 v75, 0xffff0000, v9
	v_lshlrev_b32_e32 v76, 16, v10
	v_and_b32_e32 v77, 0xffff0000, v10
	v_lshlrev_b32_e32 v78, 16, v11
	v_and_b32_e32 v79, 0xffff0000, v11
	v_lshlrev_b32_e32 v80, 16, v12
	v_and_b32_e32 v81, 0xffff0000, v12
	v_lshlrev_b32_e32 v82, 16, v13
	v_and_b32_e32 v83, 0xffff0000, v13
	v_lshlrev_b32_e32 v84, 16, v14
	v_and_b32_e32 v85, 0xffff0000, v14
	v_lshlrev_b32_e32 v86, 16, v15
	v_and_b32_e32 v87, 0xffff0000, v15
	v_lshlrev_b32_e32 v88, 16, v16
	v_and_b32_e32 v89, 0xffff0000, v16
	v_lshlrev_b32_e32 v90, 16, v17
	v_and_b32_e32 v91, 0xffff0000, v17
	v_lshlrev_b32_e32 v92, 16, v18
	v_and_b32_e32 v93, 0xffff0000, v18
	v_lshlrev_b32_e32 v94, 16, v19
	v_and_b32_e32 v95, 0xffff0000, v19
	v_lshlrev_b32_e32 v96, 16, v20
	v_and_b32_e32 v97, 0xffff0000, v20
	v_lshlrev_b32_e32 v98, 16, v21
	v_and_b32_e32 v99, 0xffff0000, v21
	v_lshlrev_b32_e32 v100, 16, v22
	v_and_b32_e32 v101, 0xffff0000, v22
	v_lshlrev_b32_e32 v102, 16, v23
	v_and_b32_e32 v103, 0xffff0000, v23
	v_add_f32_e32 v104, v72, v73
	v_add_f32_e32 v104, v104, v74
	v_add_f32_e32 v104, v104, v75
	v_add_f32_e32 v104, v104, v76
	v_add_f32_e32 v104, v104, v77
	v_add_f32_e32 v104, v104, v78
	v_add_f32_e32 v104, v104, v79
	v_add_f32_e32 v105, v80, v81
	v_add_f32_e32 v105, v105, v82
	v_add_f32_e32 v105, v105, v83
	v_add_f32_e32 v105, v105, v84
	v_add_f32_e32 v105, v105, v85
	v_add_f32_e32 v105, v105, v86
	v_add_f32_e32 v105, v105, v87
	v_add_f32_e32 v106, v88, v89
	v_add_f32_e32 v106, v106, v90
	v_add_f32_e32 v106, v106, v91
	v_add_f32_e32 v106, v106, v92
	v_add_f32_e32 v106, v106, v93
	v_add_f32_e32 v106, v106, v94
	v_add_f32_e32 v106, v106, v95
	v_add_f32_e32 v107, v96, v97
	v_add_f32_e32 v107, v107, v98
	v_add_f32_e32 v107, v107, v99
	v_add_f32_e32 v107, v107, v100
	v_add_f32_e32 v107, v107, v101
	v_add_f32_e32 v107, v107, v102
	v_add_f32_e32 v107, v107, v103
	v_add_f32_dpp v104, v104, v104 quad_perm:[1,0,3,2] row_mask:0xf bank_mask:0xf
	v_add_f32_dpp v105, v105, v105 quad_perm:[1,0,3,2] row_mask:0xf bank_mask:0xf
	v_add_f32_dpp v106, v106, v106 quad_perm:[1,0,3,2] row_mask:0xf bank_mask:0xf
	v_add_f32_dpp v107, v107, v107 quad_perm:[1,0,3,2] row_mask:0xf bank_mask:0xf
	v_add_f32_dpp v104, v104, v104 quad_perm:[2,3,0,1] row_mask:0xf bank_mask:0xf
	v_add_f32_dpp v105, v105, v105 quad_perm:[2,3,0,1] row_mask:0xf bank_mask:0xf
	v_add_f32_dpp v106, v106, v106 quad_perm:[2,3,0,1] row_mask:0xf bank_mask:0xf
	v_add_f32_dpp v107, v107, v107 quad_perm:[2,3,0,1] row_mask:0xf bank_mask:0xf
	v_add_f32_dpp v104, v104, v104 row_half_mirror row_mask:0xf bank_mask:0xf
	v_add_f32_dpp v105, v105, v105 row_half_mirror row_mask:0xf bank_mask:0xf
	v_add_f32_dpp v106, v106, v106 row_half_mirror row_mask:0xf bank_mask:0xf
	v_add_f32_dpp v107, v107, v107 row_half_mirror row_mask:0xf bank_mask:0xf
	v_add_f32_dpp v104, v104, v104 row_mirror row_mask:0xf bank_mask:0xf
	v_add_f32_dpp v105, v105, v105 row_mirror row_mask:0xf bank_mask:0xf
	v_add_f32_dpp v106, v106, v106 row_mirror row_mask:0xf bank_mask:0xf
	v_add_f32_dpp v107, v107, v107 row_mirror row_mask:0xf bank_mask:0xf
	v_add_f32_dpp v104, v104, v104 row_bcast:15 row_mask:0xa bank_mask:0xf
	v_add_f32_dpp v105, v105, v105 row_bcast:15 row_mask:0xa bank_mask:0xf
	v_add_f32_dpp v106, v106, v106 row_bcast:15 row_mask:0xa bank_mask:0xf
	v_add_f32_dpp v107, v107, v107 row_bcast:15 row_mask:0xa bank_mask:0xf
	v_add_f32_dpp v104, v104, v104 row_bcast:31 row_mask:0xc bank_mask:0xf
	v_add_f32_dpp v105, v105, v105 row_bcast:31 row_mask:0xc bank_mask:0xf
	v_add_f32_dpp v106, v106, v106 row_bcast:31 row_mask:0xc bank_mask:0xf
	v_add_f32_dpp v107, v107, v107 row_bcast:31 row_mask:0xc bank_mask:0xf
	v_readlane_b32 s24, v104, 63
	v_readlane_b32 s25, v105, 63
	v_readlane_b32 s26, v106, 63
	v_readlane_b32 s27, v107, 63
	s_nop 0
	v_mul_f32_e32 v108, s24, v7
	v_mul_f32_e32 v109, s25, v7
	v_mul_f32_e32 v110, s26, v7
	v_mul_f32_e32 v111, s27, v7
	v_sub_f32_e32 v72, v72, v108
	v_sub_f32_e32 v73, v73, v108
	v_sub_f32_e32 v74, v74, v108
	v_sub_f32_e32 v75, v75, v108
	v_sub_f32_e32 v76, v76, v108
	v_sub_f32_e32 v77, v77, v108
	v_sub_f32_e32 v78, v78, v108
	v_sub_f32_e32 v79, v79, v108
	v_sub_f32_e32 v80, v80, v109
	v_sub_f32_e32 v81, v81, v109
	v_sub_f32_e32 v82, v82, v109
	v_sub_f32_e32 v83, v83, v109
	v_sub_f32_e32 v84, v84, v109
	v_sub_f32_e32 v85, v85, v109
	v_sub_f32_e32 v86, v86, v109
	v_sub_f32_e32 v87, v87, v109
	v_sub_f32_e32 v88, v88, v110
	v_sub_f32_e32 v89, v89, v110
	v_sub_f32_e32 v90, v90, v110
	v_sub_f32_e32 v91, v91, v110
	v_sub_f32_e32 v92, v92, v110
	v_sub_f32_e32 v93, v93, v110
	v_sub_f32_e32 v94, v94, v110
	v_sub_f32_e32 v95, v95, v110
	v_sub_f32_e32 v96, v96, v111
	v_sub_f32_e32 v97, v97, v111
	v_sub_f32_e32 v98, v98, v111
	v_sub_f32_e32 v99, v99, v111
	v_sub_f32_e32 v100, v100, v111
	v_sub_f32_e32 v101, v101, v111
	v_sub_f32_e32 v102, v102, v111
	v_sub_f32_e32 v103, v103, v111
	v_mul_f32_e32 v104, v72, v72
	v_fmac_f32_e32 v104, v73, v73
	v_fmac_f32_e32 v104, v74, v74
	v_fmac_f32_e32 v104, v75, v75
	v_fmac_f32_e32 v104, v76, v76
	v_fmac_f32_e32 v104, v77, v77
	v_fmac_f32_e32 v104, v78, v78
	v_fmac_f32_e32 v104, v79, v79
	v_mul_f32_e32 v105, v80, v80
	v_fmac_f32_e32 v105, v81, v81
	v_fmac_f32_e32 v105, v82, v82
	v_fmac_f32_e32 v105, v83, v83
	v_fmac_f32_e32 v105, v84, v84
	v_fmac_f32_e32 v105, v85, v85
	v_fmac_f32_e32 v105, v86, v86
	v_fmac_f32_e32 v105, v87, v87
	v_mul_f32_e32 v106, v88, v88
	v_fmac_f32_e32 v106, v89, v89
	v_fmac_f32_e32 v106, v90, v90
	v_fmac_f32_e32 v106, v91, v91
	v_fmac_f32_e32 v106, v92, v92
	v_fmac_f32_e32 v106, v93, v93
	v_fmac_f32_e32 v106, v94, v94
	v_fmac_f32_e32 v106, v95, v95
	v_mul_f32_e32 v107, v96, v96
	v_fmac_f32_e32 v107, v97, v97
	v_fmac_f32_e32 v107, v98, v98
	v_fmac_f32_e32 v107, v99, v99
	v_fmac_f32_e32 v107, v100, v100
	v_fmac_f32_e32 v107, v101, v101
	v_fmac_f32_e32 v107, v102, v102
	v_fmac_f32_e32 v107, v103, v103
	v_add_f32_dpp v104, v104, v104 quad_perm:[1,0,3,2] row_mask:0xf bank_mask:0xf
	v_add_f32_dpp v105, v105, v105 quad_perm:[1,0,3,2] row_mask:0xf bank_mask:0xf
	v_add_f32_dpp v106, v106, v106 quad_perm:[1,0,3,2] row_mask:0xf bank_mask:0xf
	v_add_f32_dpp v107, v107, v107 quad_perm:[1,0,3,2] row_mask:0xf bank_mask:0xf
	v_add_f32_dpp v104, v104, v104 quad_perm:[2,3,0,1] row_mask:0xf bank_mask:0xf
	v_add_f32_dpp v105, v105, v105 quad_perm:[2,3,0,1] row_mask:0xf bank_mask:0xf
	v_add_f32_dpp v106, v106, v106 quad_perm:[2,3,0,1] row_mask:0xf bank_mask:0xf
	v_add_f32_dpp v107, v107, v107 quad_perm:[2,3,0,1] row_mask:0xf bank_mask:0xf
	v_add_f32_dpp v104, v104, v104 row_half_mirror row_mask:0xf bank_mask:0xf
	v_add_f32_dpp v105, v105, v105 row_half_mirror row_mask:0xf bank_mask:0xf
	v_add_f32_dpp v106, v106, v106 row_half_mirror row_mask:0xf bank_mask:0xf
	v_add_f32_dpp v107, v107, v107 row_half_mirror row_mask:0xf bank_mask:0xf
	v_add_f32_dpp v104, v104, v104 row_mirror row_mask:0xf bank_mask:0xf
	v_add_f32_dpp v105, v105, v105 row_mirror row_mask:0xf bank_mask:0xf
	v_add_f32_dpp v106, v106, v106 row_mirror row_mask:0xf bank_mask:0xf
	v_add_f32_dpp v107, v107, v107 row_mirror row_mask:0xf bank_mask:0xf
	v_add_f32_dpp v104, v104, v104 row_bcast:15 row_mask:0xa bank_mask:0xf
	v_add_f32_dpp v105, v105, v105 row_bcast:15 row_mask:0xa bank_mask:0xf
	v_add_f32_dpp v106, v106, v106 row_bcast:15 row_mask:0xa bank_mask:0xf
	v_add_f32_dpp v107, v107, v107 row_bcast:15 row_mask:0xa bank_mask:0xf
	v_add_f32_dpp v104, v104, v104 row_bcast:31 row_mask:0xc bank_mask:0xf
	v_add_f32_dpp v105, v105, v105 row_bcast:31 row_mask:0xc bank_mask:0xf
	v_add_f32_dpp v106, v106, v106 row_bcast:31 row_mask:0xc bank_mask:0xf
	v_add_f32_dpp v107, v107, v107 row_bcast:31 row_mask:0xc bank_mask:0xf
	v_readlane_b32 s24, v104, 63
	v_readlane_b32 s25, v105, 63
	v_readlane_b32 s26, v106, 63
	v_readlane_b32 s27, v107, 63
	s_nop 0
	v_fma_f32 v108, s24, v7, v132
	v_fma_f32 v109, s25, v7, v132
	v_fma_f32 v110, s26, v7, v132
	v_fma_f32 v111, s27, v7, v132
	v_rsq_f32_e32 v108, v108
	v_rsq_f32_e32 v109, v109
	v_rsq_f32_e32 v110, v110
	v_rsq_f32_e32 v111, v111
	s_nop 0
	v_mul_f32_e32 v72, v72, v108
	v_mul_f32_e32 v73, v73, v108
	v_mul_f32_e32 v74, v74, v108
	v_mul_f32_e32 v75, v75, v108
	v_mul_f32_e32 v76, v76, v108
	v_mul_f32_e32 v77, v77, v108
	v_mul_f32_e32 v78, v78, v108
	v_mul_f32_e32 v79, v79, v108
	v_fma_f32 v72, v72, v112, v120
	v_fma_f32 v73, v73, v113, v121
	v_fma_f32 v74, v74, v114, v122
	v_fma_f32 v75, v75, v115, v123
	v_fma_f32 v76, v76, v116, v124
	v_fma_f32 v77, v77, v117, v125
	v_fma_f32 v78, v78, v118, v126
	v_fma_f32 v79, v79, v119, v127
	v_mul_f32_e32 v80, v80, v109
	v_mul_f32_e32 v81, v81, v109
	v_mul_f32_e32 v82, v82, v109
	v_mul_f32_e32 v83, v83, v109
	v_mul_f32_e32 v84, v84, v109
	v_mul_f32_e32 v85, v85, v109
	v_mul_f32_e32 v86, v86, v109
	v_mul_f32_e32 v87, v87, v109
	v_fma_f32 v80, v80, v112, v120
	v_fma_f32 v81, v81, v113, v121
	v_fma_f32 v82, v82, v114, v122
	v_fma_f32 v83, v83, v115, v123
	v_fma_f32 v84, v84, v116, v124
	v_fma_f32 v85, v85, v117, v125
	v_fma_f32 v86, v86, v118, v126
	v_fma_f32 v87, v87, v119, v127
	v_mul_f32_e32 v88, v88, v110
	v_mul_f32_e32 v89, v89, v110
	v_mul_f32_e32 v90, v90, v110
	v_mul_f32_e32 v91, v91, v110
	v_mul_f32_e32 v92, v92, v110
	v_mul_f32_e32 v93, v93, v110
	v_mul_f32_e32 v94, v94, v110
	v_mul_f32_e32 v95, v95, v110
	v_fma_f32 v88, v88, v112, v120
	v_fma_f32 v89, v89, v113, v121
	v_fma_f32 v90, v90, v114, v122
	v_fma_f32 v91, v91, v115, v123
	v_fma_f32 v92, v92, v116, v124
	v_fma_f32 v93, v93, v117, v125
	v_fma_f32 v94, v94, v118, v126
	v_fma_f32 v95, v95, v119, v127
	v_mul_f32_e32 v96, v96, v111
	v_mul_f32_e32 v97, v97, v111
	v_mul_f32_e32 v98, v98, v111
	v_mul_f32_e32 v99, v99, v111
	v_mul_f32_e32 v100, v100, v111
	v_mul_f32_e32 v101, v101, v111
	v_mul_f32_e32 v102, v102, v111
	v_mul_f32_e32 v103, v103, v111
	v_fma_f32 v96, v96, v112, v120
	v_fma_f32 v97, v97, v113, v121
	v_fma_f32 v98, v98, v114, v122
	v_fma_f32 v99, v99, v115, v123
	v_fma_f32 v100, v100, v116, v124
	v_fma_f32 v101, v101, v117, v125
	v_fma_f32 v102, v102, v118, v126
	v_fma_f32 v103, v103, v119, v127
	v_cvt_pk_bf16_f32 v8, v72, v73
	v_cvt_pk_bf16_f32 v9, v74, v75
	v_cvt_pk_bf16_f32 v10, v76, v77
	v_cvt_pk_bf16_f32 v11, v78, v79
	v_cvt_pk_bf16_f32 v12, v80, v81
	v_cvt_pk_bf16_f32 v13, v82, v83
	v_cvt_pk_bf16_f32 v14, v84, v85
	v_cvt_pk_bf16_f32 v15, v86, v87
	v_cvt_pk_bf16_f32 v16, v88, v89
	v_cvt_pk_bf16_f32 v17, v90, v91
	v_cvt_pk_bf16_f32 v18, v92, v93
	v_cvt_pk_bf16_f32 v19, v94, v95
	v_cvt_pk_bf16_f32 v20, v96, v97
	v_cvt_pk_bf16_f32 v21, v98, v99
	v_cvt_pk_bf16_f32 v22, v100, v101
	v_cvt_pk_bf16_f32 v23, v102, v103
	ds_write_b128 v128, v[8:11] offset:0
	ds_write_b128 v129, v[12:15] offset:1024
	ds_write_b128 v130, v[16:19] offset:2048
	ds_write_b128 v131, v[20:23] offset:3072
	s_waitcnt vmcnt(24)
	v_lshlrev_b32_e32 v72, 16, v24
	v_and_b32_e32 v73, 0xffff0000, v24
	v_lshlrev_b32_e32 v74, 16, v25
	v_and_b32_e32 v75, 0xffff0000, v25
	v_lshlrev_b32_e32 v76, 16, v26
	v_and_b32_e32 v77, 0xffff0000, v26
	v_lshlrev_b32_e32 v78, 16, v27
	v_and_b32_e32 v79, 0xffff0000, v27
	v_lshlrev_b32_e32 v80, 16, v28
	v_and_b32_e32 v81, 0xffff0000, v28
	v_lshlrev_b32_e32 v82, 16, v29
	v_and_b32_e32 v83, 0xffff0000, v29
	v_lshlrev_b32_e32 v84, 16, v30
	v_and_b32_e32 v85, 0xffff0000, v30
	v_lshlrev_b32_e32 v86, 16, v31
	v_and_b32_e32 v87, 0xffff0000, v31
	v_lshlrev_b32_e32 v88, 16, v32
	v_and_b32_e32 v89, 0xffff0000, v32
	v_lshlrev_b32_e32 v90, 16, v33
	v_and_b32_e32 v91, 0xffff0000, v33
	v_lshlrev_b32_e32 v92, 16, v34
	v_and_b32_e32 v93, 0xffff0000, v34
	v_lshlrev_b32_e32 v94, 16, v35
	v_and_b32_e32 v95, 0xffff0000, v35
	v_lshlrev_b32_e32 v96, 16, v36
	v_and_b32_e32 v97, 0xffff0000, v36
	v_lshlrev_b32_e32 v98, 16, v37
	v_and_b32_e32 v99, 0xffff0000, v37
	v_lshlrev_b32_e32 v100, 16, v38
	v_and_b32_e32 v101, 0xffff0000, v38
	v_lshlrev_b32_e32 v102, 16, v39
	v_and_b32_e32 v103, 0xffff0000, v39
	v_add_f32_e32 v104, v72, v73
	v_add_f32_e32 v104, v104, v74
	v_add_f32_e32 v104, v104, v75
	v_add_f32_e32 v104, v104, v76
	v_add_f32_e32 v104, v104, v77
	v_add_f32_e32 v104, v104, v78
	v_add_f32_e32 v104, v104, v79
	v_add_f32_e32 v105, v80, v81
	v_add_f32_e32 v105, v105, v82
	v_add_f32_e32 v105, v105, v83
	v_add_f32_e32 v105, v105, v84
	v_add_f32_e32 v105, v105, v85
	v_add_f32_e32 v105, v105, v86
	v_add_f32_e32 v105, v105, v87
	v_add_f32_e32 v106, v88, v89
	v_add_f32_e32 v106, v106, v90
	v_add_f32_e32 v106, v106, v91
	v_add_f32_e32 v106, v106, v92
	v_add_f32_e32 v106, v106, v93
	v_add_f32_e32 v106, v106, v94
	v_add_f32_e32 v106, v106, v95
	v_add_f32_e32 v107, v96, v97
	v_add_f32_e32 v107, v107, v98
	v_add_f32_e32 v107, v107, v99
	v_add_f32_e32 v107, v107, v100
	v_add_f32_e32 v107, v107, v101
	v_add_f32_e32 v107, v107, v102
	v_add_f32_e32 v107, v107, v103
	v_add_f32_dpp v104, v104, v104 quad_perm:[1,0,3,2] row_mask:0xf bank_mask:0xf
	v_add_f32_dpp v105, v105, v105 quad_perm:[1,0,3,2] row_mask:0xf bank_mask:0xf
	v_add_f32_dpp v106, v106, v106 quad_perm:[1,0,3,2] row_mask:0xf bank_mask:0xf
	v_add_f32_dpp v107, v107, v107 quad_perm:[1,0,3,2] row_mask:0xf bank_mask:0xf
	v_add_f32_dpp v104, v104, v104 quad_perm:[2,3,0,1] row_mask:0xf bank_mask:0xf
	v_add_f32_dpp v105, v105, v105 quad_perm:[2,3,0,1] row_mask:0xf bank_mask:0xf
	v_add_f32_dpp v106, v106, v106 quad_perm:[2,3,0,1] row_mask:0xf bank_mask:0xf
	v_add_f32_dpp v107, v107, v107 quad_perm:[2,3,0,1] row_mask:0xf bank_mask:0xf
	v_add_f32_dpp v104, v104, v104 row_half_mirror row_mask:0xf bank_mask:0xf
	v_add_f32_dpp v105, v105, v105 row_half_mirror row_mask:0xf bank_mask:0xf
	v_add_f32_dpp v106, v106, v106 row_half_mirror row_mask:0xf bank_mask:0xf
	v_add_f32_dpp v107, v107, v107 row_half_mirror row_mask:0xf bank_mask:0xf
	v_add_f32_dpp v104, v104, v104 row_mirror row_mask:0xf bank_mask:0xf
	v_add_f32_dpp v105, v105, v105 row_mirror row_mask:0xf bank_mask:0xf
	v_add_f32_dpp v106, v106, v106 row_mirror row_mask:0xf bank_mask:0xf
	v_add_f32_dpp v107, v107, v107 row_mirror row_mask:0xf bank_mask:0xf
	v_add_f32_dpp v104, v104, v104 row_bcast:15 row_mask:0xa bank_mask:0xf
	v_add_f32_dpp v105, v105, v105 row_bcast:15 row_mask:0xa bank_mask:0xf
	v_add_f32_dpp v106, v106, v106 row_bcast:15 row_mask:0xa bank_mask:0xf
	v_add_f32_dpp v107, v107, v107 row_bcast:15 row_mask:0xa bank_mask:0xf
	v_add_f32_dpp v104, v104, v104 row_bcast:31 row_mask:0xc bank_mask:0xf
	v_add_f32_dpp v105, v105, v105 row_bcast:31 row_mask:0xc bank_mask:0xf
	v_add_f32_dpp v106, v106, v106 row_bcast:31 row_mask:0xc bank_mask:0xf
	v_add_f32_dpp v107, v107, v107 row_bcast:31 row_mask:0xc bank_mask:0xf
	v_readlane_b32 s24, v104, 63
	v_readlane_b32 s25, v105, 63
	v_readlane_b32 s26, v106, 63
	v_readlane_b32 s27, v107, 63
	s_nop 0
	v_mul_f32_e32 v108, s24, v7
	v_mul_f32_e32 v109, s25, v7
	v_mul_f32_e32 v110, s26, v7
	v_mul_f32_e32 v111, s27, v7
	v_sub_f32_e32 v72, v72, v108
	v_sub_f32_e32 v73, v73, v108
	v_sub_f32_e32 v74, v74, v108
	v_sub_f32_e32 v75, v75, v108
	v_sub_f32_e32 v76, v76, v108
	v_sub_f32_e32 v77, v77, v108
	v_sub_f32_e32 v78, v78, v108
	v_sub_f32_e32 v79, v79, v108
	v_sub_f32_e32 v80, v80, v109
	v_sub_f32_e32 v81, v81, v109
	v_sub_f32_e32 v82, v82, v109
	v_sub_f32_e32 v83, v83, v109
	v_sub_f32_e32 v84, v84, v109
	v_sub_f32_e32 v85, v85, v109
	v_sub_f32_e32 v86, v86, v109
	v_sub_f32_e32 v87, v87, v109
	v_sub_f32_e32 v88, v88, v110
	v_sub_f32_e32 v89, v89, v110
	v_sub_f32_e32 v90, v90, v110
	v_sub_f32_e32 v91, v91, v110
	v_sub_f32_e32 v92, v92, v110
	v_sub_f32_e32 v93, v93, v110
	v_sub_f32_e32 v94, v94, v110
	v_sub_f32_e32 v95, v95, v110
	v_sub_f32_e32 v96, v96, v111
	v_sub_f32_e32 v97, v97, v111
	v_sub_f32_e32 v98, v98, v111
	v_sub_f32_e32 v99, v99, v111
	v_sub_f32_e32 v100, v100, v111
	v_sub_f32_e32 v101, v101, v111
	v_sub_f32_e32 v102, v102, v111
	v_sub_f32_e32 v103, v103, v111
	v_mul_f32_e32 v104, v72, v72
	v_fmac_f32_e32 v104, v73, v73
	v_fmac_f32_e32 v104, v74, v74
	v_fmac_f32_e32 v104, v75, v75
	v_fmac_f32_e32 v104, v76, v76
	v_fmac_f32_e32 v104, v77, v77
	v_fmac_f32_e32 v104, v78, v78
	v_fmac_f32_e32 v104, v79, v79
	v_mul_f32_e32 v105, v80, v80
	v_fmac_f32_e32 v105, v81, v81
	v_fmac_f32_e32 v105, v82, v82
	v_fmac_f32_e32 v105, v83, v83
	v_fmac_f32_e32 v105, v84, v84
	v_fmac_f32_e32 v105, v85, v85
	v_fmac_f32_e32 v105, v86, v86
	v_fmac_f32_e32 v105, v87, v87
	v_mul_f32_e32 v106, v88, v88
	v_fmac_f32_e32 v106, v89, v89
	v_fmac_f32_e32 v106, v90, v90
	v_fmac_f32_e32 v106, v91, v91
	v_fmac_f32_e32 v106, v92, v92
	v_fmac_f32_e32 v106, v93, v93
	v_fmac_f32_e32 v106, v94, v94
	v_fmac_f32_e32 v106, v95, v95
	v_mul_f32_e32 v107, v96, v96
	v_fmac_f32_e32 v107, v97, v97
	v_fmac_f32_e32 v107, v98, v98
	v_fmac_f32_e32 v107, v99, v99
	v_fmac_f32_e32 v107, v100, v100
	v_fmac_f32_e32 v107, v101, v101
	v_fmac_f32_e32 v107, v102, v102
	v_fmac_f32_e32 v107, v103, v103
	v_add_f32_dpp v104, v104, v104 quad_perm:[1,0,3,2] row_mask:0xf bank_mask:0xf
	v_add_f32_dpp v105, v105, v105 quad_perm:[1,0,3,2] row_mask:0xf bank_mask:0xf
	v_add_f32_dpp v106, v106, v106 quad_perm:[1,0,3,2] row_mask:0xf bank_mask:0xf
	v_add_f32_dpp v107, v107, v107 quad_perm:[1,0,3,2] row_mask:0xf bank_mask:0xf
	v_add_f32_dpp v104, v104, v104 quad_perm:[2,3,0,1] row_mask:0xf bank_mask:0xf
	v_add_f32_dpp v105, v105, v105 quad_perm:[2,3,0,1] row_mask:0xf bank_mask:0xf
	v_add_f32_dpp v106, v106, v106 quad_perm:[2,3,0,1] row_mask:0xf bank_mask:0xf
	v_add_f32_dpp v107, v107, v107 quad_perm:[2,3,0,1] row_mask:0xf bank_mask:0xf
	v_add_f32_dpp v104, v104, v104 row_half_mirror row_mask:0xf bank_mask:0xf
	v_add_f32_dpp v105, v105, v105 row_half_mirror row_mask:0xf bank_mask:0xf
	v_add_f32_dpp v106, v106, v106 row_half_mirror row_mask:0xf bank_mask:0xf
	v_add_f32_dpp v107, v107, v107 row_half_mirror row_mask:0xf bank_mask:0xf
	v_add_f32_dpp v104, v104, v104 row_mirror row_mask:0xf bank_mask:0xf
	v_add_f32_dpp v105, v105, v105 row_mirror row_mask:0xf bank_mask:0xf
	v_add_f32_dpp v106, v106, v106 row_mirror row_mask:0xf bank_mask:0xf
	v_add_f32_dpp v107, v107, v107 row_mirror row_mask:0xf bank_mask:0xf
	v_add_f32_dpp v104, v104, v104 row_bcast:15 row_mask:0xa bank_mask:0xf
	v_add_f32_dpp v105, v105, v105 row_bcast:15 row_mask:0xa bank_mask:0xf
	v_add_f32_dpp v106, v106, v106 row_bcast:15 row_mask:0xa bank_mask:0xf
	v_add_f32_dpp v107, v107, v107 row_bcast:15 row_mask:0xa bank_mask:0xf
	v_add_f32_dpp v104, v104, v104 row_bcast:31 row_mask:0xc bank_mask:0xf
	v_add_f32_dpp v105, v105, v105 row_bcast:31 row_mask:0xc bank_mask:0xf
	v_add_f32_dpp v106, v106, v106 row_bcast:31 row_mask:0xc bank_mask:0xf
	v_add_f32_dpp v107, v107, v107 row_bcast:31 row_mask:0xc bank_mask:0xf
	v_readlane_b32 s24, v104, 63
	v_readlane_b32 s25, v105, 63
	v_readlane_b32 s26, v106, 63
	v_readlane_b32 s27, v107, 63
	s_nop 0
	v_fma_f32 v108, s24, v7, v132
	v_fma_f32 v109, s25, v7, v132
	v_fma_f32 v110, s26, v7, v132
	v_fma_f32 v111, s27, v7, v132
	v_rsq_f32_e32 v108, v108
	v_rsq_f32_e32 v109, v109
	v_rsq_f32_e32 v110, v110
	v_rsq_f32_e32 v111, v111
	s_nop 0
	v_mul_f32_e32 v72, v72, v108
	v_mul_f32_e32 v73, v73, v108
	v_mul_f32_e32 v74, v74, v108
	v_mul_f32_e32 v75, v75, v108
	v_mul_f32_e32 v76, v76, v108
	v_mul_f32_e32 v77, v77, v108
	v_mul_f32_e32 v78, v78, v108
	v_mul_f32_e32 v79, v79, v108
	v_fma_f32 v72, v72, v112, v120
	v_fma_f32 v73, v73, v113, v121
	v_fma_f32 v74, v74, v114, v122
	v_fma_f32 v75, v75, v115, v123
	v_fma_f32 v76, v76, v116, v124
	v_fma_f32 v77, v77, v117, v125
	v_fma_f32 v78, v78, v118, v126
	v_fma_f32 v79, v79, v119, v127
	v_mul_f32_e32 v80, v80, v109
	v_mul_f32_e32 v81, v81, v109
	v_mul_f32_e32 v82, v82, v109
	v_mul_f32_e32 v83, v83, v109
	v_mul_f32_e32 v84, v84, v109
	v_mul_f32_e32 v85, v85, v109
	v_mul_f32_e32 v86, v86, v109
	v_mul_f32_e32 v87, v87, v109
	v_fma_f32 v80, v80, v112, v120
	v_fma_f32 v81, v81, v113, v121
	v_fma_f32 v82, v82, v114, v122
	v_fma_f32 v83, v83, v115, v123
	v_fma_f32 v84, v84, v116, v124
	v_fma_f32 v85, v85, v117, v125
	v_fma_f32 v86, v86, v118, v126
	v_fma_f32 v87, v87, v119, v127
	v_mul_f32_e32 v88, v88, v110
	v_mul_f32_e32 v89, v89, v110
	v_mul_f32_e32 v90, v90, v110
	v_mul_f32_e32 v91, v91, v110
	v_mul_f32_e32 v92, v92, v110
	v_mul_f32_e32 v93, v93, v110
	v_mul_f32_e32 v94, v94, v110
	v_mul_f32_e32 v95, v95, v110
	v_fma_f32 v88, v88, v112, v120
	v_fma_f32 v89, v89, v113, v121
	v_fma_f32 v90, v90, v114, v122
	v_fma_f32 v91, v91, v115, v123
	v_fma_f32 v92, v92, v116, v124
	v_fma_f32 v93, v93, v117, v125
	v_fma_f32 v94, v94, v118, v126
	v_fma_f32 v95, v95, v119, v127
	v_mul_f32_e32 v96, v96, v111
	v_mul_f32_e32 v97, v97, v111
	v_mul_f32_e32 v98, v98, v111
	v_mul_f32_e32 v99, v99, v111
	v_mul_f32_e32 v100, v100, v111
	v_mul_f32_e32 v101, v101, v111
	v_mul_f32_e32 v102, v102, v111
	v_mul_f32_e32 v103, v103, v111
	v_fma_f32 v96, v96, v112, v120
	v_fma_f32 v97, v97, v113, v121
	v_fma_f32 v98, v98, v114, v122
	v_fma_f32 v99, v99, v115, v123
	v_fma_f32 v100, v100, v116, v124
	v_fma_f32 v101, v101, v117, v125
	v_fma_f32 v102, v102, v118, v126
	v_fma_f32 v103, v103, v119, v127
	v_cvt_pk_bf16_f32 v24, v72, v73
	v_cvt_pk_bf16_f32 v25, v74, v75
	v_cvt_pk_bf16_f32 v26, v76, v77
	v_cvt_pk_bf16_f32 v27, v78, v79
	v_cvt_pk_bf16_f32 v28, v80, v81
	v_cvt_pk_bf16_f32 v29, v82, v83
	v_cvt_pk_bf16_f32 v30, v84, v85
	v_cvt_pk_bf16_f32 v31, v86, v87
	v_cvt_pk_bf16_f32 v32, v88, v89
	v_cvt_pk_bf16_f32 v33, v90, v91
	v_cvt_pk_bf16_f32 v34, v92, v93
	v_cvt_pk_bf16_f32 v35, v94, v95
	v_cvt_pk_bf16_f32 v36, v96, v97
	v_cvt_pk_bf16_f32 v37, v98, v99
	v_cvt_pk_bf16_f32 v38, v100, v101
	v_cvt_pk_bf16_f32 v39, v102, v103
	ds_write_b128 v128, v[24:27] offset:4096
	ds_write_b128 v129, v[28:31] offset:5120
	ds_write_b128 v130, v[32:35] offset:6144
	ds_write_b128 v131, v[36:39] offset:7168
	s_waitcnt vmcnt(20)
	v_lshlrev_b32_e32 v72, 16, v40
	v_and_b32_e32 v73, 0xffff0000, v40
	v_lshlrev_b32_e32 v74, 16, v41
	v_and_b32_e32 v75, 0xffff0000, v41
	v_lshlrev_b32_e32 v76, 16, v42
	v_and_b32_e32 v77, 0xffff0000, v42
	v_lshlrev_b32_e32 v78, 16, v43
	v_and_b32_e32 v79, 0xffff0000, v43
	v_lshlrev_b32_e32 v80, 16, v44
	v_and_b32_e32 v81, 0xffff0000, v44
	v_lshlrev_b32_e32 v82, 16, v45
	v_and_b32_e32 v83, 0xffff0000, v45
	v_lshlrev_b32_e32 v84, 16, v46
	v_and_b32_e32 v85, 0xffff0000, v46
	v_lshlrev_b32_e32 v86, 16, v47
	v_and_b32_e32 v87, 0xffff0000, v47
	v_lshlrev_b32_e32 v88, 16, v48
	v_and_b32_e32 v89, 0xffff0000, v48
	v_lshlrev_b32_e32 v90, 16, v49
	v_and_b32_e32 v91, 0xffff0000, v49
	v_lshlrev_b32_e32 v92, 16, v50
	v_and_b32_e32 v93, 0xffff0000, v50
	v_lshlrev_b32_e32 v94, 16, v51
	v_and_b32_e32 v95, 0xffff0000, v51
	v_lshlrev_b32_e32 v96, 16, v52
	v_and_b32_e32 v97, 0xffff0000, v52
	v_lshlrev_b32_e32 v98, 16, v53
	v_and_b32_e32 v99, 0xffff0000, v53
	v_lshlrev_b32_e32 v100, 16, v54
	v_and_b32_e32 v101, 0xffff0000, v54
	v_lshlrev_b32_e32 v102, 16, v55
	v_and_b32_e32 v103, 0xffff0000, v55
	v_add_f32_e32 v104, v72, v73
	v_add_f32_e32 v104, v104, v74
	v_add_f32_e32 v104, v104, v75
	v_add_f32_e32 v104, v104, v76
	v_add_f32_e32 v104, v104, v77
	v_add_f32_e32 v104, v104, v78
	v_add_f32_e32 v104, v104, v79
	v_add_f32_e32 v105, v80, v81
	v_add_f32_e32 v105, v105, v82
	v_add_f32_e32 v105, v105, v83
	v_add_f32_e32 v105, v105, v84
	v_add_f32_e32 v105, v105, v85
	v_add_f32_e32 v105, v105, v86
	v_add_f32_e32 v105, v105, v87
	v_add_f32_e32 v106, v88, v89
	v_add_f32_e32 v106, v106, v90
	v_add_f32_e32 v106, v106, v91
	v_add_f32_e32 v106, v106, v92
	v_add_f32_e32 v106, v106, v93
	v_add_f32_e32 v106, v106, v94
	v_add_f32_e32 v106, v106, v95
	v_add_f32_e32 v107, v96, v97
	v_add_f32_e32 v107, v107, v98
	v_add_f32_e32 v107, v107, v99
	v_add_f32_e32 v107, v107, v100
	v_add_f32_e32 v107, v107, v101
	v_add_f32_e32 v107, v107, v102
	v_add_f32_e32 v107, v107, v103
	v_add_f32_dpp v104, v104, v104 quad_perm:[1,0,3,2] row_mask:0xf bank_mask:0xf
	v_add_f32_dpp v105, v105, v105 quad_perm:[1,0,3,2] row_mask:0xf bank_mask:0xf
	v_add_f32_dpp v106, v106, v106 quad_perm:[1,0,3,2] row_mask:0xf bank_mask:0xf
	v_add_f32_dpp v107, v107, v107 quad_perm:[1,0,3,2] row_mask:0xf bank_mask:0xf
	v_add_f32_dpp v104, v104, v104 quad_perm:[2,3,0,1] row_mask:0xf bank_mask:0xf
	v_add_f32_dpp v105, v105, v105 quad_perm:[2,3,0,1] row_mask:0xf bank_mask:0xf
	v_add_f32_dpp v106, v106, v106 quad_perm:[2,3,0,1] row_mask:0xf bank_mask:0xf
	v_add_f32_dpp v107, v107, v107 quad_perm:[2,3,0,1] row_mask:0xf bank_mask:0xf
	v_add_f32_dpp v104, v104, v104 row_half_mirror row_mask:0xf bank_mask:0xf
	v_add_f32_dpp v105, v105, v105 row_half_mirror row_mask:0xf bank_mask:0xf
	v_add_f32_dpp v106, v106, v106 row_half_mirror row_mask:0xf bank_mask:0xf
	v_add_f32_dpp v107, v107, v107 row_half_mirror row_mask:0xf bank_mask:0xf
	v_add_f32_dpp v104, v104, v104 row_mirror row_mask:0xf bank_mask:0xf
	v_add_f32_dpp v105, v105, v105 row_mirror row_mask:0xf bank_mask:0xf
	v_add_f32_dpp v106, v106, v106 row_mirror row_mask:0xf bank_mask:0xf
	v_add_f32_dpp v107, v107, v107 row_mirror row_mask:0xf bank_mask:0xf
	v_add_f32_dpp v104, v104, v104 row_bcast:15 row_mask:0xa bank_mask:0xf
	v_add_f32_dpp v105, v105, v105 row_bcast:15 row_mask:0xa bank_mask:0xf
	v_add_f32_dpp v106, v106, v106 row_bcast:15 row_mask:0xa bank_mask:0xf
	v_add_f32_dpp v107, v107, v107 row_bcast:15 row_mask:0xa bank_mask:0xf
	v_add_f32_dpp v104, v104, v104 row_bcast:31 row_mask:0xc bank_mask:0xf
	v_add_f32_dpp v105, v105, v105 row_bcast:31 row_mask:0xc bank_mask:0xf
	v_add_f32_dpp v106, v106, v106 row_bcast:31 row_mask:0xc bank_mask:0xf
	v_add_f32_dpp v107, v107, v107 row_bcast:31 row_mask:0xc bank_mask:0xf
	v_readlane_b32 s24, v104, 63
	v_readlane_b32 s25, v105, 63
	v_readlane_b32 s26, v106, 63
	v_readlane_b32 s27, v107, 63
	s_nop 0
	v_mul_f32_e32 v108, s24, v7
	v_mul_f32_e32 v109, s25, v7
	v_mul_f32_e32 v110, s26, v7
	v_mul_f32_e32 v111, s27, v7
	v_sub_f32_e32 v72, v72, v108
	v_sub_f32_e32 v73, v73, v108
	v_sub_f32_e32 v74, v74, v108
	v_sub_f32_e32 v75, v75, v108
	v_sub_f32_e32 v76, v76, v108
	v_sub_f32_e32 v77, v77, v108
	v_sub_f32_e32 v78, v78, v108
	v_sub_f32_e32 v79, v79, v108
	v_sub_f32_e32 v80, v80, v109
	v_sub_f32_e32 v81, v81, v109
	v_sub_f32_e32 v82, v82, v109
	v_sub_f32_e32 v83, v83, v109
	v_sub_f32_e32 v84, v84, v109
	v_sub_f32_e32 v85, v85, v109
	v_sub_f32_e32 v86, v86, v109
	v_sub_f32_e32 v87, v87, v109
	v_sub_f32_e32 v88, v88, v110
	v_sub_f32_e32 v89, v89, v110
	v_sub_f32_e32 v90, v90, v110
	v_sub_f32_e32 v91, v91, v110
	v_sub_f32_e32 v92, v92, v110
	v_sub_f32_e32 v93, v93, v110
	v_sub_f32_e32 v94, v94, v110
	v_sub_f32_e32 v95, v95, v110
	v_sub_f32_e32 v96, v96, v111
	v_sub_f32_e32 v97, v97, v111
	v_sub_f32_e32 v98, v98, v111
	v_sub_f32_e32 v99, v99, v111
	v_sub_f32_e32 v100, v100, v111
	v_sub_f32_e32 v101, v101, v111
	v_sub_f32_e32 v102, v102, v111
	v_sub_f32_e32 v103, v103, v111
	v_mul_f32_e32 v104, v72, v72
	v_fmac_f32_e32 v104, v73, v73
	v_fmac_f32_e32 v104, v74, v74
	v_fmac_f32_e32 v104, v75, v75
	v_fmac_f32_e32 v104, v76, v76
	v_fmac_f32_e32 v104, v77, v77
	v_fmac_f32_e32 v104, v78, v78
	v_fmac_f32_e32 v104, v79, v79
	v_mul_f32_e32 v105, v80, v80
	v_fmac_f32_e32 v105, v81, v81
	v_fmac_f32_e32 v105, v82, v82
	v_fmac_f32_e32 v105, v83, v83
	v_fmac_f32_e32 v105, v84, v84
	v_fmac_f32_e32 v105, v85, v85
	v_fmac_f32_e32 v105, v86, v86
	v_fmac_f32_e32 v105, v87, v87
	v_mul_f32_e32 v106, v88, v88
	v_fmac_f32_e32 v106, v89, v89
	v_fmac_f32_e32 v106, v90, v90
	v_fmac_f32_e32 v106, v91, v91
	v_fmac_f32_e32 v106, v92, v92
	v_fmac_f32_e32 v106, v93, v93
	v_fmac_f32_e32 v106, v94, v94
	v_fmac_f32_e32 v106, v95, v95
	v_mul_f32_e32 v107, v96, v96
	v_fmac_f32_e32 v107, v97, v97
	v_fmac_f32_e32 v107, v98, v98
	v_fmac_f32_e32 v107, v99, v99
	v_fmac_f32_e32 v107, v100, v100
	v_fmac_f32_e32 v107, v101, v101
	v_fmac_f32_e32 v107, v102, v102
	v_fmac_f32_e32 v107, v103, v103
	v_add_f32_dpp v104, v104, v104 quad_perm:[1,0,3,2] row_mask:0xf bank_mask:0xf
	v_add_f32_dpp v105, v105, v105 quad_perm:[1,0,3,2] row_mask:0xf bank_mask:0xf
	v_add_f32_dpp v106, v106, v106 quad_perm:[1,0,3,2] row_mask:0xf bank_mask:0xf
	v_add_f32_dpp v107, v107, v107 quad_perm:[1,0,3,2] row_mask:0xf bank_mask:0xf
	v_add_f32_dpp v104, v104, v104 quad_perm:[2,3,0,1] row_mask:0xf bank_mask:0xf
	v_add_f32_dpp v105, v105, v105 quad_perm:[2,3,0,1] row_mask:0xf bank_mask:0xf
	v_add_f32_dpp v106, v106, v106 quad_perm:[2,3,0,1] row_mask:0xf bank_mask:0xf
	v_add_f32_dpp v107, v107, v107 quad_perm:[2,3,0,1] row_mask:0xf bank_mask:0xf
	v_add_f32_dpp v104, v104, v104 row_half_mirror row_mask:0xf bank_mask:0xf
	v_add_f32_dpp v105, v105, v105 row_half_mirror row_mask:0xf bank_mask:0xf
	v_add_f32_dpp v106, v106, v106 row_half_mirror row_mask:0xf bank_mask:0xf
	v_add_f32_dpp v107, v107, v107 row_half_mirror row_mask:0xf bank_mask:0xf
	v_add_f32_dpp v104, v104, v104 row_mirror row_mask:0xf bank_mask:0xf
	v_add_f32_dpp v105, v105, v105 row_mirror row_mask:0xf bank_mask:0xf
	v_add_f32_dpp v106, v106, v106 row_mirror row_mask:0xf bank_mask:0xf
	v_add_f32_dpp v107, v107, v107 row_mirror row_mask:0xf bank_mask:0xf
	v_add_f32_dpp v104, v104, v104 row_bcast:15 row_mask:0xa bank_mask:0xf
	v_add_f32_dpp v105, v105, v105 row_bcast:15 row_mask:0xa bank_mask:0xf
	v_add_f32_dpp v106, v106, v106 row_bcast:15 row_mask:0xa bank_mask:0xf
	v_add_f32_dpp v107, v107, v107 row_bcast:15 row_mask:0xa bank_mask:0xf
	v_add_f32_dpp v104, v104, v104 row_bcast:31 row_mask:0xc bank_mask:0xf
	v_add_f32_dpp v105, v105, v105 row_bcast:31 row_mask:0xc bank_mask:0xf
	v_add_f32_dpp v106, v106, v106 row_bcast:31 row_mask:0xc bank_mask:0xf
	v_add_f32_dpp v107, v107, v107 row_bcast:31 row_mask:0xc bank_mask:0xf
	v_readlane_b32 s24, v104, 63
	v_readlane_b32 s25, v105, 63
	v_readlane_b32 s26, v106, 63
	v_readlane_b32 s27, v107, 63
	s_nop 0
	v_fma_f32 v108, s24, v7, v132
	v_fma_f32 v109, s25, v7, v132
	v_fma_f32 v110, s26, v7, v132
	v_fma_f32 v111, s27, v7, v132
	v_rsq_f32_e32 v108, v108
	v_rsq_f32_e32 v109, v109
	v_rsq_f32_e32 v110, v110
	v_rsq_f32_e32 v111, v111
	s_nop 0
	v_mul_f32_e32 v72, v72, v108
	v_mul_f32_e32 v73, v73, v108
	v_mul_f32_e32 v74, v74, v108
	v_mul_f32_e32 v75, v75, v108
	v_mul_f32_e32 v76, v76, v108
	v_mul_f32_e32 v77, v77, v108
	v_mul_f32_e32 v78, v78, v108
	v_mul_f32_e32 v79, v79, v108
	v_fma_f32 v72, v72, v112, v120
	v_fma_f32 v73, v73, v113, v121
	v_fma_f32 v74, v74, v114, v122
	v_fma_f32 v75, v75, v115, v123
	v_fma_f32 v76, v76, v116, v124
	v_fma_f32 v77, v77, v117, v125
	v_fma_f32 v78, v78, v118, v126
	v_fma_f32 v79, v79, v119, v127
	v_mul_f32_e32 v80, v80, v109
	v_mul_f32_e32 v81, v81, v109
	v_mul_f32_e32 v82, v82, v109
	v_mul_f32_e32 v83, v83, v109
	v_mul_f32_e32 v84, v84, v109
	v_mul_f32_e32 v85, v85, v109
	v_mul_f32_e32 v86, v86, v109
	v_mul_f32_e32 v87, v87, v109
	v_fma_f32 v80, v80, v112, v120
	v_fma_f32 v81, v81, v113, v121
	v_fma_f32 v82, v82, v114, v122
	v_fma_f32 v83, v83, v115, v123
	v_fma_f32 v84, v84, v116, v124
	v_fma_f32 v85, v85, v117, v125
	v_fma_f32 v86, v86, v118, v126
	v_fma_f32 v87, v87, v119, v127
	v_mul_f32_e32 v88, v88, v110
	v_mul_f32_e32 v89, v89, v110
	v_mul_f32_e32 v90, v90, v110
	v_mul_f32_e32 v91, v91, v110
	v_mul_f32_e32 v92, v92, v110
	v_mul_f32_e32 v93, v93, v110
	v_mul_f32_e32 v94, v94, v110
	v_mul_f32_e32 v95, v95, v110
	v_fma_f32 v88, v88, v112, v120
	v_fma_f32 v89, v89, v113, v121
	v_fma_f32 v90, v90, v114, v122
	v_fma_f32 v91, v91, v115, v123
	v_fma_f32 v92, v92, v116, v124
	v_fma_f32 v93, v93, v117, v125
	v_fma_f32 v94, v94, v118, v126
	v_fma_f32 v95, v95, v119, v127
	v_mul_f32_e32 v96, v96, v111
	v_mul_f32_e32 v97, v97, v111
	v_mul_f32_e32 v98, v98, v111
	v_mul_f32_e32 v99, v99, v111
	v_mul_f32_e32 v100, v100, v111
	v_mul_f32_e32 v101, v101, v111
	v_mul_f32_e32 v102, v102, v111
	v_mul_f32_e32 v103, v103, v111
	v_fma_f32 v96, v96, v112, v120
	v_fma_f32 v97, v97, v113, v121
	v_fma_f32 v98, v98, v114, v122
	v_fma_f32 v99, v99, v115, v123
	v_fma_f32 v100, v100, v116, v124
	v_fma_f32 v101, v101, v117, v125
	v_fma_f32 v102, v102, v118, v126
	v_fma_f32 v103, v103, v119, v127
	v_cvt_pk_bf16_f32 v40, v72, v73
	v_cvt_pk_bf16_f32 v41, v74, v75
	v_cvt_pk_bf16_f32 v42, v76, v77
	v_cvt_pk_bf16_f32 v43, v78, v79
	v_cvt_pk_bf16_f32 v44, v80, v81
	v_cvt_pk_bf16_f32 v45, v82, v83
	v_cvt_pk_bf16_f32 v46, v84, v85
	v_cvt_pk_bf16_f32 v47, v86, v87
	v_cvt_pk_bf16_f32 v48, v88, v89
	v_cvt_pk_bf16_f32 v49, v90, v91
	v_cvt_pk_bf16_f32 v50, v92, v93
	v_cvt_pk_bf16_f32 v51, v94, v95
	v_cvt_pk_bf16_f32 v52, v96, v97
	v_cvt_pk_bf16_f32 v53, v98, v99
	v_cvt_pk_bf16_f32 v54, v100, v101
	v_cvt_pk_bf16_f32 v55, v102, v103
	ds_write_b128 v128, v[40:43] offset:8192
	ds_write_b128 v129, v[44:47] offset:9216
	ds_write_b128 v130, v[48:51] offset:10240
	ds_write_b128 v131, v[52:55] offset:11264
	s_waitcnt vmcnt(16)
	v_lshlrev_b32_e32 v72, 16, v56
	v_and_b32_e32 v73, 0xffff0000, v56
	v_lshlrev_b32_e32 v74, 16, v57
	v_and_b32_e32 v75, 0xffff0000, v57
	v_lshlrev_b32_e32 v76, 16, v58
	v_and_b32_e32 v77, 0xffff0000, v58
	v_lshlrev_b32_e32 v78, 16, v59
	v_and_b32_e32 v79, 0xffff0000, v59
	v_lshlrev_b32_e32 v80, 16, v60
	v_and_b32_e32 v81, 0xffff0000, v60
	v_lshlrev_b32_e32 v82, 16, v61
	v_and_b32_e32 v83, 0xffff0000, v61
	v_lshlrev_b32_e32 v84, 16, v62
	v_and_b32_e32 v85, 0xffff0000, v62
	v_lshlrev_b32_e32 v86, 16, v63
	v_and_b32_e32 v87, 0xffff0000, v63
	v_lshlrev_b32_e32 v88, 16, v64
	v_and_b32_e32 v89, 0xffff0000, v64
	v_lshlrev_b32_e32 v90, 16, v65
	v_and_b32_e32 v91, 0xffff0000, v65
	v_lshlrev_b32_e32 v92, 16, v66
	v_and_b32_e32 v93, 0xffff0000, v66
	v_lshlrev_b32_e32 v94, 16, v67
	v_and_b32_e32 v95, 0xffff0000, v67
	v_lshlrev_b32_e32 v96, 16, v68
	v_and_b32_e32 v97, 0xffff0000, v68
	v_lshlrev_b32_e32 v98, 16, v69
	v_and_b32_e32 v99, 0xffff0000, v69
	v_lshlrev_b32_e32 v100, 16, v70
	v_and_b32_e32 v101, 0xffff0000, v70
	v_lshlrev_b32_e32 v102, 16, v71
	v_and_b32_e32 v103, 0xffff0000, v71
	v_add_f32_e32 v104, v72, v73
	v_add_f32_e32 v104, v104, v74
	v_add_f32_e32 v104, v104, v75
	v_add_f32_e32 v104, v104, v76
	v_add_f32_e32 v104, v104, v77
	v_add_f32_e32 v104, v104, v78
	v_add_f32_e32 v104, v104, v79
	v_add_f32_e32 v105, v80, v81
	v_add_f32_e32 v105, v105, v82
	v_add_f32_e32 v105, v105, v83
	v_add_f32_e32 v105, v105, v84
	v_add_f32_e32 v105, v105, v85
	v_add_f32_e32 v105, v105, v86
	v_add_f32_e32 v105, v105, v87
	v_add_f32_e32 v106, v88, v89
	v_add_f32_e32 v106, v106, v90
	v_add_f32_e32 v106, v106, v91
	v_add_f32_e32 v106, v106, v92
	v_add_f32_e32 v106, v106, v93
	v_add_f32_e32 v106, v106, v94
	v_add_f32_e32 v106, v106, v95
	v_add_f32_e32 v107, v96, v97
	v_add_f32_e32 v107, v107, v98
	v_add_f32_e32 v107, v107, v99
	v_add_f32_e32 v107, v107, v100
	v_add_f32_e32 v107, v107, v101
	v_add_f32_e32 v107, v107, v102
	v_add_f32_e32 v107, v107, v103
	v_add_f32_dpp v104, v104, v104 quad_perm:[1,0,3,2] row_mask:0xf bank_mask:0xf
	v_add_f32_dpp v105, v105, v105 quad_perm:[1,0,3,2] row_mask:0xf bank_mask:0xf
	v_add_f32_dpp v106, v106, v106 quad_perm:[1,0,3,2] row_mask:0xf bank_mask:0xf
	v_add_f32_dpp v107, v107, v107 quad_perm:[1,0,3,2] row_mask:0xf bank_mask:0xf
	v_add_f32_dpp v104, v104, v104 quad_perm:[2,3,0,1] row_mask:0xf bank_mask:0xf
	v_add_f32_dpp v105, v105, v105 quad_perm:[2,3,0,1] row_mask:0xf bank_mask:0xf
	v_add_f32_dpp v106, v106, v106 quad_perm:[2,3,0,1] row_mask:0xf bank_mask:0xf
	v_add_f32_dpp v107, v107, v107 quad_perm:[2,3,0,1] row_mask:0xf bank_mask:0xf
	v_add_f32_dpp v104, v104, v104 row_half_mirror row_mask:0xf bank_mask:0xf
	v_add_f32_dpp v105, v105, v105 row_half_mirror row_mask:0xf bank_mask:0xf
	v_add_f32_dpp v106, v106, v106 row_half_mirror row_mask:0xf bank_mask:0xf
	v_add_f32_dpp v107, v107, v107 row_half_mirror row_mask:0xf bank_mask:0xf
	v_add_f32_dpp v104, v104, v104 row_mirror row_mask:0xf bank_mask:0xf
	v_add_f32_dpp v105, v105, v105 row_mirror row_mask:0xf bank_mask:0xf
	v_add_f32_dpp v106, v106, v106 row_mirror row_mask:0xf bank_mask:0xf
	v_add_f32_dpp v107, v107, v107 row_mirror row_mask:0xf bank_mask:0xf
	v_add_f32_dpp v104, v104, v104 row_bcast:15 row_mask:0xa bank_mask:0xf
	v_add_f32_dpp v105, v105, v105 row_bcast:15 row_mask:0xa bank_mask:0xf
	v_add_f32_dpp v106, v106, v106 row_bcast:15 row_mask:0xa bank_mask:0xf
	v_add_f32_dpp v107, v107, v107 row_bcast:15 row_mask:0xa bank_mask:0xf
	v_add_f32_dpp v104, v104, v104 row_bcast:31 row_mask:0xc bank_mask:0xf
	v_add_f32_dpp v105, v105, v105 row_bcast:31 row_mask:0xc bank_mask:0xf
	v_add_f32_dpp v106, v106, v106 row_bcast:31 row_mask:0xc bank_mask:0xf
	v_add_f32_dpp v107, v107, v107 row_bcast:31 row_mask:0xc bank_mask:0xf
	v_readlane_b32 s24, v104, 63
	v_readlane_b32 s25, v105, 63
	v_readlane_b32 s26, v106, 63
	v_readlane_b32 s27, v107, 63
	s_nop 0
	v_mul_f32_e32 v108, s24, v7
	v_mul_f32_e32 v109, s25, v7
	v_mul_f32_e32 v110, s26, v7
	v_mul_f32_e32 v111, s27, v7
	v_sub_f32_e32 v72, v72, v108
	v_sub_f32_e32 v73, v73, v108
	v_sub_f32_e32 v74, v74, v108
	v_sub_f32_e32 v75, v75, v108
	v_sub_f32_e32 v76, v76, v108
	v_sub_f32_e32 v77, v77, v108
	v_sub_f32_e32 v78, v78, v108
	v_sub_f32_e32 v79, v79, v108
	v_sub_f32_e32 v80, v80, v109
	v_sub_f32_e32 v81, v81, v109
	v_sub_f32_e32 v82, v82, v109
	v_sub_f32_e32 v83, v83, v109
	v_sub_f32_e32 v84, v84, v109
	v_sub_f32_e32 v85, v85, v109
	v_sub_f32_e32 v86, v86, v109
	v_sub_f32_e32 v87, v87, v109
	v_sub_f32_e32 v88, v88, v110
	v_sub_f32_e32 v89, v89, v110
	v_sub_f32_e32 v90, v90, v110
	v_sub_f32_e32 v91, v91, v110
	v_sub_f32_e32 v92, v92, v110
	v_sub_f32_e32 v93, v93, v110
	v_sub_f32_e32 v94, v94, v110
	v_sub_f32_e32 v95, v95, v110
	v_sub_f32_e32 v96, v96, v111
	v_sub_f32_e32 v97, v97, v111
	v_sub_f32_e32 v98, v98, v111
	v_sub_f32_e32 v99, v99, v111
	v_sub_f32_e32 v100, v100, v111
	v_sub_f32_e32 v101, v101, v111
	v_sub_f32_e32 v102, v102, v111
	v_sub_f32_e32 v103, v103, v111
	v_mul_f32_e32 v104, v72, v72
	v_fmac_f32_e32 v104, v73, v73
	v_fmac_f32_e32 v104, v74, v74
	v_fmac_f32_e32 v104, v75, v75
	v_fmac_f32_e32 v104, v76, v76
	v_fmac_f32_e32 v104, v77, v77
	v_fmac_f32_e32 v104, v78, v78
	v_fmac_f32_e32 v104, v79, v79
	v_mul_f32_e32 v105, v80, v80
	v_fmac_f32_e32 v105, v81, v81
	v_fmac_f32_e32 v105, v82, v82
	v_fmac_f32_e32 v105, v83, v83
	v_fmac_f32_e32 v105, v84, v84
	v_fmac_f32_e32 v105, v85, v85
	v_fmac_f32_e32 v105, v86, v86
	v_fmac_f32_e32 v105, v87, v87
	v_mul_f32_e32 v106, v88, v88
	v_fmac_f32_e32 v106, v89, v89
	v_fmac_f32_e32 v106, v90, v90
	v_fmac_f32_e32 v106, v91, v91
	v_fmac_f32_e32 v106, v92, v92
	v_fmac_f32_e32 v106, v93, v93
	v_fmac_f32_e32 v106, v94, v94
	v_fmac_f32_e32 v106, v95, v95
	v_mul_f32_e32 v107, v96, v96
	v_fmac_f32_e32 v107, v97, v97
	v_fmac_f32_e32 v107, v98, v98
	v_fmac_f32_e32 v107, v99, v99
	v_fmac_f32_e32 v107, v100, v100
	v_fmac_f32_e32 v107, v101, v101
	v_fmac_f32_e32 v107, v102, v102
	v_fmac_f32_e32 v107, v103, v103
	v_add_f32_dpp v104, v104, v104 quad_perm:[1,0,3,2] row_mask:0xf bank_mask:0xf
	v_add_f32_dpp v105, v105, v105 quad_perm:[1,0,3,2] row_mask:0xf bank_mask:0xf
	v_add_f32_dpp v106, v106, v106 quad_perm:[1,0,3,2] row_mask:0xf bank_mask:0xf
	v_add_f32_dpp v107, v107, v107 quad_perm:[1,0,3,2] row_mask:0xf bank_mask:0xf
	v_add_f32_dpp v104, v104, v104 quad_perm:[2,3,0,1] row_mask:0xf bank_mask:0xf
	v_add_f32_dpp v105, v105, v105 quad_perm:[2,3,0,1] row_mask:0xf bank_mask:0xf
	v_add_f32_dpp v106, v106, v106 quad_perm:[2,3,0,1] row_mask:0xf bank_mask:0xf
	v_add_f32_dpp v107, v107, v107 quad_perm:[2,3,0,1] row_mask:0xf bank_mask:0xf
	v_add_f32_dpp v104, v104, v104 row_half_mirror row_mask:0xf bank_mask:0xf
	v_add_f32_dpp v105, v105, v105 row_half_mirror row_mask:0xf bank_mask:0xf
	v_add_f32_dpp v106, v106, v106 row_half_mirror row_mask:0xf bank_mask:0xf
	v_add_f32_dpp v107, v107, v107 row_half_mirror row_mask:0xf bank_mask:0xf
	v_add_f32_dpp v104, v104, v104 row_mirror row_mask:0xf bank_mask:0xf
	v_add_f32_dpp v105, v105, v105 row_mirror row_mask:0xf bank_mask:0xf
	v_add_f32_dpp v106, v106, v106 row_mirror row_mask:0xf bank_mask:0xf
	v_add_f32_dpp v107, v107, v107 row_mirror row_mask:0xf bank_mask:0xf
	v_add_f32_dpp v104, v104, v104 row_bcast:15 row_mask:0xa bank_mask:0xf
	v_add_f32_dpp v105, v105, v105 row_bcast:15 row_mask:0xa bank_mask:0xf
	v_add_f32_dpp v106, v106, v106 row_bcast:15 row_mask:0xa bank_mask:0xf
	v_add_f32_dpp v107, v107, v107 row_bcast:15 row_mask:0xa bank_mask:0xf
	v_add_f32_dpp v104, v104, v104 row_bcast:31 row_mask:0xc bank_mask:0xf
	v_add_f32_dpp v105, v105, v105 row_bcast:31 row_mask:0xc bank_mask:0xf
	v_add_f32_dpp v106, v106, v106 row_bcast:31 row_mask:0xc bank_mask:0xf
	v_add_f32_dpp v107, v107, v107 row_bcast:31 row_mask:0xc bank_mask:0xf
	v_readlane_b32 s24, v104, 63
	v_readlane_b32 s25, v105, 63
	v_readlane_b32 s26, v106, 63
	v_readlane_b32 s27, v107, 63
	s_nop 0
	v_fma_f32 v108, s24, v7, v132
	v_fma_f32 v109, s25, v7, v132
	v_fma_f32 v110, s26, v7, v132
	v_fma_f32 v111, s27, v7, v132
	v_rsq_f32_e32 v108, v108
	v_rsq_f32_e32 v109, v109
	v_rsq_f32_e32 v110, v110
	v_rsq_f32_e32 v111, v111
	s_nop 0
	v_mul_f32_e32 v72, v72, v108
	v_mul_f32_e32 v73, v73, v108
	v_mul_f32_e32 v74, v74, v108
	v_mul_f32_e32 v75, v75, v108
	v_mul_f32_e32 v76, v76, v108
	v_mul_f32_e32 v77, v77, v108
	v_mul_f32_e32 v78, v78, v108
	v_mul_f32_e32 v79, v79, v108
	v_fma_f32 v72, v72, v112, v120
	v_fma_f32 v73, v73, v113, v121
	v_fma_f32 v74, v74, v114, v122
	v_fma_f32 v75, v75, v115, v123
	v_fma_f32 v76, v76, v116, v124
	v_fma_f32 v77, v77, v117, v125
	v_fma_f32 v78, v78, v118, v126
	v_fma_f32 v79, v79, v119, v127
	v_mul_f32_e32 v80, v80, v109
	v_mul_f32_e32 v81, v81, v109
	v_mul_f32_e32 v82, v82, v109
	v_mul_f32_e32 v83, v83, v109
	v_mul_f32_e32 v84, v84, v109
	v_mul_f32_e32 v85, v85, v109
	v_mul_f32_e32 v86, v86, v109
	v_mul_f32_e32 v87, v87, v109
	v_fma_f32 v80, v80, v112, v120
	v_fma_f32 v81, v81, v113, v121
	v_fma_f32 v82, v82, v114, v122
	v_fma_f32 v83, v83, v115, v123
	v_fma_f32 v84, v84, v116, v124
	v_fma_f32 v85, v85, v117, v125
	v_fma_f32 v86, v86, v118, v126
	v_fma_f32 v87, v87, v119, v127
	v_mul_f32_e32 v88, v88, v110
	v_mul_f32_e32 v89, v89, v110
	v_mul_f32_e32 v90, v90, v110
	v_mul_f32_e32 v91, v91, v110
	v_mul_f32_e32 v92, v92, v110
	v_mul_f32_e32 v93, v93, v110
	v_mul_f32_e32 v94, v94, v110
	v_mul_f32_e32 v95, v95, v110
	v_fma_f32 v88, v88, v112, v120
	v_fma_f32 v89, v89, v113, v121
	v_fma_f32 v90, v90, v114, v122
	v_fma_f32 v91, v91, v115, v123
	v_fma_f32 v92, v92, v116, v124
	v_fma_f32 v93, v93, v117, v125
	v_fma_f32 v94, v94, v118, v126
	v_fma_f32 v95, v95, v119, v127
	v_mul_f32_e32 v96, v96, v111
	v_mul_f32_e32 v97, v97, v111
	v_mul_f32_e32 v98, v98, v111
	v_mul_f32_e32 v99, v99, v111
	v_mul_f32_e32 v100, v100, v111
	v_mul_f32_e32 v101, v101, v111
	v_mul_f32_e32 v102, v102, v111
	v_mul_f32_e32 v103, v103, v111
	v_fma_f32 v96, v96, v112, v120
	v_fma_f32 v97, v97, v113, v121
	v_fma_f32 v98, v98, v114, v122
	v_fma_f32 v99, v99, v115, v123
	v_fma_f32 v100, v100, v116, v124
	v_fma_f32 v101, v101, v117, v125
	v_fma_f32 v102, v102, v118, v126
	v_fma_f32 v103, v103, v119, v127
	v_cvt_pk_bf16_f32 v56, v72, v73
	v_cvt_pk_bf16_f32 v57, v74, v75
	v_cvt_pk_bf16_f32 v58, v76, v77
	v_cvt_pk_bf16_f32 v59, v78, v79
	v_cvt_pk_bf16_f32 v60, v80, v81
	v_cvt_pk_bf16_f32 v61, v82, v83
	v_cvt_pk_bf16_f32 v62, v84, v85
	v_cvt_pk_bf16_f32 v63, v86, v87
	v_cvt_pk_bf16_f32 v64, v88, v89
	v_cvt_pk_bf16_f32 v65, v90, v91
	v_cvt_pk_bf16_f32 v66, v92, v93
	v_cvt_pk_bf16_f32 v67, v94, v95
	v_cvt_pk_bf16_f32 v68, v96, v97
	v_cvt_pk_bf16_f32 v69, v98, v99
	v_cvt_pk_bf16_f32 v70, v100, v101
	v_cvt_pk_bf16_f32 v71, v102, v103
	ds_write_b128 v128, v[56:59] offset:12288
	ds_write_b128 v129, v[60:63] offset:13312
	ds_write_b128 v130, v[64:67] offset:14336
	ds_write_b128 v131, v[68:71] offset:15360
	s_waitcnt lgkmcnt(0)
	s_mov_b64 s[34:35], s[32:33]
	s_add_u32 s36, s32, 0x2000
	s_addc_u32 s37, s33, 0
	global_load_dwordx4 v[8:11], v137, s[34:35] offset:0
	global_load_dwordx4 v[12:15], v137, s[34:35] offset:32
	s_add_u32 s34, s34, 0x4000
	s_addc_u32 s35, s35, 0
	global_load_dwordx4 v[16:19], v137, s[36:37] offset:0
	global_load_dwordx4 v[20:23], v137, s[36:37] offset:32
	global_load_dwordx4 v[24:27], v137, s[36:37] offset:64
	global_load_dwordx4 v[28:31], v137, s[36:37] offset:96
	s_add_u32 s36, s36, 0x4000
	s_addc_u32 s37, s37, 0
	global_load_dwordx4 v[32:35], v137, s[34:35] offset:0
	global_load_dwordx4 v[36:39], v137, s[34:35] offset:32
	global_load_dwordx4 v[40:43], v137, s[34:35] offset:64
	global_load_dwordx4 v[44:47], v137, s[34:35] offset:96
	global_load_dwordx4 v[48:51], v137, s[34:35] offset:128
	global_load_dwordx4 v[52:55], v137, s[34:35] offset:160
	global_load_dwordx4 v[56:59], v137, s[36:37] offset:0
	global_load_dwordx4 v[60:63], v137, s[36:37] offset:32
	global_load_dwordx4 v[64:67], v137, s[36:37] offset:64
	global_load_dwordx4 v[68:71], v137, s[36:37] offset:96
	global_load_dwordx4 v[72:75], v137, s[36:37] offset:128
	global_load_dwordx4 v[76:79], v137, s[36:37] offset:160
	global_load_dwordx4 v[80:83], v137, s[36:37] offset:192
	global_load_dwordx4 v[84:87], v137, s[36:37] offset:224
	global_load_dword v88, v140, s[44:45] offset:0
	global_load_dword v89, v140, s[44:45] offset:128
	global_load_dword v90, v140, s[44:45] offset:256
	global_load_dword v91, v140, s[44:45] offset:384
	s_lshl_b32 s4, s1, 18
	s_lshl_b32 s5, s0, 7
	s_add_i32 s5, s5, 0x400
	s_add_u32 s38, s30, s4
	s_addc_u32 s39, s31, 0
	s_add_u32 s38, s38, s5
	s_addc_u32 s39, s39, 0
	s_add_u32 s46, s38, 0x10000
	s_addc_u32 s47, s39, 0
	s_add_u32 s54, s38, 0x20000
	s_addc_u32 s55, s39, 0
	s_add_u32 s56, s38, 0x30000
	s_addc_u32 s57, s39, 0
	s_barrier
	ds_read_b64_tr_b16 v[208:209], v133 offset:0
	ds_read_b64_tr_b16 v[210:211], v133 offset:4096
	ds_read_b64_tr_b16 v[212:213], v133 offset:16384
	ds_read_b64_tr_b16 v[214:215], v133 offset:20480
	ds_read_b64_tr_b16 v[216:217], v133 offset:32768
	ds_read_b64_tr_b16 v[218:219], v133 offset:36864
	ds_read_b64_tr_b16 v[220:221], v133 offset:49152
	ds_read_b64_tr_b16 v[222:223], v133 offset:53248
	ds_read_b64_tr_b16 v[224:225], v134 offset:0
	ds_read_b64_tr_b16 v[226:227], v134 offset:4096
	ds_read_b64_tr_b16 v[228:229], v134 offset:16384
	ds_read_b64_tr_b16 v[230:231], v134 offset:20480
	ds_read_b64_tr_b16 v[232:233], v134 offset:32768
	ds_read_b64_tr_b16 v[234:235], v134 offset:36864
	ds_read_b64_tr_b16 v[236:237], v134 offset:49152
	ds_read_b64_tr_b16 v[238:239], v134 offset:53248
	s_waitcnt vmcnt(0) lgkmcnt(0)
	v_mfma_f32_32x32x16_bf16 v[112:127], v[208:211], v[8:11], 0
	v_mfma_f32_32x32x16_bf16 v[112:127], v[212:215], v[12:15], v[112:127]
	s_nop 7
	s_nop 7
	v_permlane32_swap_b32 v144, v146
	v_permlane32_swap_b32 v145, v147
	v_permlane32_swap_b32 v148, v150
	v_permlane32_swap_b32 v149, v151
	v_add_f32_e32 v112, v112, v88
	v_add_f32_e32 v113, v113, v88
	v_add_f32_e32 v114, v114, v88
	v_add_f32_e32 v115, v115, v88
	v_add_f32_e32 v116, v116, v88
	v_add_f32_e32 v117, v117, v88
	v_add_f32_e32 v118, v118, v88
	v_add_f32_e32 v119, v119, v88
	v_add_f32_e32 v120, v120, v88
	v_add_f32_e32 v121, v121, v88
	v_add_f32_e32 v122, v122, v88
	v_add_f32_e32 v123, v123, v88
	v_add_f32_e32 v124, v124, v88
	v_add_f32_e32 v125, v125, v88
	v_add_f32_e32 v126, v126, v88
	v_add_f32_e32 v127, v127, v88
	v_lshlrev_b32_e32 v4, 16, v144
	v_mul_f32_e32 v112, v112, v4
	v_and_b32_e32 v4, 0xffff0000, v144
	v_mul_f32_e32 v113, v113, v4
	v_lshlrev_b32_e32 v4, 16, v145
	v_mul_f32_e32 v114, v114, v4
	v_and_b32_e32 v4, 0xffff0000, v145
	v_mul_f32_e32 v115, v115, v4
	v_cvt_pk_bf16_f32 v104, v112, v113
	v_cvt_pk_bf16_f32 v105, v114, v115
	v_lshlrev_b32_e32 v4, 16, v146
	v_mul_f32_e32 v116, v116, v4
	v_and_b32_e32 v4, 0xffff0000, v146
	v_mul_f32_e32 v117, v117, v4
	v_lshlrev_b32_e32 v4, 16, v147
	v_mul_f32_e32 v118, v118, v4
	v_and_b32_e32 v4, 0xffff0000, v147
	v_mul_f32_e32 v119, v119, v4
	v_cvt_pk_bf16_f32 v106, v116, v117
	v_cvt_pk_bf16_f32 v107, v118, v119
	v_lshlrev_b32_e32 v4, 16, v148
	v_mul_f32_e32 v120, v120, v4
	v_and_b32_e32 v4, 0xffff0000, v148
	v_mul_f32_e32 v121, v121, v4
	v_lshlrev_b32_e32 v4, 16, v149
	v_mul_f32_e32 v122, v122, v4
	v_and_b32_e32 v4, 0xffff0000, v149
	v_mul_f32_e32 v123, v123, v4
	v_cvt_pk_bf16_f32 v108, v120, v121
	v_cvt_pk_bf16_f32 v109, v122, v123
	v_lshlrev_b32_e32 v4, 16, v150
	v_mul_f32_e32 v124, v124, v4
	v_and_b32_e32 v4, 0xffff0000, v150
	v_mul_f32_e32 v125, v125, v4
	v_lshlrev_b32_e32 v4, 16, v151
	v_mul_f32_e32 v126, v126, v4
	v_and_b32_e32 v4, 0xffff0000, v151
	v_mul_f32_e32 v127, v127, v4
	v_cvt_pk_bf16_f32 v110, v124, v125
	v_cvt_pk_bf16_f32 v111, v126, v127
	s_nop 1
	v_permlane32_swap_b32 v104, v106
	v_permlane32_swap_b32 v105, v107
	v_permlane32_swap_b32 v108, v110
	v_permlane32_swap_b32 v109, v111
	global_store_dwordx4 v139, v[104:107], s[38:39] offset:0
	global_store_dwordx4 v139, v[108:111], s[38:39] offset:32
	v_mfma_f32_32x32x16_bf16 v[112:127], v[208:211], v[16:19], 0
	v_mfma_f32_32x32x16_bf16 v[112:127], v[212:215], v[20:23], v[112:127]
	v_mfma_f32_32x32x16_bf16 v[112:127], v[216:219], v[24:27], v[112:127]
	v_mfma_f32_32x32x16_bf16 v[112:127], v[220:223], v[28:31], v[112:127]
	s_nop 7
	s_nop 7
	v_permlane32_swap_b32 v160, v162
	v_permlane32_swap_b32 v161, v163
	v_permlane32_swap_b32 v164, v166
	v_permlane32_swap_b32 v165, v167
	v_add_f32_e32 v112, v112, v89
	v_add_f32_e32 v113, v113, v89
	v_add_f32_e32 v114, v114, v89
	v_add_f32_e32 v115, v115, v89
	v_add_f32_e32 v116, v116, v89
	v_add_f32_e32 v117, v117, v89
	v_add_f32_e32 v118, v118, v89
	v_add_f32_e32 v119, v119, v89
	v_add_f32_e32 v120, v120, v89
	v_add_f32_e32 v121, v121, v89
	v_add_f32_e32 v122, v122, v89
	v_add_f32_e32 v123, v123, v89
	v_add_f32_e32 v124, v124, v89
	v_add_f32_e32 v125, v125, v89
	v_add_f32_e32 v126, v126, v89
	v_add_f32_e32 v127, v127, v89
	v_lshlrev_b32_e32 v4, 16, v160
	v_mul_f32_e32 v112, v112, v4
	v_and_b32_e32 v4, 0xffff0000, v160
	v_mul_f32_e32 v113, v113, v4
	v_lshlrev_b32_e32 v4, 16, v161
	v_mul_f32_e32 v114, v114, v4
	v_and_b32_e32 v4, 0xffff0000, v161
	v_mul_f32_e32 v115, v115, v4
	v_cvt_pk_bf16_f32 v104, v112, v113
	v_cvt_pk_bf16_f32 v105, v114, v115
	v_lshlrev_b32_e32 v4, 16, v162
	v_mul_f32_e32 v116, v116, v4
	v_and_b32_e32 v4, 0xffff0000, v162
	v_mul_f32_e32 v117, v117, v4
	v_lshlrev_b32_e32 v4, 16, v163
	v_mul_f32_e32 v118, v118, v4
	v_and_b32_e32 v4, 0xffff0000, v163
	v_mul_f32_e32 v119, v119, v4
	v_cvt_pk_bf16_f32 v106, v116, v117
	v_cvt_pk_bf16_f32 v107, v118, v119
	v_lshlrev_b32_e32 v4, 16, v164
	v_mul_f32_e32 v120, v120, v4
	v_and_b32_e32 v4, 0xffff0000, v164
	v_mul_f32_e32 v121, v121, v4
	v_lshlrev_b32_e32 v4, 16, v165
	v_mul_f32_e32 v122, v122, v4
	v_and_b32_e32 v4, 0xffff0000, v165
	v_mul_f32_e32 v123, v123, v4
	v_cvt_pk_bf16_f32 v108, v120, v121
	v_cvt_pk_bf16_f32 v109, v122, v123
	v_lshlrev_b32_e32 v4, 16, v166
	v_mul_f32_e32 v124, v124, v4
	v_and_b32_e32 v4, 0xffff0000, v166
	v_mul_f32_e32 v125, v125, v4
	v_lshlrev_b32_e32 v4, 16, v167
	v_mul_f32_e32 v126, v126, v4
	v_and_b32_e32 v4, 0xffff0000, v167
	v_mul_f32_e32 v127, v127, v4
	v_cvt_pk_bf16_f32 v110, v124, v125
	v_cvt_pk_bf16_f32 v111, v126, v127
	s_nop 1
	v_permlane32_swap_b32 v104, v106
	v_permlane32_swap_b32 v105, v107
	v_permlane32_swap_b32 v108, v110
	v_permlane32_swap_b32 v109, v111
	global_store_dwordx4 v139, v[104:107], s[46:47] offset:0
	global_store_dwordx4 v139, v[108:111], s[46:47] offset:32
	v_mfma_f32_32x32x16_bf16 v[112:127], v[208:211], v[32:35], 0
	v_mfma_f32_32x32x16_bf16 v[112:127], v[212:215], v[36:39], v[112:127]
	v_mfma_f32_32x32x16_bf16 v[112:127], v[216:219], v[40:43], v[112:127]
	v_mfma_f32_32x32x16_bf16 v[112:127], v[220:223], v[44:47], v[112:127]
	v_mfma_f32_32x32x16_bf16 v[112:127], v[224:227], v[48:51], v[112:127]
	v_mfma_f32_32x32x16_bf16 v[112:127], v[228:231], v[52:55], v[112:127]
	s_nop 7
	s_nop 7
	v_permlane32_swap_b32 v176, v178
	v_permlane32_swap_b32 v177, v179
	v_permlane32_swap_b32 v184, v186
	v_permlane32_swap_b32 v185, v187
	v_add_f32_e32 v112, v112, v90
	v_add_f32_e32 v113, v113, v90
	v_add_f32_e32 v114, v114, v90
	v_add_f32_e32 v115, v115, v90
	v_add_f32_e32 v116, v116, v90
	v_add_f32_e32 v117, v117, v90
	v_add_f32_e32 v118, v118, v90
	v_add_f32_e32 v119, v119, v90
	v_add_f32_e32 v120, v120, v90
	v_add_f32_e32 v121, v121, v90
	v_add_f32_e32 v122, v122, v90
	v_add_f32_e32 v123, v123, v90
	v_add_f32_e32 v124, v124, v90
	v_add_f32_e32 v125, v125, v90
	v_add_f32_e32 v126, v126, v90
	v_add_f32_e32 v127, v127, v90
	v_lshlrev_b32_e32 v4, 16, v176
	v_mul_f32_e32 v112, v112, v4
	v_and_b32_e32 v4, 0xffff0000, v176
	v_mul_f32_e32 v113, v113, v4
	v_lshlrev_b32_e32 v4, 16, v177
	v_mul_f32_e32 v114, v114, v4
	v_and_b32_e32 v4, 0xffff0000, v177
	v_mul_f32_e32 v115, v115, v4
	v_cvt_pk_bf16_f32 v104, v112, v113
	v_cvt_pk_bf16_f32 v105, v114, v115
	v_lshlrev_b32_e32 v4, 16, v178
	v_mul_f32_e32 v116, v116, v4
	v_and_b32_e32 v4, 0xffff0000, v178
	v_mul_f32_e32 v117, v117, v4
	v_lshlrev_b32_e32 v4, 16, v179
	v_mul_f32_e32 v118, v118, v4
	v_and_b32_e32 v4, 0xffff0000, v179
	v_mul_f32_e32 v119, v119, v4
	v_cvt_pk_bf16_f32 v106, v116, v117
	v_cvt_pk_bf16_f32 v107, v118, v119
	v_lshlrev_b32_e32 v4, 16, v184
	v_mul_f32_e32 v120, v120, v4
	v_and_b32_e32 v4, 0xffff0000, v184
	v_mul_f32_e32 v121, v121, v4
	v_lshlrev_b32_e32 v4, 16, v185
	v_mul_f32_e32 v122, v122, v4
	v_and_b32_e32 v4, 0xffff0000, v185
	v_mul_f32_e32 v123, v123, v4
	v_cvt_pk_bf16_f32 v108, v120, v121
	v_cvt_pk_bf16_f32 v109, v122, v123
	v_lshlrev_b32_e32 v4, 16, v186
	v_mul_f32_e32 v124, v124, v4
	v_and_b32_e32 v4, 0xffff0000, v186
	v_mul_f32_e32 v125, v125, v4
	v_lshlrev_b32_e32 v4, 16, v187
	v_mul_f32_e32 v126, v126, v4
	v_and_b32_e32 v4, 0xffff0000, v187
	v_mul_f32_e32 v127, v127, v4
	v_cvt_pk_bf16_f32 v110, v124, v125
	v_cvt_pk_bf16_f32 v111, v126, v127
	s_nop 1
	v_permlane32_swap_b32 v104, v106
	v_permlane32_swap_b32 v105, v107
	v_permlane32_swap_b32 v108, v110
	v_permlane32_swap_b32 v109, v111
	global_store_dwordx4 v139, v[104:107], s[54:55] offset:0
	global_store_dwordx4 v139, v[108:111], s[54:55] offset:32
	v_mfma_f32_32x32x16_bf16 v[112:127], v[208:211], v[56:59], 0
	v_mfma_f32_32x32x16_bf16 v[112:127], v[212:215], v[60:63], v[112:127]
	v_mfma_f32_32x32x16_bf16 v[112:127], v[216:219], v[64:67], v[112:127]
	v_mfma_f32_32x32x16_bf16 v[112:127], v[220:223], v[68:71], v[112:127]
	v_mfma_f32_32x32x16_bf16 v[112:127], v[224:227], v[72:75], v[112:127]
	v_mfma_f32_32x32x16_bf16 v[112:127], v[228:231], v[76:79], v[112:127]
	v_mfma_f32_32x32x16_bf16 v[112:127], v[232:235], v[80:83], v[112:127]
	v_mfma_f32_32x32x16_bf16 v[112:127], v[236:239], v[84:87], v[112:127]
	s_nop 7
	s_nop 7
	v_permlane32_swap_b32 v196, v198
	v_permlane32_swap_b32 v197, v199
	v_permlane32_swap_b32 v200, v202
	v_permlane32_swap_b32 v201, v203
	v_add_f32_e32 v112, v112, v91
	v_add_f32_e32 v113, v113, v91
	v_add_f32_e32 v114, v114, v91
	v_add_f32_e32 v115, v115, v91
	v_add_f32_e32 v116, v116, v91
	v_add_f32_e32 v117, v117, v91
	v_add_f32_e32 v118, v118, v91
	v_add_f32_e32 v119, v119, v91
	v_add_f32_e32 v120, v120, v91
	v_add_f32_e32 v121, v121, v91
	v_add_f32_e32 v122, v122, v91
	v_add_f32_e32 v123, v123, v91
	v_add_f32_e32 v124, v124, v91
	v_add_f32_e32 v125, v125, v91
	v_add_f32_e32 v126, v126, v91
	v_add_f32_e32 v127, v127, v91
	v_lshlrev_b32_e32 v4, 16, v196
	v_mul_f32_e32 v112, v112, v4
	v_and_b32_e32 v4, 0xffff0000, v196
	v_mul_f32_e32 v113, v113, v4
	v_lshlrev_b32_e32 v4, 16, v197
	v_mul_f32_e32 v114, v114, v4
	v_and_b32_e32 v4, 0xffff0000, v197
	v_mul_f32_e32 v115, v115, v4
	v_cvt_pk_bf16_f32 v104, v112, v113
	v_cvt_pk_bf16_f32 v105, v114, v115
	v_lshlrev_b32_e32 v4, 16, v198
	v_mul_f32_e32 v116, v116, v4
	v_and_b32_e32 v4, 0xffff0000, v198
	v_mul_f32_e32 v117, v117, v4
	v_lshlrev_b32_e32 v4, 16, v199
	v_mul_f32_e32 v118, v118, v4
	v_and_b32_e32 v4, 0xffff0000, v199
	v_mul_f32_e32 v119, v119, v4
	v_cvt_pk_bf16_f32 v106, v116, v117
	v_cvt_pk_bf16_f32 v107, v118, v119
	v_lshlrev_b32_e32 v4, 16, v200
	v_mul_f32_e32 v120, v120, v4
	v_and_b32_e32 v4, 0xffff0000, v200
	v_mul_f32_e32 v121, v121, v4
	v_lshlrev_b32_e32 v4, 16, v201
	v_mul_f32_e32 v122, v122, v4
	v_and_b32_e32 v4, 0xffff0000, v201
	v_mul_f32_e32 v123, v123, v4
	v_cvt_pk_bf16_f32 v108, v120, v121
	v_cvt_pk_bf16_f32 v109, v122, v123
	v_lshlrev_b32_e32 v4, 16, v202
	v_mul_f32_e32 v124, v124, v4
	v_and_b32_e32 v4, 0xffff0000, v202
	v_mul_f32_e32 v125, v125, v4
	v_lshlrev_b32_e32 v4, 16, v203
	v_mul_f32_e32 v126, v126, v4
	v_and_b32_e32 v4, 0xffff0000, v203
	v_mul_f32_e32 v127, v127, v4
	v_cvt_pk_bf16_f32 v110, v124, v125
	v_cvt_pk_bf16_f32 v111, v126, v127
	s_nop 1
	v_permlane32_swap_b32 v104, v106
	v_permlane32_swap_b32 v105, v107
	v_permlane32_swap_b32 v108, v110
	v_permlane32_swap_b32 v109, v111
	global_store_dwordx4 v139, v[104:107], s[56:57] offset:0
	global_store_dwordx4 v139, v[108:111], s[56:57] offset:32
	ds_read_b64_tr_b16 v[208:209], v135 offset:0
	ds_read_b64_tr_b16 v[210:211], v135 offset:4096
	ds_read_b64_tr_b16 v[212:213], v135 offset:16384
	ds_read_b64_tr_b16 v[214:215], v135 offset:20480
	ds_read_b64_tr_b16 v[216:217], v135 offset:32768
	ds_read_b64_tr_b16 v[218:219], v135 offset:36864
	ds_read_b64_tr_b16 v[220:221], v135 offset:49152
	ds_read_b64_tr_b16 v[222:223], v135 offset:53248
	ds_read_b64_tr_b16 v[224:225], v136 offset:0
	ds_read_b64_tr_b16 v[226:227], v136 offset:4096
	ds_read_b64_tr_b16 v[228:229], v136 offset:16384
	ds_read_b64_tr_b16 v[230:231], v136 offset:20480
	ds_read_b64_tr_b16 v[232:233], v136 offset:32768
	ds_read_b64_tr_b16 v[234:235], v136 offset:36864
	ds_read_b64_tr_b16 v[236:237], v136 offset:49152
	ds_read_b64_tr_b16 v[238:239], v136 offset:53248
	s_waitcnt vmcnt(0) lgkmcnt(0)
	v_mfma_f32_32x32x16_bf16 v[112:127], v[208:211], v[8:11], 0
	v_mfma_f32_32x32x16_bf16 v[112:127], v[212:215], v[12:15], v[112:127]
	s_nop 7
	s_nop 7
	v_permlane32_swap_b32 v152, v154
	v_permlane32_swap_b32 v153, v155
	v_permlane32_swap_b32 v156, v158
	v_permlane32_swap_b32 v157, v159
	v_add_f32_e32 v112, v112, v88
	v_add_f32_e32 v113, v113, v88
	v_add_f32_e32 v114, v114, v88
	v_add_f32_e32 v115, v115, v88
	v_add_f32_e32 v116, v116, v88
	v_add_f32_e32 v117, v117, v88
	v_add_f32_e32 v118, v118, v88
	v_add_f32_e32 v119, v119, v88
	v_add_f32_e32 v120, v120, v88
	v_add_f32_e32 v121, v121, v88
	v_add_f32_e32 v122, v122, v88
	v_add_f32_e32 v123, v123, v88
	v_add_f32_e32 v124, v124, v88
	v_add_f32_e32 v125, v125, v88
	v_add_f32_e32 v126, v126, v88
	v_add_f32_e32 v127, v127, v88
	v_lshlrev_b32_e32 v4, 16, v152
	v_mul_f32_e32 v112, v112, v4
	v_and_b32_e32 v4, 0xffff0000, v152
	v_mul_f32_e32 v113, v113, v4
	v_lshlrev_b32_e32 v4, 16, v153
	v_mul_f32_e32 v114, v114, v4
	v_and_b32_e32 v4, 0xffff0000, v153
	v_mul_f32_e32 v115, v115, v4
	v_cvt_pk_bf16_f32 v104, v112, v113
	v_cvt_pk_bf16_f32 v105, v114, v115
	v_lshlrev_b32_e32 v4, 16, v154
	v_mul_f32_e32 v116, v116, v4
	v_and_b32_e32 v4, 0xffff0000, v154
	v_mul_f32_e32 v117, v117, v4
	v_lshlrev_b32_e32 v4, 16, v155
	v_mul_f32_e32 v118, v118, v4
	v_and_b32_e32 v4, 0xffff0000, v155
	v_mul_f32_e32 v119, v119, v4
	v_cvt_pk_bf16_f32 v106, v116, v117
	v_cvt_pk_bf16_f32 v107, v118, v119
	v_lshlrev_b32_e32 v4, 16, v156
	v_mul_f32_e32 v120, v120, v4
	v_and_b32_e32 v4, 0xffff0000, v156
	v_mul_f32_e32 v121, v121, v4
	v_lshlrev_b32_e32 v4, 16, v157
	v_mul_f32_e32 v122, v122, v4
	v_and_b32_e32 v4, 0xffff0000, v157
	v_mul_f32_e32 v123, v123, v4
	v_cvt_pk_bf16_f32 v108, v120, v121
	v_cvt_pk_bf16_f32 v109, v122, v123
	v_lshlrev_b32_e32 v4, 16, v158
	v_mul_f32_e32 v124, v124, v4
	v_and_b32_e32 v4, 0xffff0000, v158
	v_mul_f32_e32 v125, v125, v4
	v_lshlrev_b32_e32 v4, 16, v159
	v_mul_f32_e32 v126, v126, v4
	v_and_b32_e32 v4, 0xffff0000, v159
	v_mul_f32_e32 v127, v127, v4
	v_cvt_pk_bf16_f32 v110, v124, v125
	v_cvt_pk_bf16_f32 v111, v126, v127
	s_nop 1
	v_permlane32_swap_b32 v104, v106
	v_permlane32_swap_b32 v105, v107
	v_permlane32_swap_b32 v108, v110
	v_permlane32_swap_b32 v109, v111
	global_store_dwordx4 v139, v[104:107], s[38:39] offset:64
	global_store_dwordx4 v139, v[108:111], s[38:39] offset:96
	v_mfma_f32_32x32x16_bf16 v[112:127], v[208:211], v[16:19], 0
	v_mfma_f32_32x32x16_bf16 v[112:127], v[212:215], v[20:23], v[112:127]
	v_mfma_f32_32x32x16_bf16 v[112:127], v[216:219], v[24:27], v[112:127]
	v_mfma_f32_32x32x16_bf16 v[112:127], v[220:223], v[28:31], v[112:127]
	s_nop 7
	s_nop 7
	v_permlane32_swap_b32 v168, v170
	v_permlane32_swap_b32 v169, v171
	v_permlane32_swap_b32 v172, v174
	v_permlane32_swap_b32 v173, v175
	v_add_f32_e32 v112, v112, v89
	v_add_f32_e32 v113, v113, v89
	v_add_f32_e32 v114, v114, v89
	v_add_f32_e32 v115, v115, v89
	v_add_f32_e32 v116, v116, v89
	v_add_f32_e32 v117, v117, v89
	v_add_f32_e32 v118, v118, v89
	v_add_f32_e32 v119, v119, v89
	v_add_f32_e32 v120, v120, v89
	v_add_f32_e32 v121, v121, v89
	v_add_f32_e32 v122, v122, v89
	v_add_f32_e32 v123, v123, v89
	v_add_f32_e32 v124, v124, v89
	v_add_f32_e32 v125, v125, v89
	v_add_f32_e32 v126, v126, v89
	v_add_f32_e32 v127, v127, v89
	v_lshlrev_b32_e32 v4, 16, v168
	v_mul_f32_e32 v112, v112, v4
	v_and_b32_e32 v4, 0xffff0000, v168
	v_mul_f32_e32 v113, v113, v4
	v_lshlrev_b32_e32 v4, 16, v169
	v_mul_f32_e32 v114, v114, v4
	v_and_b32_e32 v4, 0xffff0000, v169
	v_mul_f32_e32 v115, v115, v4
	v_cvt_pk_bf16_f32 v104, v112, v113
	v_cvt_pk_bf16_f32 v105, v114, v115
	v_lshlrev_b32_e32 v4, 16, v170
	v_mul_f32_e32 v116, v116, v4
	v_and_b32_e32 v4, 0xffff0000, v170
	v_mul_f32_e32 v117, v117, v4
	v_lshlrev_b32_e32 v4, 16, v171
	v_mul_f32_e32 v118, v118, v4
	v_and_b32_e32 v4, 0xffff0000, v171
	v_mul_f32_e32 v119, v119, v4
	v_cvt_pk_bf16_f32 v106, v116, v117
	v_cvt_pk_bf16_f32 v107, v118, v119
	v_lshlrev_b32_e32 v4, 16, v172
	v_mul_f32_e32 v120, v120, v4
	v_and_b32_e32 v4, 0xffff0000, v172
	v_mul_f32_e32 v121, v121, v4
	v_lshlrev_b32_e32 v4, 16, v173
	v_mul_f32_e32 v122, v122, v4
	v_and_b32_e32 v4, 0xffff0000, v173
	v_mul_f32_e32 v123, v123, v4
	v_cvt_pk_bf16_f32 v108, v120, v121
	v_cvt_pk_bf16_f32 v109, v122, v123
	v_lshlrev_b32_e32 v4, 16, v174
	v_mul_f32_e32 v124, v124, v4
	v_and_b32_e32 v4, 0xffff0000, v174
	v_mul_f32_e32 v125, v125, v4
	v_lshlrev_b32_e32 v4, 16, v175
	v_mul_f32_e32 v126, v126, v4
	v_and_b32_e32 v4, 0xffff0000, v175
	v_mul_f32_e32 v127, v127, v4
	v_cvt_pk_bf16_f32 v110, v124, v125
	v_cvt_pk_bf16_f32 v111, v126, v127
	s_nop 1
	v_permlane32_swap_b32 v104, v106
	v_permlane32_swap_b32 v105, v107
	v_permlane32_swap_b32 v108, v110
	v_permlane32_swap_b32 v109, v111
	global_store_dwordx4 v139, v[104:107], s[46:47] offset:64
	global_store_dwordx4 v139, v[108:111], s[46:47] offset:96
	v_mfma_f32_32x32x16_bf16 v[112:127], v[208:211], v[32:35], 0
	v_mfma_f32_32x32x16_bf16 v[112:127], v[212:215], v[36:39], v[112:127]
	v_mfma_f32_32x32x16_bf16 v[112:127], v[216:219], v[40:43], v[112:127]
	v_mfma_f32_32x32x16_bf16 v[112:127], v[220:223], v[44:47], v[112:127]
	v_mfma_f32_32x32x16_bf16 v[112:127], v[224:227], v[48:51], v[112:127]
	v_mfma_f32_32x32x16_bf16 v[112:127], v[228:231], v[52:55], v[112:127]
	s_nop 7
	s_nop 7
	v_permlane32_swap_b32 v188, v190
	v_permlane32_swap_b32 v189, v191
	v_permlane32_swap_b32 v192, v194
	v_permlane32_swap_b32 v193, v195
	v_add_f32_e32 v112, v112, v90
	v_add_f32_e32 v113, v113, v90
	v_add_f32_e32 v114, v114, v90
	v_add_f32_e32 v115, v115, v90
	v_add_f32_e32 v116, v116, v90
	v_add_f32_e32 v117, v117, v90
	v_add_f32_e32 v118, v118, v90
	v_add_f32_e32 v119, v119, v90
	v_add_f32_e32 v120, v120, v90
	v_add_f32_e32 v121, v121, v90
	v_add_f32_e32 v122, v122, v90
	v_add_f32_e32 v123, v123, v90
	v_add_f32_e32 v124, v124, v90
	v_add_f32_e32 v125, v125, v90
	v_add_f32_e32 v126, v126, v90
	v_add_f32_e32 v127, v127, v90
	v_lshlrev_b32_e32 v4, 16, v188
	v_mul_f32_e32 v112, v112, v4
	v_and_b32_e32 v4, 0xffff0000, v188
	v_mul_f32_e32 v113, v113, v4
	v_lshlrev_b32_e32 v4, 16, v189
	v_mul_f32_e32 v114, v114, v4
	v_and_b32_e32 v4, 0xffff0000, v189
	v_mul_f32_e32 v115, v115, v4
	v_cvt_pk_bf16_f32 v104, v112, v113
	v_cvt_pk_bf16_f32 v105, v114, v115
	v_lshlrev_b32_e32 v4, 16, v190
	v_mul_f32_e32 v116, v116, v4
	v_and_b32_e32 v4, 0xffff0000, v190
	v_mul_f32_e32 v117, v117, v4
	v_lshlrev_b32_e32 v4, 16, v191
	v_mul_f32_e32 v118, v118, v4
	v_and_b32_e32 v4, 0xffff0000, v191
	v_mul_f32_e32 v119, v119, v4
	v_cvt_pk_bf16_f32 v106, v116, v117
	v_cvt_pk_bf16_f32 v107, v118, v119
	v_lshlrev_b32_e32 v4, 16, v192
	v_mul_f32_e32 v120, v120, v4
	v_and_b32_e32 v4, 0xffff0000, v192
	v_mul_f32_e32 v121, v121, v4
	v_lshlrev_b32_e32 v4, 16, v193
	v_mul_f32_e32 v122, v122, v4
	v_and_b32_e32 v4, 0xffff0000, v193
	v_mul_f32_e32 v123, v123, v4
	v_cvt_pk_bf16_f32 v108, v120, v121
	v_cvt_pk_bf16_f32 v109, v122, v123
	v_lshlrev_b32_e32 v4, 16, v194
	v_mul_f32_e32 v124, v124, v4
	v_and_b32_e32 v4, 0xffff0000, v194
	v_mul_f32_e32 v125, v125, v4
	v_lshlrev_b32_e32 v4, 16, v195
	v_mul_f32_e32 v126, v126, v4
	v_and_b32_e32 v4, 0xffff0000, v195
	v_mul_f32_e32 v127, v127, v4
	v_cvt_pk_bf16_f32 v110, v124, v125
	v_cvt_pk_bf16_f32 v111, v126, v127
	s_nop 1
	v_permlane32_swap_b32 v104, v106
	v_permlane32_swap_b32 v105, v107
	v_permlane32_swap_b32 v108, v110
	v_permlane32_swap_b32 v109, v111
	global_store_dwordx4 v139, v[104:107], s[54:55] offset:64
	global_store_dwordx4 v139, v[108:111], s[54:55] offset:96
	v_mfma_f32_32x32x16_bf16 v[112:127], v[208:211], v[56:59], 0
	v_mfma_f32_32x32x16_bf16 v[112:127], v[212:215], v[60:63], v[112:127]
	v_mfma_f32_32x32x16_bf16 v[112:127], v[216:219], v[64:67], v[112:127]
	v_mfma_f32_32x32x16_bf16 v[112:127], v[220:223], v[68:71], v[112:127]
	v_mfma_f32_32x32x16_bf16 v[112:127], v[224:227], v[72:75], v[112:127]
	v_mfma_f32_32x32x16_bf16 v[112:127], v[228:231], v[76:79], v[112:127]
	v_mfma_f32_32x32x16_bf16 v[112:127], v[232:235], v[80:83], v[112:127]
	v_mfma_f32_32x32x16_bf16 v[112:127], v[236:239], v[84:87], v[112:127]
	s_nop 7
	s_nop 7
	v_permlane32_swap_b32 v204, v206
	v_permlane32_swap_b32 v205, v207
	v_permlane32_swap_b32 v240, v242
	v_permlane32_swap_b32 v241, v243
	v_add_f32_e32 v112, v112, v91
	v_add_f32_e32 v113, v113, v91
	v_add_f32_e32 v114, v114, v91
	v_add_f32_e32 v115, v115, v91
	v_add_f32_e32 v116, v116, v91
	v_add_f32_e32 v117, v117, v91
	v_add_f32_e32 v118, v118, v91
	v_add_f32_e32 v119, v119, v91
	v_add_f32_e32 v120, v120, v91
	v_add_f32_e32 v121, v121, v91
	v_add_f32_e32 v122, v122, v91
	v_add_f32_e32 v123, v123, v91
	v_add_f32_e32 v124, v124, v91
	v_add_f32_e32 v125, v125, v91
	v_add_f32_e32 v126, v126, v91
	v_add_f32_e32 v127, v127, v91
	v_lshlrev_b32_e32 v4, 16, v204
	v_mul_f32_e32 v112, v112, v4
	v_and_b32_e32 v4, 0xffff0000, v204
	v_mul_f32_e32 v113, v113, v4
	v_lshlrev_b32_e32 v4, 16, v205
	v_mul_f32_e32 v114, v114, v4
	v_and_b32_e32 v4, 0xffff0000, v205
	v_mul_f32_e32 v115, v115, v4
	v_cvt_pk_bf16_f32 v104, v112, v113
	v_cvt_pk_bf16_f32 v105, v114, v115
	v_lshlrev_b32_e32 v4, 16, v206
	v_mul_f32_e32 v116, v116, v4
	v_and_b32_e32 v4, 0xffff0000, v206
	v_mul_f32_e32 v117, v117, v4
	v_lshlrev_b32_e32 v4, 16, v207
	v_mul_f32_e32 v118, v118, v4
	v_and_b32_e32 v4, 0xffff0000, v207
	v_mul_f32_e32 v119, v119, v4
	v_cvt_pk_bf16_f32 v106, v116, v117
	v_cvt_pk_bf16_f32 v107, v118, v119
	v_lshlrev_b32_e32 v4, 16, v240
	v_mul_f32_e32 v120, v120, v4
	v_and_b32_e32 v4, 0xffff0000, v240
	v_mul_f32_e32 v121, v121, v4
	v_lshlrev_b32_e32 v4, 16, v241
	v_mul_f32_e32 v122, v122, v4
	v_and_b32_e32 v4, 0xffff0000, v241
	v_mul_f32_e32 v123, v123, v4
	v_cvt_pk_bf16_f32 v108, v120, v121
	v_cvt_pk_bf16_f32 v109, v122, v123
	v_lshlrev_b32_e32 v4, 16, v242
	v_mul_f32_e32 v124, v124, v4
	v_and_b32_e32 v4, 0xffff0000, v242
	v_mul_f32_e32 v125, v125, v4
	v_lshlrev_b32_e32 v4, 16, v243
	v_mul_f32_e32 v126, v126, v4
	v_and_b32_e32 v4, 0xffff0000, v243
	v_mul_f32_e32 v127, v127, v4
	v_cvt_pk_bf16_f32 v110, v124, v125
	v_cvt_pk_bf16_f32 v111, v126, v127
	s_nop 1
	v_permlane32_swap_b32 v104, v106
	v_permlane32_swap_b32 v105, v107
	v_permlane32_swap_b32 v108, v110
	v_permlane32_swap_b32 v109, v111
	global_store_dwordx4 v139, v[104:107], s[56:57] offset:64
	global_store_dwordx4 v139, v[108:111], s[56:57] offset:96
	s_add_i32 s1, s1, s66
	s_cmp_lt_i32 s1, 0x100
	s_cbranch_scc0 .Lgm_done
	s_barrier
	s_branch .Lgm_loop
